# M2 two-deep operand prefetch (unroll 2, role-specific tail waits), prep x-conversion loop software-pipelined (8 loads in flight), gdn l2norm butterflies batched
# speedup vs baseline: 1.0112x; 1.0093x over previous
.LBB0_1:
	s_mov_b64 s[60:61], s[0:1]
	s_mul_hi_i32 s0, s2, 0x13e22cbd
	s_lshr_b32 s1, s0, 31
	s_ashr_i32 s0, s0, 9
	s_add_i32 s0, s0, s1
	s_mul_i32 s1, s0, 0x19c0
	s_sub_i32 s30, s2, s1
	v_writelane_b32 v250, s4, 0
	s_add_i32 s9, s30, 0xffffee80
	s_cmpk_gt_i32 s30, 0x117f
	v_writelane_b32 v250, s5, 1
	v_writelane_b32 v250, s6, 2
	v_writelane_b32 v250, s7, 3
	s_cselect_b32 s6, s9, s30
	s_sext_i32_i16 s1, s6
	s_lshr_b32 s7, s1, 15
	s_bfe_u32 s1, s7, 0x4000c
	s_add_i32 s8, s6, s1
	s_lshl_b32 s1, s8, 2
	s_and_b32 s3, s1, 0xffc0
	s_sext_i32_i16 s1, s1
	s_bfe_u32 s1, s1, 0x80017
	s_add_i32 s1, s3, s1
	s_and_b32 s1, s1, 0xff00
	s_load_dwordx4 s[72:75], s[60:61], 0x100
	s_load_dwordx4 s[16:19], s[60:61], 0x110
	s_sub_i32 s5, s3, s1
	s_sext_i32_i16 s1, s5
	s_cmpk_lt_i32 s1, 0x80
	s_cselect_b32 s1, 27, 28
	s_cselect_b32 s3, 8, 9
	s_cmpk_gt_i32 s30, 0x117f
	s_cselect_b32 s14, s1, s3
	s_waitcnt lgkmcnt(0)
	s_add_u32 s66, s74, 0xcf21000
	s_addc_u32 s67, s75, 0
	s_add_u32 s64, s74, 0x11021000
	s_addc_u32 s65, s75, 0
	s_add_u32 s70, s74, 0x130a1000
	s_addc_u32 s71, s75, 0
	s_add_u32 s27, s74, 0x23cc1000
	s_addc_u32 s26, s75, 0
	s_add_u32 s10, s74, 0x2df41000
	s_addc_u32 s11, s75, 0
	v_writelane_b32 v250, s10, 4
	s_cmp_lt_i32 s17, 0
	s_load_dwordx4 s[16:19], s[60:61], 0x110
	v_writelane_b32 v250, s11, 5
	s_cselect_b64 s[10:11], -1, 0
	s_add_u32 s84, s60, 0x120
	v_writelane_b32 v250, s10, 6
	s_addc_u32 s85, s61, 0
	s_load_dwordx16 s[36:51], s[60:61], 0x98
	v_writelane_b32 v250, s11, 7
	s_add_u32 s10, s74, 0x38f43000
	s_addc_u32 s11, s75, 0
	s_cmpk_lt_i32 s2, 0x100
	s_cselect_b64 s[20:21], -1, 0
	s_add_u32 s28, s74, 0x38f43200
	v_writelane_b32 v250, s10, 8
	s_addc_u32 s29, s75, 0
	s_add_u32 s1, s74, 0x38f43400
	v_writelane_b32 v250, s11, 9
	v_writelane_b32 v250, s1, 10
	s_addc_u32 s1, s75, 0
	v_writelane_b32 v250, s1, 11
	s_add_u32 s1, s74, 0x38f43100
	v_writelane_b32 v250, s1, 12
	s_addc_u32 s1, s75, 0
	v_writelane_b32 v250, s1, 13
	s_ashr_i32 s1, s2, 31
	s_mov_b32 s68, s1
	s_lshr_b32 s1, s1, 29
	s_add_i32 s1, s2, s1
	s_ashr_i32 s3, s1, 3
	s_and_b32 s1, s1, -8
	s_sub_i32 s4, s2, s1
	s_lshl_b32 s15, s4, 5
	s_cmpk_lt_i32 s2, 0x80
	s_cselect_b64 s[10:11], -1, 0
	v_writelane_b32 v250, s10, 14
	s_cmpk_lt_i32 s2, 0x500
	s_mov_b32 s57, 0
	v_writelane_b32 v250, s11, 15
	s_cselect_b64 s[10:11], -1, 0
	v_writelane_b32 v250, s10, 16
	s_mov_b32 s56, s2
	v_and_b32_e32 v197, 0x3ff, v0
	v_writelane_b32 v250, s11, 17
	s_add_u32 s10, s72, 0x5a20000
	s_addc_u32 s11, s73, 0
	s_add_u32 s78, s74, 0x2dd41000
	s_addc_u32 s79, s75, 0
	s_add_u32 s80, s74, 0x2de41000
	v_writelane_b32 v250, s10, 18
	s_addc_u32 s81, s75, 0
	s_add_u32 s1, s74, 0x29d41000
	v_writelane_b32 v250, s11, 19
	v_writelane_b32 v250, s1, 20
	s_addc_u32 s1, s75, 0
	s_add_u32 s82, s74, 0x33f41000
	s_addc_u32 s83, s75, 0
	v_writelane_b32 v250, s1, 21
	s_add_u32 s1, s74, 0x38f41000
	v_writelane_b32 v250, s1, 22
	s_addc_u32 s1, s75, 0
	s_add_u32 s10, s74, 0x37f41000
	v_writelane_b32 v250, s1, 23
	s_addc_u32 s11, s75, 0
	v_writelane_b32 v250, s10, 24
	v_and_b32_e32 v0, 0x3fffffff, v0
	v_mov_b32_e32 v145, 0
	v_writelane_b32 v250, s11, 25
	s_add_u32 s10, s74, 0x2ff41000
	s_addc_u32 s11, s75, 0
	v_writelane_b32 v250, s10, 26
	s_add_u32 s1, s72, 0x4100000
	v_mov_b32_e32 v198, 0x3727c5ac
	v_writelane_b32 v250, s11, 27
	v_writelane_b32 v250, s1, 28
	s_addc_u32 s1, s73, 0
	v_writelane_b32 v250, s1, 29
	s_waitcnt lgkmcnt(0)
	s_bfe_u32 s1, s18, 0x1000d
	s_load_dwordx4 s[16:19], s[60:61], 0x110
	s_add_u32 s22, s74, 0xce21000
	v_writelane_b32 v250, s1, 30
	s_addc_u32 s23, s75, 0
	v_mov_b32_e32 v199, 0x4000
	s_waitcnt lgkmcnt(0)
	s_bfe_u32 s1, s18, 0x1000e
	v_writelane_b32 v250, s1, 31
	s_add_u32 s1, s74, 0xce00000
	v_writelane_b32 v250, s1, 32
	s_addc_u32 s1, s75, 0
	v_writelane_b32 v250, s1, 33
	s_cmpk_lt_i32 s2, 0x861
	s_mul_i32 s1, s4, 0x10c
	s_cselect_b64 s[10:11], -1, 0
	s_or_b32 s16, s1, 1
	v_writelane_b32 v250, s10, 34
	s_cmpk_lt_i32 s2, 0x596
	s_mul_i32 s1, s4, 0xb2
	v_writelane_b32 v250, s11, 35
	s_cselect_b64 s[10:11], -1, 0
	s_add_i32 s17, s1, 6
	v_writelane_b32 v250, s10, 36
	s_cmpk_lt_i32 s2, 0x6700
	v_mov_b32_e32 v146, 0.5
	v_writelane_b32 v250, s11, 37
	s_cselect_b64 s[10:11], -1, 0
	s_ashr_i32 s1, s0, 31
	v_writelane_b32 v250, s10, 38
	s_cmpk_gt_i32 s30, 0x57f
	v_mov_b32_e32 v200, 0x358637bd
	v_writelane_b32 v250, s11, 39
	s_cselect_b64 s[10:11], -1, 0
	s_cmpk_gt_u32 s9, 0x57f
	s_cselect_b64 s[12:13], -1, 0
	s_and_b64 s[10:11], s[10:11], s[12:13]
	s_add_i32 s9, s30, 0xffffe900
	v_writelane_b32 v250, s10, 40
	s_cmp_gt_u32 s9, 0xfffff13f
	s_mul_i32 s13, s0, 0x2010000
	v_writelane_b32 v250, s11, 41
	s_cselect_b64 s[10:11], -1, 0
	v_writelane_b32 v250, s10, 42
	s_cmpk_lt_u32 s30, 0x1080
	s_mul_hi_i32 s12, s0, 0x2010000
	v_writelane_b32 v250, s11, 43
	s_cselect_b64 s[10:11], -1, 0
	v_writelane_b32 v250, s10, 44
	v_mov_b32_e32 v201, 1
	v_mov_b64_e32 v[148:149], 0x100
	v_writelane_b32 v250, s11, 45
	s_lshl_b64 s[10:11], s[0:1], 22
	s_add_u32 s10, s46, s10
	v_writelane_b32 v250, s36, 46
	s_addc_u32 s11, s47, s11
	s_lshl_b32 s1, s30, 2
	v_writelane_b32 v250, s37, 47
	v_writelane_b32 v250, s38, 48
	v_writelane_b32 v250, s39, 49
	v_writelane_b32 v250, s40, 50
	v_writelane_b32 v250, s41, 51
	v_writelane_b32 v250, s42, 52
	v_writelane_b32 v250, s43, 53
	v_writelane_b32 v250, s44, 54
	v_writelane_b32 v250, s45, 55
	v_writelane_b32 v250, s46, 56
	v_writelane_b32 v250, s47, 57
	s_and_b32 s9, s1, 0x7fc0
	v_writelane_b32 v250, s48, 58
	s_addk_i32 s9, 0xbe00
	v_writelane_b32 v250, s49, 59
	v_writelane_b32 v251, s9, 0
	s_lshl_b32 s9, s30, 6
	v_writelane_b32 v250, s50, 60
	s_and_b32 s9, s9, 0x3c0
	s_add_i32 s1, s1, 0x3df00
	v_writelane_b32 v250, s51, 61
	v_writelane_b32 v251, s9, 1
	s_and_b32 s1, s1, 0x3ffc0
	s_and_b32 s9, s30, 0x1ff0
	s_load_dwordx16 s[36:51], s[60:61], 0x58
	v_writelane_b32 v250, s10, 62
	s_cmpk_eq_i32 s9, 0x1040
	s_cselect_b32 s9, 0x1800, 0
	v_writelane_b32 v250, s11, 63
	s_cselect_b32 s10, 16, 0
	s_add_i32 s11, s1, 0xfffff800
	s_cmpk_lt_u32 s1, 0x2010
	s_cselect_b32 s11, s11, -1
	s_or_b32 s18, s1, 16
	s_waitcnt lgkmcnt(0)
	s_add_u32 s24, s36, s13
	v_writelane_b32 v251, s36, 2
	s_addc_u32 s25, s37, s12
	s_cmpk_gt_u32 s30, 0x16ff
	v_writelane_b32 v251, s37, 3
	v_writelane_b32 v251, s38, 4
	v_writelane_b32 v251, s39, 5
	v_writelane_b32 v251, s40, 6
	v_writelane_b32 v251, s41, 7
	v_writelane_b32 v251, s42, 8
	v_writelane_b32 v251, s43, 9
	v_writelane_b32 v251, s44, 10
	v_writelane_b32 v251, s45, 11
	v_writelane_b32 v251, s46, 12
	v_writelane_b32 v251, s47, 13
	v_writelane_b32 v251, s48, 14
	v_writelane_b32 v251, s49, 15
	v_writelane_b32 v251, s50, 16
	v_writelane_b32 v251, s51, 17
	s_mov_b32 s12, 0xe900
	v_writelane_b32 v251, s24, 18
	s_cselect_b32 s12, s12, 0xfa80
	s_movk_i32 s13, 0xe8
	v_writelane_b32 v251, s25, 19
	s_cselect_b32 s13, s13, 0x50
	s_add_i32 s12, s12, s30
	v_writelane_b32 v251, s13, 20
	s_and_b32 s13, s12, 0xffff
	s_mul_i32 s13, s13, 0xba2f
	s_lshr_b32 s13, s13, 21
	s_mul_i32 s19, s13, 44
	s_and_b32 s8, s8, 0xfff0
	s_bfe_u32 s7, s7, 0x6000a
	s_sub_i32 s12, s12, s19
	s_sub_i32 s8, s6, s8
	s_add_i32 s6, s6, s7
	s_lshl_b32 s7, s13, 6
	v_writelane_b32 v251, s7, 21
	s_lshl_b32 s7, s12, 6
	s_and_b32 s7, s7, 0xffc0
	v_writelane_b32 v251, s7, 22
	s_lshl_b32 s7, s14, 3
	s_sext_i32_i16 s6, s6
	s_add_u32 s12, s60, s7
	s_addc_u32 s13, s61, 0
	s_lshl_b32 s6, s6, 1
	v_writelane_b32 v251, s12, 23
	s_and_b32 s6, s6, 0xffffff80
	s_and_b32 s5, s5, 64
	v_writelane_b32 v251, s13, 24
	s_or_b32 s5, s6, s5
	v_writelane_b32 v251, s5, 25
	s_sext_i32_i16 s5, s8
	s_lshl_b32 s5, s5, 6
	v_writelane_b32 v251, s5, 26
	s_lshl_b64 s[6:7], s[56:57], 9
	v_writelane_b32 v251, s6, 27
	s_cmp_eq_u64 s[72:73], 0
	s_mul_i32 s5, s4, 33
	v_writelane_b32 v251, s7, 28
	s_cselect_b64 s[6:7], -1, 0
	s_cmp_lt_i32 s4, 0
	s_cselect_b32 s5, s5, s15
	v_writelane_b32 v251, s6, 29
	s_add_i32 s5, s5, s3
	s_mov_b32 s46, s2
	v_writelane_b32 v251, s7, 30
	s_ashr_i32 s6, s5, 31
	s_lshr_b32 s6, s6, 27
	s_add_i32 s6, s5, s6
	s_and_b32 s7, s6, 0xffe0
	s_sub_i32 s5, s5, s7
	s_bfe_i32 s7, s5, 0x80000
	s_bfe_u32 s7, s7, 0x3000c
	s_add_i32 s7, s5, s7
	s_and_b32 s8, s7, 0xf8
	s_sub_i32 s5, s5, s8
	s_ashr_i32 s6, s6, 5
	s_bfe_i32 s7, s7, 0x80000
	s_lshl_b32 s6, s6, 3
	s_sext_i32_i16 s7, s7
	s_sext_i32_i8 s5, s5
	s_add_i32 s14, s6, s5
	s_lshr_b32 s6, s7, 3
	s_ashr_i32 s5, s7, 3
	s_bfe_i64 s[6:7], s[6:7], 0x100000
	v_writelane_b32 v251, s5, 31
	s_lshl_b64 s[6:7], s[6:7], 19
	s_ashr_i32 s15, s14, 31
	v_writelane_b32 v251, s6, 32
	s_mul_i32 s5, s4, 0x10d
	s_mul_hi_i32 s8, s14, 0x160000
	v_writelane_b32 v251, s7, 33
	s_lshl_b64 s[6:7], s[14:15], 19
	s_add_u32 s6, s27, s6
	v_writelane_b32 v251, s27, 34
	s_addc_u32 s7, s26, s7
	v_writelane_b32 v251, s26, 35
	s_add_u32 s12, s6, 0x40000
	v_writelane_b32 v251, s6, 36
	s_addc_u32 s13, s7, 0
	s_cmp_lt_i32 s4, 1
	s_cselect_b32 s5, s5, s16
	s_add_i32 s5, s5, s3
	v_writelane_b32 v251, s7, 37
	s_mul_hi_i32 s6, s5, 0x3e0f83e1
	s_lshr_b32 s7, s6, 31
	s_ashr_i32 s6, s6, 6
	v_writelane_b32 v251, s12, 38
	s_add_i32 s6, s6, s7
	s_mul_i32 s7, s6, 0x108
	v_writelane_b32 v251, s13, 39
	s_lshl_b32 s6, s6, 3
	s_mov_b32 s12, s14
	s_sub_i32 s5, s5, s7
	s_sub_i32 s7, 0x41, s6
	v_writelane_b32 v251, s12, 40
	s_min_u32 s7, s7, 8
	v_cvt_f32_ubyte0_e32 v2, s7
	v_writelane_b32 v251, s13, 41
	s_mul_i32 s12, s14, 0x160000
	s_add_u32 s14, s70, s12
	s_addc_u32 s15, s71, s8
	s_add_u32 s12, s14, 0xb0000
	v_writelane_b32 v251, s14, 42
	s_addc_u32 s13, s15, 0
	s_cmp_lt_i32 s4, 6
	s_mulk_i32 s4, 0xb3
	s_cselect_b32 s4, s4, s17
	s_add_i32 s4, s4, s3
	s_mul_hi_i32 s3, s4, 0x2e8ba2e9
	v_writelane_b32 v251, s15, 43
	s_lshr_b32 s8, s3, 31
	s_ashr_i32 s3, s3, 5
	v_writelane_b32 v251, s12, 44
	s_add_i32 s3, s3, s8
	v_cvt_f32_i32_e32 v1, s5
	v_writelane_b32 v251, s13, 45
	s_lshl_b32 s12, s3, 3
	v_rcp_iflag_f32_e32 v3, v2
	s_mul_i32 s8, s3, 0xb0
	s_sub_i32 s3, 0x41, s12
	s_sub_i32 s8, s4, s8
	s_min_u32 s13, s3, 8
	s_cmpk_lt_u32 s1, 0x2000
	s_cselect_b32 s3, s18, s11
	s_cmpk_lt_u32 s1, 0x1800
	v_mul_f32_e32 v3, v1, v3
	s_cselect_b32 s1, s1, s3
	s_cmpk_lt_u32 s30, 0x1040
	v_trunc_f32_e32 v3, v3
	s_cselect_b32 s1, s1, s9
	v_fma_f32 v1, -v3, v2, v1
	v_writelane_b32 v251, s1, 46
	s_cselect_b32 s1, 64, s10
	v_cmp_ge_f32_e64 s[2:3], |v1|, v2
	v_cvt_i32_f32_e32 v1, v3
	v_writelane_b32 v251, s1, 47
	s_ashr_i32 s1, s5, 30
	s_or_b32 s1, s1, 1
	s_and_b64 s[2:3], s[2:3], exec
	s_cselect_b32 s1, s1, 0
	v_readfirstlane_b32 s2, v1
	s_add_i32 s2, s2, s1
	s_mul_i32 s1, s2, s7
	s_sub_i32 s1, s5, s1
	s_bfe_i64 s[4:5], s[2:3], 0x100000
	s_sext_i32_i16 s1, s1
	s_lshl_b64 s[4:5], s[4:5], 19
	v_cvt_f32_ubyte0_e32 v2, s13
	s_add_i32 s6, s6, s1
	v_writelane_b32 v251, s4, 48
	v_cvt_f32_i32_e32 v1, s8
	v_rcp_iflag_f32_e32 v3, v2
	v_writelane_b32 v251, s5, 49
	s_mov_b32 s4, s6
	s_ashr_i32 s7, s6, 31
	v_writelane_b32 v251, s4, 50
	v_mul_f32_e32 v3, v1, v3
	v_trunc_f32_e32 v3, v3
	v_writelane_b32 v251, s5, 51
	s_lshl_b64 s[4:5], s[6:7], 19
	s_add_u32 s4, s64, s4
	s_addc_u32 s5, s65, s5
	s_add_u32 s6, s4, 0x40000
	v_writelane_b32 v251, s4, 52
	v_fma_f32 v1, -v3, v2, v1
	s_addc_u32 s7, s5, 0
	v_writelane_b32 v251, s5, 53
	v_cmp_ge_f32_e64 s[4:5], |v1|, v2
	v_cvt_i32_f32_e32 v1, v3
	s_ashr_i32 s1, s8, 30
	s_or_b32 s1, s1, 1
	s_and_b64 s[4:5], s[4:5], exec
	s_cselect_b32 s1, s1, 0
	v_readfirstlane_b32 s3, v1
	s_add_i32 s4, s3, s1
	v_writelane_b32 v251, s6, 54
	s_mul_i32 s1, s4, s13
	s_sub_i32 s1, s8, s1
	v_writelane_b32 v251, s7, 55
	s_bfe_i64 s[6:7], s[4:5], 0x100000
	s_sext_i32_i16 s1, s1
	s_lshl_b64 s[6:7], s[6:7], 19
	s_add_i32 s12, s12, s1
	v_writelane_b32 v251, s6, 56
	s_mul_hi_i32 s1, s0, 0xb00000
	s_ashr_i32 s13, s12, 31
	v_writelane_b32 v251, s7, 57
	s_mov_b32 s6, s12
	v_writelane_b32 v251, s6, 58
	s_mul_i32 s0, s0, 0xb00000
	s_load_dwordx4 s[8:11], s[60:61], 0x110
	v_writelane_b32 v251, s7, 59
	v_writelane_b32 v251, s20, 60
	s_lshl_b64 s[6:7], s[12:13], 19
	s_add_u32 s6, s64, s6
	v_writelane_b32 v251, s21, 61
	v_writelane_b32 v251, s1, 62
	v_writelane_b32 v251, s0, 63
	s_sext_i32_i16 s0, s2
	v_writelane_b32 v252, s0, 0
	s_sext_i32_i16 s0, s4
	s_addc_u32 s7, s65, s7
	v_writelane_b32 v252, s0, 1
	s_add_u32 s0, s6, 0x40000
	v_writelane_b32 v252, s6, 2
	s_addc_u32 s1, s7, 0
	s_load_dwordx8 s[12:19], s[60:61], 0x0
	v_writelane_b32 v252, s7, 3
	v_writelane_b32 v252, s0, 4
	s_mov_b64 s[44:45], s[28:29]
	v_mbcnt_lo_u32_b32 v1, -1, 0
	v_writelane_b32 v252, s1, 5
	s_lshl_b32 s0, s46, 1
	v_writelane_b32 v252, s0, 6
	s_add_i32 s0, s46, 0x4000
	v_writelane_b32 v252, s0, 7
	s_lshl_b32 s0, s46, 6
	v_writelane_b32 v252, s0, 8
	s_lshl_b32 s0, s46, 2
	v_writelane_b32 v252, s0, 9
	s_lshl_b64 s[0:1], s[56:57], 11
	s_add_u32 s0, s74, s0
	s_addc_u32 s1, s75, s1
	s_add_u32 s0, s0, 0xce00000
	s_addc_u32 s1, s1, 0
	v_writelane_b32 v252, s0, 10
	s_lshl_b64 s[2:3], s[56:57], 13
	s_waitcnt lgkmcnt(0)
	s_mov_b64 s[4:5], s[16:17]
	v_writelane_b32 v252, s1, 11
	s_lshl_b32 s0, s46, 14
	v_writelane_b32 v252, s0, 12
	s_add_u32 s0, s12, s2
	s_addc_u32 s1, s13, s3
	v_writelane_b32 v252, s0, 13
	s_mov_b64 s[6:7], s[18:19]
	v_cndmask_b32_e64 v196, 0, 1, s[20:21]
	v_writelane_b32 v252, s1, 14
	s_add_u32 s0, s14, s2
	v_writelane_b32 v252, s0, 15
	v_mov_b64_e32 v[150:151], 0xff
	v_mbcnt_hi_u32_b32 v202, -1, v1
	v_writelane_b32 v252, s1, 16
	v_writelane_b32 v252, s2, 17
	v_writelane_b32 v252, s3, 18
	v_writelane_b32 v252, s4, 19
	v_writelane_b32 v252, s5, 20
	v_writelane_b32 v252, s6, 21
	v_writelane_b32 v252, s7, 22
	s_addc_u32 s1, s15, s3
	s_add_u32 s0, s0, 0xfc000000
	s_addc_u32 s1, s1, -1
	v_writelane_b32 v252, s0, 23
	v_mov_b32_e32 v203, 0x29d41020
	v_mov_b32_e32 v204, 0x3c0
	v_writelane_b32 v252, s1, 24
	s_add_u32 s0, s74, s2
	v_writelane_b32 v252, s2, 25
	s_addc_u32 s1, s75, s3
	s_add_u32 s0, s0, 0xcf21000
	v_writelane_b32 v252, s3, 26
	s_addc_u32 s1, s1, 0
	v_writelane_b32 v252, s0, 27
	v_mov_b32_e32 v205, 0x41b17218
	v_mov_b32_e32 v206, 0x4200
	v_writelane_b32 v252, s1, 28
	s_lshl_b64 s[0:1], s[56:57], 12
	s_add_u32 s0, s74, s0
	s_addc_u32 s1, s75, s1
	s_add_u32 s0, s0, 0x23cc1000
	s_addc_u32 s1, s1, 0
	v_writelane_b32 v252, s0, 29
	v_mov_b32_e32 v207, 0x2df41020
	v_mov_b32_e32 v208, 0x2ff41020
	v_writelane_b32 v252, s1, 30
	v_cmp_eq_u32_e64 s[0:1], 0, v0
	v_mov_b32_e32 v209, 0x3db504f3
	v_mov_b64_e32 v[154:155], 0x861
	v_writelane_b32 v252, s0, 31
	v_mov_b64_e32 v[156:157], 0x595
	v_mov_b64_e32 v[158:159], 0x596
	v_writelane_b32 v252, s1, 32
	v_cmp_eq_u32_e64 s[0:1], 0, v197
	v_mov_b32_e32 v210, 0x88
	v_mov_b32_e32 v211, 0x78
	v_writelane_b32 v252, s0, 33
	v_mov_b32_e32 v240, v145
	v_mov_b32_e32 v241, v145
	v_writelane_b32 v252, s1, 34
	s_load_dwordx4 s[0:3], s[60:61], 0x20
	s_movk_i32 s33, 0x2000
	s_mov_b32 s86, 0x800000
	s_movk_i32 s87, 0x3000
	s_mov_b32 s88, 0xbfb8aa3b
	s_waitcnt lgkmcnt(0)
	v_writelane_b32 v252, s0, 35
	s_mov_b32 s89, 0x3c23d70a
	s_mov_b32 s90, 0x3f317217
	v_writelane_b32 v252, s1, 36
	v_writelane_b32 v252, s2, 37
	v_writelane_b32 v252, s3, 38
	v_writelane_b32 v252, s84, 39
	s_mov_b32 s91, 0x7f800000
	s_mov_b32 s92, 0xbeaaaaab
	v_writelane_b32 v252, s85, 40
	v_writelane_b32 v252, s22, 41
	s_mov_b32 s93, 0xbca3d70a
	s_mov_b32 s94, 0x3e2aaaab
	v_writelane_b32 v252, s23, 42
	v_writelane_b32 v252, s46, 43
	v_writelane_b32 v252, s60, 44
	s_mov_b32 s95, 0x25d41000
	s_mov_b32 s96, 0x27d41000
	v_writelane_b32 v252, s61, 45
	v_writelane_b32 v252, s66, 46
	s_mov_b32 s97, 0x130a4000
	s_mov_b32 s12, s8
	v_writelane_b32 v252, s67, 47
	v_writelane_b32 v252, s64, 48
	s_mov_b64 s[76:77], 0x800
	s_nop 0
	v_writelane_b32 v252, s65, 49
	v_writelane_b32 v252, s70, 50
	s_nop 1
	v_writelane_b32 v252, s71, 51
	v_writelane_b32 v252, s44, 52
	s_nop 1
	v_writelane_b32 v252, s45, 53
	v_writelane_b32 v252, s68, 54
	v_writelane_b32 v252, s78, 55
	s_nop 1
	v_writelane_b32 v252, s79, 56
	v_writelane_b32 v252, s80, 57
	s_nop 1
	v_writelane_b32 v252, s81, 58
	v_writelane_b32 v252, s82, 59
	s_nop 1
	v_writelane_b32 v252, s83, 60
	s_branch .LBB0_3
.Lend_near:
	s_endpgm
.LBB0_2:
	v_readlane_b32 s12, v253, 29
	v_readlane_b32 s8, v250, 0
	s_add_i32 s12, s12, 1
	v_readlane_b32 s9, v250, 1
	v_readlane_b32 s10, v250, 2
	s_cmp_ge_i32 s12, s9
	v_readlane_b32 s11, v250, 3
	s_cbranch_scc1 .Lend_near

.LBB0_171:
	s_waitcnt vmcnt(0)
	s_lshl_b64 s[6:7], s[6:7], 3
	v_readlane_b32 s8, v253, 23
	v_readlane_b32 s9, v253, 24
	s_add_u32 s6, s6, s8
	s_addc_u32 s7, s7, s9
	s_or_b32 s6, s6, s17
	s_lshl_b64 s[6:7], s[6:7], 16
	v_readlane_b32 s8, v250, 28
	s_add_u32 s6, s8, s6
	v_readlane_b32 s8, v250, 29
	v_or_b32_e32 v0, v144, v88
	s_addc_u32 s7, s8, s7
	v_ashrrev_i32_e32 v1, 31, v0
	v_lshl_add_u64 v[0:1], v[0:1], 2, s[6:7]
	global_store_dword v[0:1], v24, off
	v_lshl_add_u64 v[0:1], v[144:145], 0, v[88:89]
	v_lshl_add_u64 v[0:1], v[0:1], 2, s[6:7]
	global_store_dword v[0:1], v25, off offset:512
	global_store_dword v[0:1], v26, off offset:1024
	global_store_dword v[0:1], v27, off offset:1536
	global_store_dword v[0:1], v36, off offset:64
	v_lshl_add_u64 v[0:1], v[144:145], 0, v[90:91]
	v_lshl_add_u64 v[0:1], v[0:1], 2, s[6:7]
	global_store_dword v[0:1], v37, off offset:64
	v_lshl_add_u64 v[0:1], v[144:145], 0, v[92:93]
	v_lshl_add_u64 v[0:1], v[0:1], 2, s[6:7]
	global_store_dword v[0:1], v38, off offset:64
	v_lshl_add_u64 v[0:1], v[144:145], 0, v[94:95]
	v_lshl_add_u64 v[0:1], v[0:1], 2, s[6:7]
	global_store_dword v[0:1], v39, off offset:64
	s_load_dword s6, s[84:85], 0x0
	s_waitcnt lgkmcnt(0)
	s_add_i32 s16, s6, s16
	s_cmpk_gt_i32 s16, 0xff
	s_cbranch_scc1 .LBB0_183

.LBB0_175:
	s_or_b64 exec, exec, s[6:7]
	s_lshl_b32 s6, s16, 3
	s_and_b32 s6, s6, 56
	s_ashr_i32 s7, s16, 5
	s_add_i32 s10, s6, s7
	s_ashr_i32 s11, s10, 31
	s_lshl_b64 s[8:9], s[10:11], 19
	s_ashr_i32 s6, s10, 3
	s_and_b32 s17, s7, 7
	s_lshl_b64 s[12:13], s[10:11], 18
	v_lshl_add_u64 v[12:13], v[82:83], 0, s[8:9]
	v_lshl_add_u64 v[20:21], v[84:85], 0, s[8:9]
	s_lshl_b64 s[8:9], s[10:11], 5
	s_lshl_b64 s[10:11], s[10:11], 7
	v_readlane_b32 s7, v250, 22
	s_add_u32 s10, s7, s10
	v_readlane_b32 s7, v250, 23
	s_addc_u32 s11, s7, s11
	s_lshl_b32 s7, s16, 2
	s_and_b32 s14, s7, 0x60
	v_or_b32_e32 v144, s14, v80
	v_lshl_add_u64 v[24:25], v[86:87], 0, s[12:13]
	v_or_b32_e32 v102, v144, v97
	s_waitcnt lgkmcnt(0)
	s_barrier
	global_load_dwordx4 v[0:3], v[12:13], off
	global_load_dwordx4 v[4:7], v[12:13], off offset:64
	global_load_dwordx4 v[8:11], v[12:13], off offset:128
	s_nop 0
	global_load_dwordx4 v[12:15], v[12:13], off offset:192
	s_nop 0
	global_load_dwordx4 v[16:19], v[20:21], off
	global_load_dwordx4 v[28:31], v[24:25], off
	s_nop 0
	global_load_dwordx4 v[20:23], v[20:21], off offset:64
	s_nop 0
	global_load_dwordx4 v[32:35], v[24:25], off offset:64
	v_or_b32_e32 v24, s12, v102
	v_mov_b32_e32 v25, s13
	v_or_b32_e32 v104, v144, v103
	v_lshl_add_u64 v[26:27], v[24:25], 2, s[82:83]
	v_or_b32_e32 v24, s12, v104
	v_or_b32_e32 v106, v144, v105
	global_load_dword v56, v[26:27], off
	v_lshl_add_u64 v[26:27], v[24:25], 2, s[82:83]
	v_or_b32_e32 v24, s12, v106
	v_or_b32_e32 v108, v144, v107
	v_or_b32_e32 v36, 16, v144
	global_load_dword v57, v[26:27], off
	v_lshl_add_u64 v[26:27], v[24:25], 2, s[82:83]
	v_or_b32_e32 v24, s12, v108
	v_or_b32_e32 v110, v36, v97
	global_load_dword v58, v[26:27], off
	v_lshl_add_u64 v[26:27], v[24:25], 2, s[82:83]
	v_or_b32_e32 v24, s12, v110
	v_or_b32_e32 v112, v36, v103
	global_load_dword v59, v[26:27], off
	v_lshl_add_u64 v[26:27], v[24:25], 2, s[82:83]
	v_or_b32_e32 v24, s12, v112
	v_or_b32_e32 v114, v36, v105
	global_load_dword v60, v[26:27], off
	v_lshl_add_u64 v[26:27], v[24:25], 2, s[82:83]
	v_or_b32_e32 v24, s12, v114
	v_or_b32_e32 v116, v36, v107
	global_load_dword v61, v[26:27], off
	v_lshl_add_u64 v[26:27], v[24:25], 2, s[82:83]
	v_or_b32_e32 v24, s12, v116
	v_lshl_add_u64 v[24:25], v[24:25], 2, s[82:83]
	global_load_dword v118, v145, s[10:11]
	global_load_dword v62, v[26:27], off
	global_load_dword v63, v[24:25], off
	s_ashr_i32 s7, s6, 31
	s_lshl_b32 s15, s17, 9
	v_readlane_b32 s12, v250, 20
	s_add_u32 s12, s12, s15
	v_readlane_b32 s13, v250, 21
	s_addc_u32 s13, s13, 0
	s_lshl_b32 s14, s14, 2
	s_add_u32 s12, s12, s14
	s_addc_u32 s13, s13, 0
	v_mov_b32_e32 v101, v145
	v_lshl_add_u64 v[120:121], s[12:13], 0, v[100:101]
	s_lshl_b64 s[12:13], s[6:7], 23
	s_or_b32 s14, s12, s15
	s_lshl_b32 s15, s16, 4
	s_and_b32 s15, s15, 0x180
	s_or_b32 s14, s14, s15
	s_mov_b32 s15, s13
	v_mov_b32_e32 v24, 0
	v_lshl_add_u64 v[122:123], v[98:99], 0, s[14:15]
	v_mov_b32_e32 v125, s13
	v_or_b32_e32 v124, s12, v96
	s_mov_b64 s[12:13], 0
	s_mov_b32 s18, 1
	v_mov_b32_e32 v25, v24
	v_mov_b32_e32 v26, v24
	v_mov_b32_e32 v27, v24
	v_mov_b32_e32 v36, v24
	v_mov_b32_e32 v37, v24
	v_mov_b32_e32 v38, v24
	v_mov_b32_e32 v39, v24
	s_mov_b32 s56, 1
	s_add_u32 s14, s8, s56
	s_addc_u32 s15, s9, 0
	s_lshl_b64 s[20:21], s[14:15], 13
	s_lshl_b64 s[14:15], s[14:15], 14
	v_lshl_add_u64 v[224:225], v[82:83], 0, s[14:15]
	v_lshl_add_u64 v[236:237], v[84:85], 0, s[14:15]
	s_lshl_b64 s[14:15], s[56:57], 2
	s_add_u32 s14, s10, s14
	v_mov_b32_e32 v181, s21
	v_or_b32_e32 v180, s20, v102
	v_mov_b32_e32 v183, s21
	v_or_b32_e32 v182, s20, v104
	v_lshl_add_u64 v[242:243], v[86:87], 0, s[20:21]
	s_addc_u32 s15, s11, s15
	v_lshl_add_u64 v[180:181], v[180:181], 2, s[82:83]
	v_lshl_add_u64 v[182:183], v[182:183], 2, s[82:83]
	global_load_dwordx4 v[212:215], v[224:225], off
	global_load_dwordx4 v[216:219], v[224:225], off offset:64
	global_load_dwordx4 v[220:223], v[224:225], off offset:128
	s_nop 0
	global_load_dwordx4 v[224:227], v[224:225], off offset:192
	s_nop 0
	global_load_dwordx4 v[228:231], v[236:237], off
	global_load_dwordx4 v[232:235], v[242:243], off
	s_nop 0
	global_load_dwordx4 v[236:239], v[236:237], off offset:64
	s_nop 0
	global_load_dwordx4 v[242:245], v[242:243], off offset:64
	v_mov_b32_e32 v185, s21
	global_load_dword v143, v145, s[14:15]
	v_or_b32_e32 v184, s20, v108
	global_load_dword v180, v[180:181], off
	v_lshl_add_u64 v[184:185], v[184:185], 2, s[82:83]
	global_load_dword v181, v[182:183], off
	v_mov_b32_e32 v183, s21
	v_or_b32_e32 v182, s20, v106
	v_lshl_add_u64 v[182:183], v[182:183], 2, s[82:83]
	global_load_dword v182, v[182:183], off
	v_mov_b32_e32 v187, s21
	global_load_dword v183, v[184:185], off
	v_mov_b32_e32 v185, s21
	v_or_b32_e32 v184, s20, v110
	v_or_b32_e32 v186, s20, v112
	v_lshl_add_u64 v[184:185], v[184:185], 2, s[82:83]
	v_lshl_add_u64 v[186:187], v[186:187], 2, s[82:83]
	global_load_dword v184, v[184:185], off
	v_mov_b32_e32 v189, s21
	global_load_dword v185, v[186:187], off
	v_mov_b32_e32 v187, s21
	v_or_b32_e32 v186, s20, v114
	v_or_b32_e32 v188, s20, v116
	v_lshl_add_u64 v[186:187], v[186:187], 2, s[82:83]
	v_lshl_add_u64 v[188:189], v[188:189], 2, s[82:83]
	global_load_dword v186, v[186:187], off
	global_load_dword v187, v[188:189], off
	s_waitcnt vmcnt(17)
	s_branch .Lm2_topA
.Lm2_tailB_r0:
	v_pk_mul_f32 v[26:27], v[26:27], v[118:119] op_sel_hi:[1,0]
	v_pk_mul_f32 v[24:25], v[24:25], v[118:119] op_sel_hi:[1,0]
	v_pk_mul_f32 v[30:31], v[38:39], v[118:119] op_sel_hi:[1,0]
	v_pk_mul_f32 v[28:29], v[36:37], v[118:119] op_sel_hi:[1,0]
	s_waitcnt lgkmcnt(3)
	v_mfma_f32_16x16x32_bf16 v[24:27], v[16:19], v[68:71], v[24:27]
	s_add_u32 s12, s12, 0x40000
	s_addc_u32 s13, s13, 0
	s_add_i32 s18, s18, 1
	s_waitcnt lgkmcnt(1)
	v_mfma_f32_16x16x32_bf16 v[16:19], v[16:19], v[64:67], v[28:31]
	s_waitcnt vmcnt(26)
	v_mov_b64_e32 v[32:33], v[52:53]
	s_cmp_eq_u32 s12, 0x800000
	v_mov_b64_e32 v[34:35], v[54:55]
	v_mfma_f32_16x16x32_bf16 v[24:27], v[20:23], v[56:59], v[24:27]
	v_mov_b64_e32 v[28:29], v[44:45]
	s_waitcnt vmcnt(24)
	v_mov_b32_e32 v56, v126
	s_waitcnt vmcnt(23)
	v_mov_b32_e32 v57, v127
	s_waitcnt lgkmcnt(0)
	v_mfma_f32_16x16x32_bf16 v[36:39], v[20:23], v[60:63], v[16:19]
	v_cvt_pk_bf16_f32 v16, v24, v25
	v_cvt_pk_bf16_f32 v17, v26, v27
	ds_write_b64 v119, v[16:17]
	v_cvt_pk_bf16_f32 v16, v36, v37
	v_cvt_pk_bf16_f32 v17, v38, v39
	ds_write_b64 v119, v[16:17] offset:4352
	s_waitcnt lgkmcnt(0)
	s_barrier
	v_mov_b64_e32 v[16:17], v[40:41]
	v_mov_b64_e32 v[20:21], v[48:49]
	s_waitcnt vmcnt(22)
	v_mov_b32_e32 v58, v128
	s_waitcnt vmcnt(21)
	v_mov_b32_e32 v59, v129
	s_waitcnt vmcnt(20)
	v_mov_b32_e32 v60, v130
	s_waitcnt vmcnt(19)
	v_mov_b32_e32 v61, v131
	s_waitcnt vmcnt(18)
	v_mov_b32_e32 v62, v132
	s_waitcnt vmcnt(17)
	v_mov_b32_e32 v63, v133
	v_mov_b64_e32 v[30:31], v[46:47]
	v_mov_b64_e32 v[18:19], v[42:43]
	v_mov_b64_e32 v[22:23], v[50:51]
	v_mov_b32_e32 v118, v101
	s_cbranch_scc1 .LBB0_171
.Lm2_topA:
	s_add_i32 s56, s18, 1
	s_min_i32 s56, s56, 31
	s_add_u32 s14, s8, s56
	s_addc_u32 s15, s9, 0
	s_nop 0
	v_mov_b64_e32 v[66:67], v[14:15]
	s_lshl_b64 s[20:21], s[14:15], 13
	s_lshl_b64 s[14:15], s[14:15], 14
	v_mov_b64_e32 v[64:65], v[12:13]
	v_lshl_add_u64 v[12:13], v[82:83], 0, s[14:15]
	v_lshl_add_u64 v[48:49], v[84:85], 0, s[14:15]
	s_lshl_b64 s[14:15], s[56:57], 2
	s_add_u32 s14, s10, s14
	v_mov_b32_e32 v127, s21
	v_or_b32_e32 v126, s20, v102
	v_mov_b32_e32 v129, s21
	v_or_b32_e32 v128, s20, v104
	v_mov_b64_e32 v[70:71], v[10:11]
	v_mov_b64_e32 v[74:75], v[6:7]
	v_mov_b64_e32 v[78:79], v[2:3]
	v_lshl_add_u64 v[52:53], v[86:87], 0, s[20:21]
	s_addc_u32 s15, s11, s15
	v_lshl_add_u64 v[126:127], v[126:127], 2, s[82:83]
	v_lshl_add_u64 v[128:129], v[128:129], 2, s[82:83]
	v_mov_b64_e32 v[68:69], v[8:9]
	v_mov_b64_e32 v[72:73], v[4:5]
	v_mov_b64_e32 v[76:77], v[0:1]
	global_load_dwordx4 v[0:3], v[12:13], off
	global_load_dwordx4 v[4:7], v[12:13], off offset:64
	global_load_dwordx4 v[8:11], v[12:13], off offset:128
	s_nop 0
	global_load_dwordx4 v[12:15], v[12:13], off offset:192
	s_nop 0
	global_load_dwordx4 v[40:43], v[48:49], off
	global_load_dwordx4 v[44:47], v[52:53], off
	s_nop 0
	global_load_dwordx4 v[48:51], v[48:49], off offset:64
	s_nop 0
	global_load_dwordx4 v[52:55], v[52:53], off offset:64
	v_mov_b32_e32 v131, s21
	global_load_dword v101, v145, s[14:15]
	v_or_b32_e32 v130, s20, v108
	global_load_dword v126, v[126:127], off
	v_lshl_add_u64 v[130:131], v[130:131], 2, s[82:83]
	global_load_dword v127, v[128:129], off
	v_mov_b32_e32 v129, s21
	v_or_b32_e32 v128, s20, v106
	v_lshl_add_u64 v[128:129], v[128:129], 2, s[82:83]
	global_load_dword v128, v[128:129], off
	v_mov_b32_e32 v133, s21
	global_load_dword v129, v[130:131], off
	v_mov_b32_e32 v131, s21
	v_or_b32_e32 v130, s20, v110
	v_or_b32_e32 v132, s20, v112
	v_lshl_add_u64 v[130:131], v[130:131], 2, s[82:83]
	v_lshl_add_u64 v[132:133], v[132:133], 2, s[82:83]
	global_load_dword v130, v[130:131], off
	v_mov_b32_e32 v135, s21
	global_load_dword v131, v[132:133], off
	v_mov_b32_e32 v133, s21
	v_or_b32_e32 v132, s20, v114
	v_or_b32_e32 v134, s20, v116
	v_lshl_add_u64 v[132:133], v[132:133], 2, s[82:83]
	v_lshl_add_u64 v[134:135], v[134:135], 2, s[82:83]
	global_load_dword v132, v[132:133], off
	v_add_u32_e32 v142, v81, v109
	global_load_dword v133, v[134:135], off
	ds_read_b128 v[162:165], v142
	ds_read_b128 v[166:169], v142 offset:4352
	ds_read_b128 v[172:175], v142 offset:64
	ds_read_b128 v[176:179], v142 offset:4416
	s_andn2_b64 vcc, exec, s[2:3]
	s_waitcnt lgkmcnt(2)
	v_mfma_f32_16x16x32_bf16 v[134:137], v[76:79], v[162:165], 0
	v_mfma_f32_16x16x32_bf16 v[138:141], v[76:79], v[166:169], 0
	s_nop 2
	ds_read_b128 v[162:165], v142 offset:128
	ds_read_b128 v[166:169], v142 offset:4480
	s_waitcnt lgkmcnt(2)
	v_mfma_f32_16x16x32_bf16 v[134:137], v[72:75], v[172:175], v[134:137]
	v_mfma_f32_16x16x32_bf16 v[138:141], v[72:75], v[176:179], v[138:141]
	s_nop 2
	ds_read_b128 v[172:175], v142 offset:192
	ds_read_b128 v[176:179], v142 offset:4544
	s_waitcnt lgkmcnt(2)
	v_mfma_f32_16x16x32_bf16 v[134:137], v[68:71], v[162:165], v[134:137]
	v_mfma_f32_16x16x32_bf16 v[138:141], v[68:71], v[166:169], v[138:141]
	s_waitcnt lgkmcnt(0)
	v_mfma_f32_16x16x32_bf16 v[72:75], v[64:67], v[172:175], v[134:137]
	v_mfma_f32_16x16x32_bf16 v[76:79], v[64:67], v[176:179], v[138:141]
	s_nop 7
	s_cbranch_vccnz .Lm2_179a
	s_waitcnt vmcnt(42)
	v_sub_f32_e32 v56, v56, v72
	s_waitcnt vmcnt(41)
	v_sub_f32_e32 v57, v57, v73
	v_cvt_pk_bf16_f32 v56, v56, v57
	s_waitcnt vmcnt(40)
	v_sub_f32_e32 v57, v58, v74
	s_waitcnt vmcnt(39)
	v_sub_f32_e32 v58, v59, v75
	v_cvt_pk_bf16_f32 v57, v57, v58
	ds_write_b64 v117, v[56:57] offset:8704
	s_waitcnt vmcnt(38)
	v_sub_f32_e32 v56, v60, v76
	s_waitcnt vmcnt(37)
	v_sub_f32_e32 v57, v61, v77
	v_cvt_pk_bf16_f32 v56, v56, v57
	s_waitcnt vmcnt(35)
	v_sub_f32_e32 v57, v62, v78
	s_waitcnt vmcnt(34)
	v_sub_f32_e32 v58, v63, v79
	v_cvt_pk_bf16_f32 v57, v57, v58
	ds_write_b64 v117, v[56:57] offset:11008
.Lm2_179a:
	s_waitcnt lgkmcnt(0)
	s_barrier
	s_waitcnt vmcnt(38)
	v_add_u32_e32 v60, v81, v111
	ds_read_b128 v[68:71], v60 offset:8704
	ds_read_b128 v[56:59], v60 offset:8768
	ds_read_b128 v[64:67], v60 offset:11008
	s_waitcnt vmcnt(34)
	ds_read_b128 v[60:63], v60 offset:11072
	s_andn2_b64 vcc, exec, s[4:5]
	s_mov_b64 s[14:15], -1
	s_cbranch_vccnz .Lm2_181a
	s_mov_b64 s[14:15], 0

.Lm2_tailA_r0:
	v_pk_mul_f32 v[26:27], v[26:27], v[118:119] op_sel_hi:[1,0]
	v_pk_mul_f32 v[24:25], v[24:25], v[118:119] op_sel_hi:[1,0]
	v_pk_mul_f32 v[30:31], v[38:39], v[118:119] op_sel_hi:[1,0]
	v_pk_mul_f32 v[28:29], v[36:37], v[118:119] op_sel_hi:[1,0]
	s_waitcnt lgkmcnt(3)
	v_mfma_f32_16x16x32_bf16 v[24:27], v[16:19], v[68:71], v[24:27]
	s_add_u32 s12, s12, 0x40000
	s_addc_u32 s13, s13, 0
	s_add_i32 s18, s18, 1
	s_waitcnt lgkmcnt(1)
	v_mfma_f32_16x16x32_bf16 v[16:19], v[16:19], v[64:67], v[28:31]
	s_waitcnt vmcnt(26)
	v_mov_b64_e32 v[32:33], v[242:243]
	s_cmp_eq_u32 s12, 0x800000
	v_mov_b64_e32 v[34:35], v[244:245]
	v_mfma_f32_16x16x32_bf16 v[24:27], v[20:23], v[56:59], v[24:27]
	v_mov_b64_e32 v[28:29], v[232:233]
	s_waitcnt vmcnt(24)
	v_mov_b32_e32 v56, v180
	s_waitcnt vmcnt(23)
	v_mov_b32_e32 v57, v181
	s_waitcnt lgkmcnt(0)
	v_mfma_f32_16x16x32_bf16 v[36:39], v[20:23], v[60:63], v[16:19]
	v_cvt_pk_bf16_f32 v16, v24, v25
	v_cvt_pk_bf16_f32 v17, v26, v27
	ds_write_b64 v119, v[16:17]
	v_cvt_pk_bf16_f32 v16, v36, v37
	v_cvt_pk_bf16_f32 v17, v38, v39
	ds_write_b64 v119, v[16:17] offset:4352
	s_waitcnt lgkmcnt(0)
	s_barrier
	v_mov_b64_e32 v[16:17], v[228:229]
	v_mov_b64_e32 v[20:21], v[236:237]
	s_waitcnt vmcnt(22)
	v_mov_b32_e32 v58, v182
	s_waitcnt vmcnt(21)
	v_mov_b32_e32 v59, v183
	s_waitcnt vmcnt(20)
	v_mov_b32_e32 v60, v184
	s_waitcnt vmcnt(19)
	v_mov_b32_e32 v61, v185
	s_waitcnt vmcnt(18)
	v_mov_b32_e32 v62, v186
	s_waitcnt vmcnt(17)
	v_mov_b32_e32 v63, v187
	v_mov_b64_e32 v[30:31], v[234:235]
	v_mov_b64_e32 v[18:19], v[230:231]
	v_mov_b64_e32 v[22:23], v[238:239]
	v_mov_b32_e32 v118, v143
	s_cbranch_scc1 .LBB0_171
.Lm2_topB:
	s_add_i32 s56, s18, 1
	s_min_i32 s56, s56, 31
	s_add_u32 s14, s8, s56
	s_addc_u32 s15, s9, 0
	s_nop 0
	v_mov_b64_e32 v[66:67], v[226:227]
	s_lshl_b64 s[20:21], s[14:15], 13
	s_lshl_b64 s[14:15], s[14:15], 14
	v_mov_b64_e32 v[64:65], v[224:225]
	v_lshl_add_u64 v[224:225], v[82:83], 0, s[14:15]
	v_lshl_add_u64 v[236:237], v[84:85], 0, s[14:15]
	s_lshl_b64 s[14:15], s[56:57], 2
	s_add_u32 s14, s10, s14
	v_mov_b32_e32 v181, s21
	v_or_b32_e32 v180, s20, v102
	v_mov_b32_e32 v183, s21
	v_or_b32_e32 v182, s20, v104
	v_mov_b64_e32 v[70:71], v[222:223]
	v_mov_b64_e32 v[74:75], v[218:219]
	v_mov_b64_e32 v[78:79], v[214:215]
	v_lshl_add_u64 v[242:243], v[86:87], 0, s[20:21]
	s_addc_u32 s15, s11, s15
	v_lshl_add_u64 v[180:181], v[180:181], 2, s[82:83]
	v_lshl_add_u64 v[182:183], v[182:183], 2, s[82:83]
	v_mov_b64_e32 v[68:69], v[220:221]
	v_mov_b64_e32 v[72:73], v[216:217]
	v_mov_b64_e32 v[76:77], v[212:213]
	global_load_dwordx4 v[212:215], v[224:225], off
	global_load_dwordx4 v[216:219], v[224:225], off offset:64
	global_load_dwordx4 v[220:223], v[224:225], off offset:128
	s_nop 0
	global_load_dwordx4 v[224:227], v[224:225], off offset:192
	s_nop 0
	global_load_dwordx4 v[228:231], v[236:237], off
	global_load_dwordx4 v[232:235], v[242:243], off
	s_nop 0
	global_load_dwordx4 v[236:239], v[236:237], off offset:64
	s_nop 0
	global_load_dwordx4 v[242:245], v[242:243], off offset:64
	v_mov_b32_e32 v185, s21
	global_load_dword v143, v145, s[14:15]
	v_or_b32_e32 v184, s20, v108
	global_load_dword v180, v[180:181], off
	v_lshl_add_u64 v[184:185], v[184:185], 2, s[82:83]
	global_load_dword v181, v[182:183], off
	v_mov_b32_e32 v183, s21
	v_or_b32_e32 v182, s20, v106
	v_lshl_add_u64 v[182:183], v[182:183], 2, s[82:83]
	global_load_dword v182, v[182:183], off
	v_mov_b32_e32 v187, s21
	global_load_dword v183, v[184:185], off
	v_mov_b32_e32 v185, s21
	v_or_b32_e32 v184, s20, v110
	v_or_b32_e32 v186, s20, v112
	v_lshl_add_u64 v[184:185], v[184:185], 2, s[82:83]
	v_lshl_add_u64 v[186:187], v[186:187], 2, s[82:83]
	global_load_dword v184, v[184:185], off
	v_mov_b32_e32 v189, s21
	global_load_dword v185, v[186:187], off
	v_mov_b32_e32 v187, s21
	v_or_b32_e32 v186, s20, v114
	v_or_b32_e32 v188, s20, v116
	v_lshl_add_u64 v[186:187], v[186:187], 2, s[82:83]
	v_lshl_add_u64 v[188:189], v[188:189], 2, s[82:83]
	global_load_dword v186, v[186:187], off
	v_add_u32_e32 v142, v81, v109
	global_load_dword v187, v[188:189], off
	ds_read_b128 v[162:165], v142
	ds_read_b128 v[166:169], v142 offset:4352
	ds_read_b128 v[172:175], v142 offset:64
	ds_read_b128 v[176:179], v142 offset:4416
	s_andn2_b64 vcc, exec, s[2:3]
	s_waitcnt lgkmcnt(2)
	v_mfma_f32_16x16x32_bf16 v[134:137], v[76:79], v[162:165], 0
	v_mfma_f32_16x16x32_bf16 v[138:141], v[76:79], v[166:169], 0
	s_nop 2
	ds_read_b128 v[162:165], v142 offset:128
	ds_read_b128 v[166:169], v142 offset:4480
	s_waitcnt lgkmcnt(2)
	v_mfma_f32_16x16x32_bf16 v[134:137], v[72:75], v[172:175], v[134:137]
	v_mfma_f32_16x16x32_bf16 v[138:141], v[72:75], v[176:179], v[138:141]
	s_nop 2
	ds_read_b128 v[172:175], v142 offset:192
	ds_read_b128 v[176:179], v142 offset:4544
	s_waitcnt lgkmcnt(2)
	v_mfma_f32_16x16x32_bf16 v[134:137], v[68:71], v[162:165], v[134:137]
	v_mfma_f32_16x16x32_bf16 v[138:141], v[68:71], v[166:169], v[138:141]
	s_waitcnt lgkmcnt(0)
	v_mfma_f32_16x16x32_bf16 v[72:75], v[64:67], v[172:175], v[134:137]
	v_mfma_f32_16x16x32_bf16 v[76:79], v[64:67], v[176:179], v[138:141]
	s_nop 7
	s_cbranch_vccnz .Lm2_179b
	s_waitcnt vmcnt(42)
	v_sub_f32_e32 v56, v56, v72
	s_waitcnt vmcnt(41)
	v_sub_f32_e32 v57, v57, v73
	v_cvt_pk_bf16_f32 v56, v56, v57
	s_waitcnt vmcnt(40)
	v_sub_f32_e32 v57, v58, v74
	s_waitcnt vmcnt(39)
	v_sub_f32_e32 v58, v59, v75
	v_cvt_pk_bf16_f32 v57, v57, v58
	ds_write_b64 v117, v[56:57] offset:8704
	s_waitcnt vmcnt(38)
	v_sub_f32_e32 v56, v60, v76
	s_waitcnt vmcnt(37)
	v_sub_f32_e32 v57, v61, v77
	v_cvt_pk_bf16_f32 v56, v56, v57
	s_waitcnt vmcnt(35)
	v_sub_f32_e32 v57, v62, v78
	s_waitcnt vmcnt(34)
	v_sub_f32_e32 v58, v63, v79
	v_cvt_pk_bf16_f32 v57, v57, v58
	ds_write_b64 v117, v[56:57] offset:11008

.Lm2_tailA_r1:
	v_pk_mul_f32 v[26:27], v[26:27], v[118:119] op_sel_hi:[1,0]
	v_pk_mul_f32 v[24:25], v[24:25], v[118:119] op_sel_hi:[1,0]
	v_pk_mul_f32 v[30:31], v[38:39], v[118:119] op_sel_hi:[1,0]
	v_pk_mul_f32 v[28:29], v[36:37], v[118:119] op_sel_hi:[1,0]
	s_waitcnt lgkmcnt(3)
	v_mfma_f32_16x16x32_bf16 v[24:27], v[16:19], v[68:71], v[24:27]
	s_add_u32 s12, s12, 0x40000
	s_addc_u32 s13, s13, 0
	s_add_i32 s18, s18, 1
	s_waitcnt lgkmcnt(1)
	v_mfma_f32_16x16x32_bf16 v[16:19], v[16:19], v[64:67], v[28:31]
	s_waitcnt vmcnt(34)
	v_mov_b64_e32 v[32:33], v[242:243]
	s_cmp_eq_u32 s12, 0x800000
	v_mov_b64_e32 v[34:35], v[244:245]
	v_mfma_f32_16x16x32_bf16 v[24:27], v[20:23], v[56:59], v[24:27]
	v_mov_b64_e32 v[28:29], v[232:233]
	s_waitcnt vmcnt(32)
	v_mov_b32_e32 v56, v180
	s_waitcnt vmcnt(31)
	v_mov_b32_e32 v57, v181
	s_waitcnt lgkmcnt(0)
	v_mfma_f32_16x16x32_bf16 v[36:39], v[20:23], v[60:63], v[16:19]
	v_cvt_pk_bf16_f32 v16, v24, v25
	v_cvt_pk_bf16_f32 v17, v26, v27
	ds_write_b64 v119, v[16:17]
	v_cvt_pk_bf16_f32 v16, v36, v37
	v_cvt_pk_bf16_f32 v17, v38, v39
	ds_write_b64 v119, v[16:17] offset:4352
	s_waitcnt lgkmcnt(0)
	s_barrier
	v_mov_b64_e32 v[16:17], v[228:229]
	v_mov_b64_e32 v[20:21], v[236:237]
	s_waitcnt vmcnt(30)
	v_mov_b32_e32 v58, v182
	s_waitcnt vmcnt(29)
	v_mov_b32_e32 v59, v183
	s_waitcnt vmcnt(28)
	v_mov_b32_e32 v60, v184
	s_waitcnt vmcnt(27)
	v_mov_b32_e32 v61, v185
	s_waitcnt vmcnt(26)
	v_mov_b32_e32 v62, v186
	s_waitcnt vmcnt(25)
	v_mov_b32_e32 v63, v187
	v_mov_b64_e32 v[30:31], v[234:235]
	v_mov_b64_e32 v[18:19], v[230:231]
	v_mov_b64_e32 v[22:23], v[238:239]
	v_mov_b32_e32 v118, v143
	s_cbranch_scc1 .LBB0_171
	s_branch .Lm2_topB
.Lm2_tailB_r1:
	v_pk_mul_f32 v[26:27], v[26:27], v[118:119] op_sel_hi:[1,0]
	v_pk_mul_f32 v[24:25], v[24:25], v[118:119] op_sel_hi:[1,0]
	v_pk_mul_f32 v[30:31], v[38:39], v[118:119] op_sel_hi:[1,0]
	v_pk_mul_f32 v[28:29], v[36:37], v[118:119] op_sel_hi:[1,0]
	s_waitcnt lgkmcnt(3)
	v_mfma_f32_16x16x32_bf16 v[24:27], v[16:19], v[68:71], v[24:27]
	s_add_u32 s12, s12, 0x40000
	s_addc_u32 s13, s13, 0
	s_add_i32 s18, s18, 1
	s_waitcnt lgkmcnt(1)
	v_mfma_f32_16x16x32_bf16 v[16:19], v[16:19], v[64:67], v[28:31]
	s_waitcnt vmcnt(34)
	v_mov_b64_e32 v[32:33], v[52:53]
	s_cmp_eq_u32 s12, 0x800000
	v_mov_b64_e32 v[34:35], v[54:55]
	v_mfma_f32_16x16x32_bf16 v[24:27], v[20:23], v[56:59], v[24:27]
	v_mov_b64_e32 v[28:29], v[44:45]
	s_waitcnt vmcnt(32)
	v_mov_b32_e32 v56, v126
	s_waitcnt vmcnt(31)
	v_mov_b32_e32 v57, v127
	s_waitcnt lgkmcnt(0)
	v_mfma_f32_16x16x32_bf16 v[36:39], v[20:23], v[60:63], v[16:19]
	v_cvt_pk_bf16_f32 v16, v24, v25
	v_cvt_pk_bf16_f32 v17, v26, v27
	ds_write_b64 v119, v[16:17]
	v_cvt_pk_bf16_f32 v16, v36, v37
	v_cvt_pk_bf16_f32 v17, v38, v39
	ds_write_b64 v119, v[16:17] offset:4352
	s_waitcnt lgkmcnt(0)
	s_barrier
	v_mov_b64_e32 v[16:17], v[40:41]
	v_mov_b64_e32 v[20:21], v[48:49]
	s_waitcnt vmcnt(30)
	v_mov_b32_e32 v58, v128
	s_waitcnt vmcnt(29)
	v_mov_b32_e32 v59, v129
	s_waitcnt vmcnt(28)
	v_mov_b32_e32 v60, v130
	s_waitcnt vmcnt(27)
	v_mov_b32_e32 v61, v131
	s_waitcnt vmcnt(26)
	v_mov_b32_e32 v62, v132
	s_waitcnt vmcnt(25)
	v_mov_b32_e32 v63, v133
	v_mov_b64_e32 v[30:31], v[46:47]
	v_mov_b64_e32 v[18:19], v[42:43]
	v_mov_b64_e32 v[22:23], v[50:51]
	v_mov_b32_e32 v118, v101
	s_cbranch_scc1 .LBB0_171
	s_branch .Lm2_topA

.LBB0_283:
	s_mov_b32 s40, 0
	s_ashr_i32 s41, s40, 31
	s_andn2_b64 vcc, exec, s[30:31]
	s_mov_b64 s[28:29], -1
	s_cbranch_vccnz .LBB0_287
	s_lshl_b64 s[28:29], s[40:41], 2
	s_add_u32 s28, s46, s28
	s_addc_u32 s29, s47, s29
	v_lshl_add_u64 v[0:1], v[48:49], 0, s[28:29]
	v_add_co_u32_e32 v4, vcc, 0x3000, v0
	s_mov_b64 s[8:9], 0x3000
	s_nop 0
	v_addc_co_u32_e32 v5, vcc, 0, v1, vcc
	global_load_dwordx4 v[24:27], v[0:1], off offset:16
	global_load_dwordx4 v[28:31], v[0:1], off
	v_lshl_add_u64 v[2:3], v[0:1], 0, s[8:9]
	global_load_dwordx4 v[12:15], v[4:5], off
	global_load_dwordx4 v[8:11], v[2:3], off offset:16
	s_mov_b64 s[28:29], 0x6000
	v_add_co_u32_e32 v4, vcc, s83, v0
	v_lshl_add_u64 v[2:3], v[0:1], 0, s[28:29]
	s_nop 0
	v_addc_co_u32_e32 v5, vcc, 0, v1, vcc
	s_mov_b64 s[28:29], 0x9000
	global_load_dwordx4 v[20:23], v[4:5], off
	global_load_dwordx4 v[16:19], v[2:3], off offset:16
	v_lshl_add_u64 v[2:3], v[0:1], 0, s[28:29]
	s_lshl_b64 s[28:29], s[40:41], 1
	s_add_u32 s28, s74, s28
	v_add_co_u32_e32 v0, vcc, 0x9000, v0
	s_addc_u32 s29, s75, s29
	s_nop 0
	v_addc_co_u32_e32 v1, vcc, 0, v1, vcc
	v_lshl_add_u64 v[66:67], s[28:29], 0, v[50:51]
	global_load_dwordx4 v[4:7], v[0:1], off
	s_nop 0
	global_load_dwordx4 v[0:3], v[2:3], off offset:16
	v_add_co_u32_e32 v62, vcc, 0x13095000, v66
	s_nop 1
	v_addc_co_u32_e32 v63, vcc, 0, v67, vcc
	global_load_dwordx4 v[112:115], v[62:63], off offset:2560
	v_add_co_u32_e32 v62, vcc, 0x13099000, v66
	s_nop 1
	v_addc_co_u32_e32 v63, vcc, 0, v67, vcc
	global_load_dwordx4 v[116:119], v[62:63], off offset:3072
	v_add_co_u32_e32 v62, vcc, 0x1309d000, v66
	s_nop 1
	v_addc_co_u32_e32 v63, vcc, 0, v67, vcc
	global_load_dwordx4 v[222:225], v[62:63], off offset:3584
	v_add_co_u32_e32 v62, vcc, 0x130a2000, v66
	s_nop 1
	v_addc_co_u32_e32 v63, vcc, 0, v67, vcc
	global_load_dwordx4 v[226:229], v[62:63], off
	v_add_co_u32_e32 v62, vcc, 0x130a6000, v66
	s_nop 1
	v_addc_co_u32_e32 v63, vcc, 0, v67, vcc
	global_load_dwordx4 v[230:233], v[62:63], off offset:512
	v_add_co_u32_e32 v62, vcc, 0x130aa000, v66
	s_nop 1
	v_addc_co_u32_e32 v63, vcc, 0, v67, vcc
	global_load_dwordx4 v[234:237], v[62:63], off offset:1024
	v_add_co_u32_e32 v62, vcc, 0x130ae000, v66
	s_nop 1
	v_addc_co_u32_e32 v63, vcc, 0, v67, vcc
	global_load_dwordx4 v[242:245], v[62:63], off offset:1536
	v_add_co_u32_e32 v62, vcc, 0x130b2000, v66
	s_nop 1
	v_addc_co_u32_e32 v63, vcc, 0, v67, vcc
	global_load_dwordx4 v[246:249], v[62:63], off offset:2048
	v_add_co_u32_e32 v62, vcc, 0x130b6000, v66
	s_nop 1
	v_addc_co_u32_e32 v63, vcc, 0, v67, vcc
	global_load_dwordx2 v[80:81], v[62:63], off offset:2560
	global_load_dwordx2 v[86:87], v[62:63], off offset:2568
	v_add_co_u32_e32 v62, vcc, 0x130ba000, v66
	s_nop 1
	v_addc_co_u32_e32 v63, vcc, 0, v67, vcc
	global_load_dwordx4 v[62:65], v[62:63], off offset:3072
	s_waitcnt vmcnt(10)
	v_cndmask_b32_e64 v76, v112, 0, s[56:57]
	v_cndmask_b32_e64 v75, v113, 0, s[56:57]
	v_cndmask_b32_e64 v68, v115, 0, s[56:57]
	v_cndmask_b32_e64 v69, v114, 0, s[56:57]
	v_lshlrev_b32_e32 v70, 16, v76
	v_lshlrev_b32_e32 v102, 16, v69
	v_and_b32_e32 v106, 0xffff0000, v69
	v_lshlrev_b32_e32 v152, 16, v68
	v_and_b32_e32 v220, 0xffff0000, v68
	v_and_b32_e32 v76, 0xffff0000, v76
	v_lshlrev_b32_e32 v84, 16, v75
	v_and_b32_e32 v98, 0xffff0000, v75
	s_waitcnt vmcnt(9)
	v_cndmask_b32_e64 v77, v116, 0, s[58:59]
	v_cndmask_b32_e64 v94, v117, 0, s[58:59]
	v_cndmask_b32_e64 v92, v119, 0, s[58:59]
	v_cndmask_b32_e64 v93, v118, 0, s[58:59]
	v_lshlrev_b32_e32 v71, 16, v77
	v_and_b32_e32 v77, 0xffff0000, v77
	v_lshlrev_b32_e32 v85, 16, v94
	v_and_b32_e32 v99, 0xffff0000, v94
	v_lshlrev_b32_e32 v103, 16, v93
	v_and_b32_e32 v107, 0xffff0000, v93
	v_lshlrev_b32_e32 v153, 16, v92
	v_and_b32_e32 v221, 0xffff0000, v92
	s_waitcnt vmcnt(8)
	v_cndmask_b32_e64 v95, v222, 0, s[60:61]
	v_cndmask_b32_e64 v74, v223, 0, s[60:61]
	v_cndmask_b32_e64 v82, v225, 0, s[60:61]
	v_cndmask_b32_e64 v78, v224, 0, s[60:61]
	v_lshlrev_b32_e32 v68, 16, v95
	s_waitcnt vmcnt(7)
	v_cndmask_b32_e64 v96, v226, 0, s[48:49]
	v_cndmask_b32_e64 v110, v227, 0, s[48:49]
	v_cndmask_b32_e64 v83, v229, 0, s[48:49]
	v_cndmask_b32_e64 v79, v228, 0, s[48:49]
	v_lshlrev_b32_e32 v69, 16, v96
	v_and_b32_e32 v75, 0xffff0000, v110
	s_waitcnt vmcnt(6)
	v_cndmask_b32_e64 v135, v230, 0, s[48:49]
	v_cndmask_b32_e64 v132, v231, 0, s[48:49]
	v_cndmask_b32_e64 v126, v233, 0, s[48:49]
	v_cndmask_b32_e64 v122, v232, 0, s[48:49]
	s_waitcnt vmcnt(5)
	v_cndmask_b32_e64 v136, v234, 0, s[48:49]
	v_cndmask_b32_e64 v133, v235, 0, s[48:49]
	v_cndmask_b32_e64 v127, v237, 0, s[48:49]
	v_cndmask_b32_e64 v123, v236, 0, s[48:49]
	s_waitcnt vmcnt(4)
	v_cndmask_b32_e64 v128, v242, 0, s[48:49]
	v_cndmask_b32_e64 v130, v243, 0, s[48:49]
	v_cndmask_b32_e64 v191, v245, 0, s[48:49]
	v_cndmask_b32_e64 v124, v244, 0, s[48:49]
	s_waitcnt vmcnt(3)
	v_cndmask_b32_e64 v129, v246, 0, s[48:49]
	v_cndmask_b32_e64 v131, v247, 0, s[48:49]
	v_cndmask_b32_e64 v216, v249, 0, s[48:49]
	v_cndmask_b32_e64 v125, v248, 0, s[48:49]
	s_waitcnt vmcnt(1)
	v_cndmask_b32_e64 v192, v80, 0, s[48:49]
	v_cndmask_b32_e64 v212, v81, 0, s[48:49]
	v_cndmask_b32_e64 v193, v87, 0, s[48:49]
	v_cndmask_b32_e64 v194, v86, 0, s[48:49]
	s_waitcnt vmcnt(0)
	v_cndmask_b32_e64 v195, v65, 0, s[48:49]
	v_cndmask_b32_e64 v213, v64, 0, s[48:49]
	v_cndmask_b32_e64 v214, v63, 0, s[48:49]
	v_cndmask_b32_e64 v215, v62, 0, s[48:49]
	v_mov_b32_e32 v64, v28
	v_mov_b32_e32 v65, v12
	v_mov_b32_e32 v62, v30
	v_mov_b32_e32 v63, v14
	v_mov_b32_e32 v14, v31
	v_mov_b32_e32 v30, v24
	v_mov_b32_e32 v31, v8
	v_mov_b32_e32 v8, v25
	v_pk_mov_b32 v[24:25], v[70:71], v[68:69] op_sel:[1,0]
	v_pk_mul_f32 v[72:73], v[64:65], v[70:71]
	v_pk_mul_f32 v[116:117], v[64:65], v[24:25]
	v_mov_b32_e32 v24, v20
	v_mov_b32_e32 v25, v4
	v_mov_b32_e32 v12, v29
	v_mov_b32_e32 v28, v26
	v_mov_b32_e32 v29, v10
	v_mov_b32_e32 v10, v27
	v_pk_mul_f32 v[26:27], v[24:25], v[68:69]
	v_add_f32_e32 v4, v72, v73
	v_add_f32_e32 v4, v4, v26
	v_and_b32_e32 v71, 0xffff0000, v96
	v_and_b32_e32 v70, 0xffff0000, v95
	v_pk_mul_f32 v[80:81], v[12:13], v[76:77]
	v_add_f32_e32 v134, v4, v27
	v_pk_mov_b32 v[26:27], v[76:77], v[70:71] op_sel:[1,0]
	v_mov_b32_e32 v4, v21
	v_pk_mul_f32 v[94:95], v[12:13], v[26:27]
	v_pk_mul_f32 v[20:21], v[4:5], v[70:71]
	v_add_f32_e32 v26, v80, v81
	v_add_f32_e32 v20, v26, v20
	v_lshlrev_b32_e32 v73, 16, v110
	v_lshlrev_b32_e32 v72, 16, v74
	v_add_f32_e32 v137, v20, v21
	v_pk_mov_b32 v[20:21], v[84:85], v[72:73] op_sel:[1,0]
	v_pk_mul_f32 v[86:87], v[62:63], v[84:85]
	v_pk_mul_f32 v[118:119], v[62:63], v[20:21]
	v_mov_b32_e32 v20, v22
	v_mov_b32_e32 v21, v6
	v_pk_mul_f32 v[26:27], v[20:21], v[72:73]
	v_add_f32_e32 v6, v86, v87
	v_add_f32_e32 v6, v6, v26
	v_and_b32_e32 v74, 0xffff0000, v74
	v_pk_mul_f32 v[100:101], v[14:15], v[98:99]
	v_add_f32_e32 v86, v6, v27
	v_pk_mov_b32 v[26:27], v[98:99], v[74:75] op_sel:[1,0]
	v_mov_b32_e32 v6, v23
	v_pk_mul_f32 v[98:99], v[14:15], v[26:27]
	v_pk_mul_f32 v[22:23], v[6:7], v[74:75]
	v_add_f32_e32 v26, v100, v101
	v_add_f32_e32 v22, v26, v22
	v_lshlrev_b32_e32 v77, 16, v79
	v_lshlrev_b32_e32 v76, 16, v78
	v_add_f32_e32 v87, v22, v23
	v_pk_mov_b32 v[22:23], v[102:103], v[76:77] op_sel:[1,0]
	v_pk_mul_f32 v[104:105], v[30:31], v[102:103]
	v_pk_mul_f32 v[120:121], v[30:31], v[22:23]
	v_mov_b32_e32 v22, v16
	v_mov_b32_e32 v23, v0
	v_pk_mul_f32 v[26:27], v[22:23], v[76:77]
	v_add_f32_e32 v0, v104, v105
	v_add_f32_e32 v0, v0, v26
	v_and_b32_e32 v79, 0xffff0000, v79
	v_and_b32_e32 v78, 0xffff0000, v78
	v_pk_mul_f32 v[112:113], v[8:9], v[106:107]
	v_pk_mul_f32 v[218:219], v[28:29], v[152:153]
	v_add_f32_e32 v152, v0, v27
	v_pk_mov_b32 v[26:27], v[106:107], v[78:79] op_sel:[1,0]
	v_mov_b32_e32 v0, v17
	v_pk_mul_f32 v[102:103], v[8:9], v[26:27]
	v_pk_mul_f32 v[16:17], v[0:1], v[78:79]
	v_add_f32_e32 v26, v112, v113
	v_add_f32_e32 v16, v26, v16
	v_lshlrev_b32_e32 v81, 16, v83
	v_lshlrev_b32_e32 v80, 16, v82
	v_add_f32_e32 v217, v16, v17
	v_pk_mov_b32 v[16:17], v[152:153], v[80:81] op_sel:[1,0]
	v_mov_b32_e32 v26, v18
	v_mov_b32_e32 v27, v2
	v_pk_mul_f32 v[112:113], v[28:29], v[16:17]
	v_pk_mul_f32 v[16:17], v[26:27], v[80:81]
	v_add_f32_e32 v2, v218, v219
	v_add_f32_e32 v2, v2, v16
	v_and_b32_e32 v83, 0xffff0000, v83
	v_and_b32_e32 v82, 0xffff0000, v82
	v_pk_mul_f32 v[222:223], v[10:11], v[220:221]
	v_add_f32_e32 v18, v2, v17
	v_pk_mov_b32 v[16:17], v[220:221], v[82:83] op_sel:[1,0]
	v_mov_b32_e32 v2, v19
	v_pk_mul_f32 v[84:85], v[10:11], v[16:17]
	v_pk_mul_f32 v[16:17], v[2:3], v[82:83]
	v_add_f32_e32 v19, v222, v223
	v_add_f32_e32 v16, v19, v16
	v_mul_f32_e32 v19, 0xbfb8aa3b, v137
	v_exp_f32_e32 v19, v19
	v_mul_f32_e32 v153, 0xbfb8aa3b, v18
	v_exp_f32_e32 v153, v153
	v_add_f32_e32 v16, v16, v17
	v_add_f32_e32 v19, 1.0, v19
	v_rcp_f32_e32 v19, v19
	v_add_f32_e32 v153, 1.0, v153
	v_rcp_f32_e32 v153, v153
	v_mul_f32_e32 v17, 0xbfb8aa3b, v134
	v_mul_f32_e32 v19, v137, v19
	v_mul_f32_e32 v137, 0xbfb8aa3b, v86
	v_exp_f32_e32 v137, v137
	v_exp_f32_e32 v17, v17
	v_mul_f32_e32 v153, v18, v153
	v_mul_f32_e32 v18, 0xbfb8aa3b, v16
	v_add_f32_e32 v137, 1.0, v137
	v_rcp_f32_e32 v137, v137
	v_exp_f32_e32 v18, v18
	v_add_f32_e32 v17, 1.0, v17
	v_rcp_f32_e32 v17, v17
	v_mul_f32_e32 v86, v86, v137
	v_mul_f32_e32 v137, 0xbfb8aa3b, v87
	v_exp_f32_e32 v137, v137
	v_add_f32_e32 v18, 1.0, v18
	v_rcp_f32_e32 v18, v18
	v_mul_f32_e32 v17, v134, v17
	v_add_f32_e32 v137, 1.0, v137
	v_rcp_f32_e32 v137, v137
	v_mul_f32_e32 v134, v19, v19
	v_fmac_f32_e32 v134, v17, v17
	v_fmac_f32_e32 v134, v86, v86
	v_mul_f32_e32 v87, v87, v137
	v_mul_f32_e32 v137, 0xbfb8aa3b, v152
	v_exp_f32_e32 v137, v137
	v_fmac_f32_e32 v134, v87, v87
	v_pk_mul_f32 v[92:93], v[64:65], v[68:69]
	v_add_f32_e32 v116, v116, v117
	v_add_f32_e32 v137, 1.0, v137
	v_rcp_f32_e32 v137, v137
	v_pk_mul_f32 v[108:109], v[12:13], v[70:71]
	v_add_f32_e32 v94, v94, v95
	v_pk_mul_f32 v[96:97], v[62:63], v[72:73]
	v_mul_f32_e32 v137, v152, v137
	v_mul_f32_e32 v152, 0xbfb8aa3b, v217
	v_exp_f32_e32 v152, v152
	v_fmac_f32_e32 v134, v137, v137
	v_pk_mul_f32 v[114:115], v[14:15], v[74:75]
	v_add_f32_e32 v98, v98, v99
	v_add_f32_e32 v152, 1.0, v152
	v_rcp_f32_e32 v152, v152
	v_pk_mul_f32 v[100:101], v[30:31], v[76:77]
	v_add_f32_e32 v120, v120, v121
	v_pk_mul_f32 v[110:111], v[8:9], v[78:79]
	v_mul_f32_e32 v152, v217, v152
	v_mul_f32_e32 v217, v16, v18
	v_cvt_pk_bf16_f32 v16, v17, v19
	v_cvt_pk_bf16_f32 v17, v86, v87
	v_lshlrev_b32_e32 v87, 16, v136
	v_lshlrev_b32_e32 v86, 16, v135
	v_cvt_pk_bf16_f32 v18, v137, v152
	v_cvt_pk_bf16_f32 v19, v153, v217
	ds_write_b128 v169, v[16:19]
	v_pk_mov_b32 v[16:17], v[68:69], v[86:87] op_sel:[1,0]
	v_fmac_f32_e32 v134, v152, v152
	v_pk_mul_f32 v[68:69], v[64:65], v[16:17]
	v_pk_mul_f32 v[16:17], v[24:25], v[16:17]
	v_pk_mul_f32 v[18:19], v[24:25], v[86:87]
	v_add_f32_e32 v16, v116, v16
	v_add_f32_e32 v16, v16, v17
	v_mul_f32_e32 v17, 0xbfb8aa3b, v16
	v_exp_f32_e32 v17, v17
	v_fmac_f32_e32 v134, v153, v153
	v_fmac_f32_e32 v134, v217, v217
	v_add_f32_e32 v102, v102, v103
	v_add_f32_e32 v17, 1.0, v17
	v_rcp_f32_e32 v17, v17
	v_pk_mul_f32 v[104:105], v[28:29], v[80:81]
	v_pk_mul_f32 v[106:107], v[10:11], v[82:83]
	v_add_f32_e32 v104, v104, v105
	v_mul_f32_e32 v152, v16, v17
	v_add_f32_e32 v16, v92, v93
	v_add_f32_e32 v16, v16, v18
	v_and_b32_e32 v93, 0xffff0000, v136
	v_and_b32_e32 v92, 0xffff0000, v135
	v_add_f32_e32 v137, v16, v19
	v_pk_mov_b32 v[16:17], v[70:71], v[92:93] op_sel:[1,0]
	v_pk_mul_f32 v[18:19], v[4:5], v[92:93]
	v_pk_mul_f32 v[70:71], v[12:13], v[16:17]
	v_pk_mul_f32 v[16:17], v[4:5], v[16:17]
	v_and_b32_e32 v105, 0xffff0000, v127
	v_add_f32_e32 v16, v94, v16
	v_add_f32_e32 v16, v16, v17
	v_mul_f32_e32 v17, 0xbfb8aa3b, v16
	v_exp_f32_e32 v17, v17
	v_add_f32_e32 v84, v84, v85
	v_pk_mul_f32 v[116:117], v[64:65], v[86:87]
	v_add_f32_e32 v17, 1.0, v17
	v_rcp_f32_e32 v17, v17
	v_add_f32_e32 v68, v68, v69
	v_and_b32_e32 v69, 0xffff0000, v129
	v_pk_mul_f32 v[94:95], v[12:13], v[92:93]
	v_mul_f32_e32 v16, v16, v17
	v_add_f32_e32 v17, v108, v109
	v_add_f32_e32 v17, v17, v18
	v_lshlrev_b32_e32 v109, 16, v133
	v_lshlrev_b32_e32 v108, 16, v132
	v_add_f32_e32 v136, v17, v19
	v_pk_mov_b32 v[18:19], v[72:73], v[108:109] op_sel:[1,0]
	v_add_f32_e32 v17, v118, v119
	v_pk_mul_f32 v[72:73], v[62:63], v[18:19]
	v_pk_mul_f32 v[18:19], v[20:21], v[18:19]
	v_mul_f32_e32 v135, v16, v16
	v_add_f32_e32 v17, v17, v18
	v_add_f32_e32 v17, v17, v19
	v_mul_f32_e32 v18, 0xbfb8aa3b, v17
	v_exp_f32_e32 v18, v18
	v_fmac_f32_e32 v135, v152, v152
	v_cvt_pk_bf16_f32 v16, v152, v16
	v_pk_mul_f32 v[152:153], v[20:21], v[108:109]
	v_add_f32_e32 v18, 1.0, v18
	v_rcp_f32_e32 v18, v18
	v_add_f32_e32 v70, v70, v71
	v_pk_mul_f32 v[118:119], v[62:63], v[108:109]
	v_mul_f32_e32 v17, v17, v18
	v_add_f32_e32 v18, v96, v97
	v_add_f32_e32 v18, v18, v152
	v_and_b32_e32 v97, 0xffff0000, v133
	v_and_b32_e32 v96, 0xffff0000, v132
	v_add_f32_e32 v152, v18, v153
	v_pk_mov_b32 v[18:19], v[74:75], v[96:97] op_sel:[1,0]
	v_fmac_f32_e32 v135, v17, v17
	v_pk_mul_f32 v[74:75], v[14:15], v[18:19]
	v_pk_mul_f32 v[18:19], v[6:7], v[18:19]
	v_pk_mul_f32 v[132:133], v[6:7], v[96:97]
	v_add_f32_e32 v18, v98, v18
	v_add_f32_e32 v18, v18, v19
	v_mul_f32_e32 v19, 0xbfb8aa3b, v18
	v_exp_f32_e32 v19, v19
	v_pk_mul_f32 v[98:99], v[14:15], v[96:97]
	v_add_f32_e32 v74, v74, v75
	v_add_f32_e32 v19, 1.0, v19
	v_rcp_f32_e32 v19, v19
	s_nop 0
	v_mul_f32_e32 v18, v18, v19
	v_fmac_f32_e32 v135, v18, v18
	v_cvt_pk_bf16_f32 v17, v17, v18
	v_add_f32_e32 v18, v114, v115
	v_add_f32_e32 v18, v18, v132
	v_lshlrev_b32_e32 v115, 16, v123
	v_lshlrev_b32_e32 v114, 16, v122
	v_add_f32_e32 v153, v18, v133
	v_pk_mov_b32 v[18:19], v[76:77], v[114:115] op_sel:[1,0]
	v_pk_mul_f32 v[132:133], v[22:23], v[114:115]
	v_pk_mul_f32 v[76:77], v[30:31], v[18:19]
	v_pk_mul_f32 v[18:19], v[22:23], v[18:19]
	v_add_f32_e32 v76, v76, v77
	v_add_f32_e32 v18, v120, v18
	v_add_f32_e32 v18, v18, v19
	v_mul_f32_e32 v19, 0xbfb8aa3b, v18
	v_exp_f32_e32 v19, v19
	v_pk_mul_f32 v[120:121], v[30:31], v[114:115]
	v_and_b32_e32 v77, 0xffff0000, v125
	v_add_f32_e32 v19, 1.0, v19
	v_rcp_f32_e32 v19, v19
	s_nop 0
	v_mul_f32_e32 v217, v18, v19
	v_add_f32_e32 v18, v100, v101
	v_add_f32_e32 v18, v18, v132
	v_and_b32_e32 v101, 0xffff0000, v123
	v_and_b32_e32 v100, 0xffff0000, v122
	v_add_f32_e32 v218, v18, v133
	v_pk_mov_b32 v[18:19], v[78:79], v[100:101] op_sel:[1,0]
	v_pk_mul_f32 v[122:123], v[0:1], v[100:101]
	v_pk_mul_f32 v[78:79], v[8:9], v[18:19]
	v_pk_mul_f32 v[18:19], v[0:1], v[18:19]
	v_fmac_f32_e32 v135, v217, v217
	v_add_f32_e32 v18, v102, v18
	v_add_f32_e32 v18, v18, v19
	v_mul_f32_e32 v19, 0xbfb8aa3b, v18
	v_exp_f32_e32 v19, v19
	v_pk_mul_f32 v[102:103], v[8:9], v[100:101]
	v_add_f32_e32 v78, v78, v79
	v_add_f32_e32 v19, 1.0, v19
	v_rcp_f32_e32 v19, v19
	s_nop 0
	v_mul_f32_e32 v18, v18, v19
	v_add_f32_e32 v19, v110, v111
	v_add_f32_e32 v19, v19, v122
	v_lshlrev_b32_e32 v111, 16, v127
	v_lshlrev_b32_e32 v110, 16, v126
	v_fmac_f32_e32 v135, v18, v18
	v_cvt_pk_bf16_f32 v18, v217, v18
	v_add_f32_e32 v217, v19, v123
	v_pk_mov_b32 v[122:123], v[80:81], v[110:111] op_sel:[1,0]
	v_add_f32_e32 v19, v112, v113
	v_pk_mul_f32 v[80:81], v[28:29], v[122:123]
	v_pk_mul_f32 v[122:123], v[26:27], v[122:123]
	v_pk_mul_f32 v[132:133], v[26:27], v[110:111]
	v_add_f32_e32 v19, v19, v122
	v_add_f32_e32 v19, v19, v123
	v_mul_f32_e32 v112, 0xbfb8aa3b, v19
	v_exp_f32_e32 v112, v112
	v_add_f32_e32 v104, v104, v132
	v_add_f32_e32 v132, v104, v133
	v_and_b32_e32 v104, 0xffff0000, v126
	v_add_f32_e32 v112, 1.0, v112
	v_rcp_f32_e32 v112, v112
	v_pk_mul_f32 v[126:127], v[2:3], v[104:105]
	v_pk_mul_f32 v[122:123], v[28:29], v[110:111]
	v_mul_f32_e32 v19, v19, v112
	v_pk_mov_b32 v[112:113], v[82:83], v[104:105] op_sel:[1,0]
	v_fmac_f32_e32 v135, v19, v19
	v_pk_mul_f32 v[82:83], v[10:11], v[112:113]
	v_pk_mul_f32 v[112:113], v[2:3], v[112:113]
	v_add_f32_e32 v82, v82, v83
	v_add_f32_e32 v84, v84, v112
	v_add_f32_e32 v84, v84, v113
	v_mul_f32_e32 v85, 0xbfb8aa3b, v84
	v_exp_f32_e32 v85, v85
	v_mul_f32_e32 v113, 0xbfb8aa3b, v132
	v_exp_f32_e32 v113, v113
	v_add_f32_e32 v85, 1.0, v85
	v_rcp_f32_e32 v85, v85
	v_add_f32_e32 v113, 1.0, v113
	v_rcp_f32_e32 v113, v113
	v_mul_f32_e32 v112, v84, v85
	v_cvt_pk_bf16_f32 v19, v19, v112
	ds_write_b128 v169, v[16:19] offset:272
	v_mul_f32_e32 v18, 0xbfb8aa3b, v136
	v_mul_f32_e32 v17, 0xbfb8aa3b, v137
	v_exp_f32_e32 v18, v18
	v_exp_f32_e32 v17, v17
	v_mul_f32_e32 v19, 0xbfb8aa3b, v152
	v_add_f32_e32 v16, v106, v107
	v_exp_f32_e32 v19, v19
	v_mul_f32_e32 v106, 0xbfb8aa3b, v153
	v_exp_f32_e32 v106, v106
	v_mul_f32_e32 v107, 0xbfb8aa3b, v218
	v_fmac_f32_e32 v135, v112, v112
	v_add_f32_e32 v16, v16, v126
	v_add_f32_e32 v18, 1.0, v18
	v_exp_f32_e32 v107, v107
	v_mul_f32_e32 v112, 0xbfb8aa3b, v217
	v_add_f32_e32 v16, v16, v127
	v_add_f32_e32 v17, 1.0, v17
	v_rcp_f32_e32 v18, v18
	v_exp_f32_e32 v112, v112
	v_rcp_f32_e32 v17, v17
	v_add_f32_e32 v19, 1.0, v19
	v_mul_f32_e32 v126, 0xbfb8aa3b, v16
	v_rcp_f32_e32 v19, v19
	v_add_f32_e32 v106, 1.0, v106
	v_exp_f32_e32 v126, v126
	v_rcp_f32_e32 v106, v106
	v_add_f32_e32 v107, 1.0, v107
	v_mul_f32_e32 v18, v136, v18
	v_rcp_f32_e32 v107, v107
	v_add_f32_e32 v112, 1.0, v112
	v_mul_f32_e32 v17, v137, v17
	v_mul_f32_e32 v136, v18, v18
	v_rcp_f32_e32 v112, v112
	v_fmac_f32_e32 v136, v17, v17
	v_mul_f32_e32 v19, v152, v19
	v_add_f32_e32 v126, 1.0, v126
	v_fmac_f32_e32 v136, v19, v19
	v_mul_f32_e32 v106, v153, v106
	v_rcp_f32_e32 v126, v126
	v_fmac_f32_e32 v136, v106, v106
	v_mul_f32_e32 v107, v218, v107
	v_fmac_f32_e32 v136, v107, v107
	v_mul_f32_e32 v112, v217, v112
	v_fmac_f32_e32 v136, v112, v112
	v_mul_f32_e32 v113, v132, v113
	v_fmac_f32_e32 v136, v113, v113
	v_mul_f32_e32 v126, v16, v126
	v_cvt_pk_bf16_f32 v16, v17, v18
	v_cvt_pk_bf16_f32 v17, v19, v106
	v_cvt_pk_bf16_f32 v18, v107, v112
	v_cvt_pk_bf16_f32 v19, v113, v126
	v_lshlrev_b32_e32 v113, 16, v129
	v_lshlrev_b32_e32 v112, 16, v128
	ds_write_b128 v169, v[16:19] offset:544
	v_pk_mov_b32 v[16:17], v[86:87], v[112:113] op_sel:[1,0]
	v_pk_mul_f32 v[18:19], v[24:25], v[112:113]
	v_pk_mul_f32 v[86:87], v[64:65], v[16:17]
	v_pk_mul_f32 v[16:17], v[24:25], v[16:17]
	v_lshlrev_b32_e32 v107, 16, v131
	v_add_f32_e32 v16, v68, v16
	v_add_f32_e32 v16, v16, v17
	v_mul_f32_e32 v17, 0xbfb8aa3b, v16
	v_exp_f32_e32 v17, v17
	v_and_b32_e32 v68, 0xffff0000, v128
	v_pk_mul_f32 v[84:85], v[10:11], v[104:105]
	v_fmac_f32_e32 v136, v126, v126
	v_add_f32_e32 v17, 1.0, v17
	v_rcp_f32_e32 v17, v17
	v_pk_mul_f32 v[126:127], v[64:65], v[112:113]
	v_mul_f32_e32 v106, v16, v17
	v_add_f32_e32 v16, v116, v117
	v_add_f32_e32 v16, v16, v18
	v_add_f32_e32 v116, v16, v19
	v_pk_mov_b32 v[16:17], v[92:93], v[68:69] op_sel:[1,0]
	v_pk_mul_f32 v[18:19], v[4:5], v[68:69]
	v_pk_mul_f32 v[92:93], v[12:13], v[16:17]
	v_pk_mul_f32 v[16:17], v[4:5], v[16:17]
	s_nop 0
	v_add_f32_e32 v16, v70, v16
	v_add_f32_e32 v16, v16, v17
	v_mul_f32_e32 v17, 0xbfb8aa3b, v16
	v_exp_f32_e32 v17, v17
	v_pk_mul_f32 v[70:71], v[12:13], v[68:69]
	v_add_f32_e32 v17, 1.0, v17
	v_rcp_f32_e32 v17, v17
	s_nop 0
	v_mul_f32_e32 v16, v16, v17
	v_mul_f32_e32 v137, v16, v16
	v_add_f32_e32 v17, v94, v95
	v_fmac_f32_e32 v137, v106, v106
	v_cvt_pk_bf16_f32 v16, v106, v16
	v_add_f32_e32 v17, v17, v18
	v_lshlrev_b32_e32 v106, 16, v130
	v_add_f32_e32 v117, v17, v19
	v_pk_mov_b32 v[18:19], v[108:109], v[106:107] op_sel:[1,0]
	v_add_f32_e32 v17, v72, v73
	v_pk_mul_f32 v[94:95], v[62:63], v[18:19]
	v_pk_mul_f32 v[18:19], v[20:21], v[18:19]
	v_pk_mul_f32 v[108:109], v[20:21], v[106:107]
	v_add_f32_e32 v17, v17, v18
	v_add_f32_e32 v17, v17, v19
	v_mul_f32_e32 v18, 0xbfb8aa3b, v17
	v_exp_f32_e32 v18, v18
	v_and_b32_e32 v73, 0xffff0000, v131
	v_and_b32_e32 v72, 0xffff0000, v130
	v_pk_mul_f32 v[128:129], v[62:63], v[106:107]
	v_add_f32_e32 v18, 1.0, v18
	v_rcp_f32_e32 v18, v18
	s_nop 0
	v_mul_f32_e32 v17, v17, v18
	v_add_f32_e32 v18, v118, v119
	v_add_f32_e32 v18, v18, v108
	v_add_f32_e32 v118, v18, v109
	v_pk_mov_b32 v[18:19], v[96:97], v[72:73] op_sel:[1,0]
	v_fmac_f32_e32 v137, v17, v17
	v_pk_mul_f32 v[96:97], v[14:15], v[18:19]
	v_pk_mul_f32 v[18:19], v[6:7], v[18:19]
	v_pk_mul_f32 v[108:109], v[6:7], v[72:73]
	v_add_f32_e32 v18, v74, v18
	v_add_f32_e32 v18, v18, v19
	v_mul_f32_e32 v19, 0xbfb8aa3b, v18
	v_exp_f32_e32 v19, v19
	v_pk_mul_f32 v[74:75], v[14:15], v[72:73]
	v_add_f32_e32 v19, 1.0, v19
	v_rcp_f32_e32 v19, v19
	s_nop 0
	v_mul_f32_e32 v18, v18, v19
	v_fmac_f32_e32 v137, v18, v18
	v_cvt_pk_bf16_f32 v17, v17, v18
	v_add_f32_e32 v18, v98, v99
	v_add_f32_e32 v18, v18, v108
	v_add_f32_e32 v119, v18, v109
	v_lshlrev_b32_e32 v109, 16, v125
	v_lshlrev_b32_e32 v108, 16, v124
	v_pk_mov_b32 v[18:19], v[114:115], v[108:109] op_sel:[1,0]
	v_pk_mul_f32 v[114:115], v[22:23], v[108:109]
	v_pk_mul_f32 v[98:99], v[30:31], v[18:19]
	v_pk_mul_f32 v[18:19], v[22:23], v[18:19]
	v_lshlrev_b32_e32 v125, 16, v216
	v_add_f32_e32 v18, v76, v18
	v_add_f32_e32 v18, v18, v19
	v_mul_f32_e32 v19, 0xbfb8aa3b, v18
	v_exp_f32_e32 v19, v19
	v_and_b32_e32 v76, 0xffff0000, v124
	v_lshlrev_b32_e32 v124, 16, v191
	v_pk_mul_f32 v[130:131], v[30:31], v[108:109]
	v_add_f32_e32 v19, 1.0, v19
	v_rcp_f32_e32 v19, v19
	s_nop 0
	v_mul_f32_e32 v132, v18, v19
	v_add_f32_e32 v18, v120, v121
	v_add_f32_e32 v18, v18, v114
	v_add_f32_e32 v152, v18, v115
	v_pk_mov_b32 v[18:19], v[100:101], v[76:77] op_sel:[1,0]
	v_pk_mul_f32 v[114:115], v[0:1], v[76:77]
	v_pk_mul_f32 v[100:101], v[8:9], v[18:19]
	v_pk_mul_f32 v[18:19], v[0:1], v[18:19]
	v_fmac_f32_e32 v137, v132, v132
	v_add_f32_e32 v18, v78, v18
	v_add_f32_e32 v18, v18, v19
	v_mul_f32_e32 v19, 0xbfb8aa3b, v18
	v_exp_f32_e32 v19, v19
	v_pk_mul_f32 v[78:79], v[8:9], v[76:77]
	v_add_f32_e32 v19, 1.0, v19
	v_rcp_f32_e32 v19, v19
	s_nop 0
	v_mul_f32_e32 v18, v18, v19
	v_add_f32_e32 v19, v102, v103
	v_add_f32_e32 v19, v19, v114
	v_pk_mov_b32 v[102:103], v[110:111], v[124:125] op_sel:[1,0]
	v_add_f32_e32 v153, v19, v115
	v_pk_mul_f32 v[110:111], v[28:29], v[102:103]
	v_pk_mul_f32 v[102:103], v[26:27], v[102:103]
	v_add_f32_e32 v19, v80, v81
	v_add_f32_e32 v19, v19, v102
	v_add_f32_e32 v19, v19, v103
	v_mul_f32_e32 v80, 0xbfb8aa3b, v19
	v_exp_f32_e32 v80, v80
	v_pk_mul_f32 v[114:115], v[26:27], v[124:125]
	v_and_b32_e32 v81, 0xffff0000, v216
	v_fmac_f32_e32 v137, v18, v18
	v_add_f32_e32 v80, 1.0, v80
	v_rcp_f32_e32 v80, v80
	v_cvt_pk_bf16_f32 v18, v132, v18
	v_pk_mul_f32 v[132:133], v[28:29], v[124:125]
	v_mul_f32_e32 v19, v19, v80
	v_add_f32_e32 v80, v122, v123
	v_add_f32_e32 v80, v80, v114
	v_add_f32_e32 v114, v80, v115
	v_and_b32_e32 v80, 0xffff0000, v191
	v_pk_mov_b32 v[102:103], v[104:105], v[80:81] op_sel:[1,0]
	v_fmac_f32_e32 v137, v19, v19
	v_pk_mul_f32 v[120:121], v[10:11], v[102:103]
	v_pk_mul_f32 v[102:103], v[2:3], v[102:103]
	v_pk_mul_f32 v[104:105], v[2:3], v[80:81]
	v_add_f32_e32 v82, v82, v102
	v_add_f32_e32 v82, v82, v103
	v_mul_f32_e32 v83, 0xbfb8aa3b, v82
	v_exp_f32_e32 v83, v83
	v_lshlrev_b32_e32 v103, 16, v213
	v_pk_mul_f32 v[122:123], v[10:11], v[80:81]
	v_add_f32_e32 v120, v120, v121
	v_add_f32_e32 v83, 1.0, v83
	v_rcp_f32_e32 v83, v83
	s_nop 0
	v_mul_f32_e32 v82, v82, v83
	v_cvt_pk_bf16_f32 v19, v19, v82
	ds_write_b128 v169, v[16:19] offset:816
	v_add_f32_e32 v16, v84, v85
	v_add_f32_e32 v16, v16, v104
	v_mul_f32_e32 v18, 0xbfb8aa3b, v117
	v_add_f32_e32 v16, v16, v105
	v_mul_f32_e32 v17, 0xbfb8aa3b, v116
	v_exp_f32_e32 v18, v18
	v_fmac_f32_e32 v137, v82, v82
	v_exp_f32_e32 v17, v17
	v_mul_f32_e32 v19, 0xbfb8aa3b, v118
	v_mul_f32_e32 v82, 0xbfb8aa3b, v119
	v_mul_f32_e32 v102, 0xbfb8aa3b, v16
	v_exp_f32_e32 v19, v19
	v_exp_f32_e32 v82, v82
	v_mul_f32_e32 v83, 0xbfb8aa3b, v152
	v_mul_f32_e32 v84, 0xbfb8aa3b, v153
	v_mul_f32_e32 v85, 0xbfb8aa3b, v114
	v_exp_f32_e32 v102, v102
	v_exp_f32_e32 v83, v83
	v_exp_f32_e32 v84, v84
	v_exp_f32_e32 v85, v85
	v_add_f32_e32 v18, 1.0, v18
	v_add_f32_e32 v17, 1.0, v17
	v_rcp_f32_e32 v18, v18
	v_rcp_f32_e32 v17, v17
	v_add_f32_e32 v19, 1.0, v19
	v_add_f32_e32 v82, 1.0, v82
	v_add_f32_e32 v102, 1.0, v102
	v_rcp_f32_e32 v19, v19
	v_rcp_f32_e32 v82, v82
	v_add_f32_e32 v83, 1.0, v83
	v_add_f32_e32 v84, 1.0, v84
	v_add_f32_e32 v85, 1.0, v85
	v_rcp_f32_e32 v102, v102
	v_rcp_f32_e32 v83, v83
	v_rcp_f32_e32 v84, v84
	v_rcp_f32_e32 v85, v85
	v_mul_f32_e32 v18, v117, v18
	v_mul_f32_e32 v17, v116, v17
	v_mul_f32_e32 v191, v18, v18
	v_fmac_f32_e32 v191, v17, v17
	v_mul_f32_e32 v19, v118, v19
	v_mul_f32_e32 v82, v119, v82
	v_mul_f32_e32 v102, v16, v102
	v_cvt_pk_bf16_f32 v16, v17, v18
	v_cvt_pk_bf16_f32 v17, v19, v82
	v_lshlrev_b32_e32 v119, 16, v215
	v_lshlrev_b32_e32 v118, 16, v192
	v_fmac_f32_e32 v191, v19, v19
	v_mul_f32_e32 v83, v152, v83
	v_mul_f32_e32 v84, v153, v84
	v_mul_f32_e32 v85, v114, v85
	v_cvt_pk_bf16_f32 v18, v83, v84
	v_cvt_pk_bf16_f32 v19, v85, v102
	ds_write_b128 v169, v[16:19] offset:1088
	v_pk_mov_b32 v[16:17], v[112:113], v[118:119] op_sel:[1,0]
	v_fmac_f32_e32 v191, v82, v82
	v_pk_mul_f32 v[116:117], v[64:65], v[16:17]
	v_pk_mul_f32 v[16:17], v[24:25], v[16:17]
	v_add_f32_e32 v82, v86, v87
	v_add_f32_e32 v16, v82, v16
	v_add_f32_e32 v16, v16, v17
	v_mul_f32_e32 v17, 0xbfb8aa3b, v16
	v_exp_f32_e32 v17, v17
	v_pk_mul_f32 v[18:19], v[24:25], v[118:119]
	v_and_b32_e32 v113, 0xffff0000, v215
	v_and_b32_e32 v112, 0xffff0000, v192
	v_add_f32_e32 v17, 1.0, v17
	v_rcp_f32_e32 v17, v17
	v_fmac_f32_e32 v191, v83, v83
	v_add_f32_e32 v83, v92, v93
	v_lshlrev_b32_e32 v105, 16, v214
	v_mul_f32_e32 v82, v16, v17
	v_add_f32_e32 v16, v126, v127
	v_add_f32_e32 v16, v16, v18
	v_add_f32_e32 v126, v16, v19
	v_pk_mov_b32 v[16:17], v[68:69], v[112:113] op_sel:[1,0]
	v_pk_mul_f32 v[18:19], v[4:5], v[112:113]
	v_pk_mul_f32 v[68:69], v[12:13], v[16:17]
	v_pk_mul_f32 v[16:17], v[4:5], v[16:17]
	v_lshlrev_b32_e32 v104, 16, v212
	v_add_f32_e32 v16, v83, v16
	v_add_f32_e32 v16, v16, v17
	v_mul_f32_e32 v17, 0xbfb8aa3b, v16
	v_exp_f32_e32 v17, v17
	v_and_b32_e32 v87, 0xffff0000, v214
	v_and_b32_e32 v86, 0xffff0000, v212
	v_add_f32_e32 v92, v96, v97
	v_add_f32_e32 v17, 1.0, v17
	v_rcp_f32_e32 v17, v17
	v_fmac_f32_e32 v191, v84, v84
	v_fmac_f32_e32 v191, v85, v85
	v_fmac_f32_e32 v191, v102, v102
	v_mul_f32_e32 v16, v16, v17
	v_add_f32_e32 v17, v70, v71
	v_add_f32_e32 v17, v17, v18
	v_add_f32_e32 v127, v17, v19
	v_pk_mov_b32 v[18:19], v[106:107], v[104:105] op_sel:[1,0]
	v_add_f32_e32 v17, v94, v95
	v_pk_mul_f32 v[70:71], v[62:63], v[18:19]
	v_pk_mul_f32 v[18:19], v[20:21], v[18:19]
	v_mul_f32_e32 v192, v16, v16
	v_add_f32_e32 v17, v17, v18
	v_add_f32_e32 v17, v17, v19
	v_mul_f32_e32 v18, 0xbfb8aa3b, v17
	v_exp_f32_e32 v18, v18
	v_fmac_f32_e32 v192, v82, v82
	v_cvt_pk_bf16_f32 v16, v82, v16
	v_pk_mul_f32 v[82:83], v[20:21], v[104:105]
	v_add_f32_e32 v18, 1.0, v18
	v_rcp_f32_e32 v18, v18
	v_lshlrev_b32_e32 v102, 16, v194
	v_add_f32_e32 v94, v98, v99
	v_and_b32_e32 v95, 0xffff0000, v213
	v_mul_f32_e32 v17, v17, v18
	v_add_f32_e32 v18, v128, v129
	v_add_f32_e32 v18, v18, v82
	v_add_f32_e32 v128, v18, v83
	v_pk_mov_b32 v[18:19], v[72:73], v[86:87] op_sel:[1,0]
	v_fmac_f32_e32 v192, v17, v17
	v_pk_mul_f32 v[72:73], v[14:15], v[18:19]
	v_pk_mul_f32 v[18:19], v[6:7], v[18:19]
	v_pk_mul_f32 v[82:83], v[6:7], v[86:87]
	v_add_f32_e32 v18, v92, v18
	v_add_f32_e32 v18, v18, v19
	v_mul_f32_e32 v19, 0xbfb8aa3b, v18
	v_exp_f32_e32 v19, v19
	v_add_f32_e32 v96, v100, v101
	v_lshlrev_b32_e32 v101, 16, v195
	v_lshlrev_b32_e32 v100, 16, v193
	v_add_f32_e32 v19, 1.0, v19
	v_rcp_f32_e32 v19, v19
	v_pk_mul_f32 v[114:115], v[64:65], v[118:119]
	v_pk_mul_f32 v[84:85], v[12:13], v[112:113]
	v_mul_f32_e32 v18, v18, v19
	v_fmac_f32_e32 v192, v18, v18
	v_cvt_pk_bf16_f32 v17, v17, v18
	v_add_f32_e32 v18, v74, v75
	v_add_f32_e32 v18, v18, v82
	v_add_f32_e32 v129, v18, v83
	v_pk_mov_b32 v[18:19], v[108:109], v[102:103] op_sel:[1,0]
	v_pk_mul_f32 v[82:83], v[22:23], v[102:103]
	v_pk_mul_f32 v[74:75], v[30:31], v[18:19]
	v_pk_mul_f32 v[18:19], v[22:23], v[18:19]
	v_pk_mul_f32 v[106:107], v[62:63], v[104:105]
	v_add_f32_e32 v18, v94, v18
	v_add_f32_e32 v18, v18, v19
	v_mul_f32_e32 v19, 0xbfb8aa3b, v18
	v_exp_f32_e32 v19, v19
	v_and_b32_e32 v94, 0xffff0000, v194
	v_pk_mul_f32 v[92:93], v[14:15], v[86:87]
	v_pk_mul_f32 v[108:109], v[30:31], v[102:103]
	v_add_f32_e32 v19, 1.0, v19
	v_rcp_f32_e32 v19, v19
	s_nop 0
	v_mul_f32_e32 v98, v18, v19
	v_add_f32_e32 v18, v130, v131
	v_add_f32_e32 v18, v18, v82
	v_add_f32_e32 v130, v18, v83
	v_pk_mov_b32 v[18:19], v[76:77], v[94:95] op_sel:[1,0]
	v_pk_mul_f32 v[82:83], v[0:1], v[94:95]
	v_pk_mul_f32 v[76:77], v[8:9], v[18:19]
	v_pk_mul_f32 v[18:19], v[0:1], v[18:19]
	v_fmac_f32_e32 v192, v98, v98
	v_add_f32_e32 v18, v96, v18
	v_add_f32_e32 v18, v18, v19
	v_mul_f32_e32 v19, 0xbfb8aa3b, v18
	v_exp_f32_e32 v19, v19
	v_mul_f32_e32 v121, 0xbfb8aa3b, v130
	v_exp_f32_e32 v121, v121
	v_pk_mul_f32 v[96:97], v[8:9], v[94:95]
	v_add_f32_e32 v19, 1.0, v19
	v_rcp_f32_e32 v19, v19
	v_add_f32_e32 v121, 1.0, v121
	v_rcp_f32_e32 v121, v121
	v_mul_f32_e32 v18, v18, v19
	v_add_f32_e32 v19, v78, v79
	v_add_f32_e32 v19, v19, v82
	v_add_f32_e32 v131, v19, v83
	v_pk_mov_b32 v[82:83], v[124:125], v[100:101] op_sel:[1,0]
	v_add_f32_e32 v19, v110, v111
	v_pk_mul_f32 v[78:79], v[28:29], v[82:83]
	v_pk_mul_f32 v[82:83], v[26:27], v[82:83]
	v_fmac_f32_e32 v192, v18, v18
	v_add_f32_e32 v19, v19, v82
	v_add_f32_e32 v19, v19, v83
	v_mul_f32_e32 v82, 0xbfb8aa3b, v19
	v_exp_f32_e32 v82, v82
	v_cvt_pk_bf16_f32 v18, v98, v18
	v_pk_mul_f32 v[98:99], v[26:27], v[100:101]
	v_mul_f32_e32 v121, v130, v121
	v_add_f32_e32 v82, 1.0, v82
	v_rcp_f32_e32 v82, v82
	v_pk_mul_f32 v[110:111], v[28:29], v[100:101]
	v_mul_f32_e32 v19, v19, v82
	v_add_f32_e32 v82, v132, v133
	v_add_f32_e32 v82, v82, v98
	v_add_f32_e32 v133, v82, v99
	v_and_b32_e32 v99, 0xffff0000, v195
	v_and_b32_e32 v98, 0xffff0000, v193
	v_pk_mov_b32 v[82:83], v[80:81], v[98:99] op_sel:[1,0]
	v_fmac_f32_e32 v192, v19, v19
	v_pk_mul_f32 v[80:81], v[10:11], v[82:83]
	v_pk_mul_f32 v[82:83], v[2:3], v[82:83]
	v_pk_mul_f32 v[124:125], v[2:3], v[98:99]
	v_add_f32_e32 v82, v120, v82
	v_add_f32_e32 v82, v82, v83
	v_mul_f32_e32 v83, 0xbfb8aa3b, v82
	v_exp_f32_e32 v83, v83
	s_nop 0
	v_add_f32_e32 v83, 1.0, v83
	v_rcp_f32_e32 v83, v83
	s_nop 0
	v_mul_f32_e32 v120, v82, v83
	v_cvt_pk_bf16_f32 v19, v19, v120
	ds_write_b128 v169, v[16:19] offset:1360
	v_mul_f32_e32 v18, 0xbfb8aa3b, v127
	v_mul_f32_e32 v17, 0xbfb8aa3b, v126
	v_exp_f32_e32 v18, v18
	v_exp_f32_e32 v17, v17
	v_mul_f32_e32 v19, 0xbfb8aa3b, v128
	v_fmac_f32_e32 v192, v120, v120
	v_exp_f32_e32 v19, v19
	v_mul_f32_e32 v120, 0xbfb8aa3b, v129
	v_add_f32_e32 v16, v122, v123
	v_exp_f32_e32 v120, v120
	v_add_f32_e32 v16, v16, v124
	v_add_f32_e32 v18, 1.0, v18
	v_mul_f32_e32 v122, 0xbfb8aa3b, v131
	v_add_f32_e32 v16, v16, v125
	v_add_f32_e32 v17, 1.0, v17
	v_rcp_f32_e32 v18, v18
	v_exp_f32_e32 v122, v122
	v_mul_f32_e32 v123, 0xbfb8aa3b, v133
	v_rcp_f32_e32 v17, v17
	v_add_f32_e32 v19, 1.0, v19
	v_exp_f32_e32 v123, v123
	v_mul_f32_e32 v124, 0xbfb8aa3b, v16
	v_rcp_f32_e32 v19, v19
	v_add_f32_e32 v120, 1.0, v120
	v_exp_f32_e32 v124, v124
	v_rcp_f32_e32 v120, v120
	v_mul_f32_e32 v18, v127, v18
	v_add_f32_e32 v122, 1.0, v122
	v_mul_f32_e32 v17, v126, v17
	v_mul_f32_e32 v132, v18, v18
	v_rcp_f32_e32 v122, v122
	v_add_f32_e32 v123, 1.0, v123
	v_fmac_f32_e32 v132, v17, v17
	v_mul_f32_e32 v19, v128, v19
	v_rcp_f32_e32 v123, v123
	v_add_f32_e32 v124, 1.0, v124
	v_fmac_f32_e32 v132, v19, v19
	v_mul_f32_e32 v120, v129, v120
	v_rcp_f32_e32 v124, v124
	v_fmac_f32_e32 v132, v120, v120
	v_fmac_f32_e32 v132, v121, v121
	v_mul_f32_e32 v122, v131, v122
	v_fmac_f32_e32 v132, v122, v122
	v_mul_f32_e32 v123, v133, v123
	v_fmac_f32_e32 v132, v123, v123
	v_mul_f32_e32 v124, v16, v124
	v_fmac_f32_e32 v132, v124, v124
	v_pk_mul_f32 v[82:83], v[10:11], v[98:99]
	v_cvt_pk_bf16_f32 v16, v17, v18
	v_cvt_pk_bf16_f32 v17, v19, v120
	v_cvt_pk_bf16_f32 v18, v121, v122
	v_cvt_pk_bf16_f32 v19, v123, v124
	ds_write_b128 v169, v[16:19] offset:1632
	s_mov_b32 s28, 0x130df000
	v_add_co_u32_e32 v120, vcc, 0x130c3000, v66
	s_nop 1
	v_addc_co_u32_e32 v121, vcc, 0, v67, vcc
	global_load_dwordx4 v[126:129], v[120:121], off
	v_add_co_u32_e32 v16, vcc, 0x130be000, v66
	s_nop 1
	v_addc_co_u32_e32 v17, vcc, 0, v67, vcc
	global_load_dwordx4 v[16:19], v[16:17], off offset:3584
	v_add_co_u32_e32 v120, vcc, 0x130c7000, v66
	s_nop 1
	v_addc_co_u32_e32 v121, vcc, 0, v67, vcc
	global_load_dwordx4 v[242:245], v[120:121], off offset:512
	v_add_co_u32_e32 v120, vcc, 0x130cb000, v66
	s_nop 1
	v_addc_co_u32_e32 v121, vcc, 0, v67, vcc
	global_load_dwordx4 v[246:249], v[120:121], off offset:1024
	v_add_co_u32_e32 v120, vcc, 0x130cf000, v66
	s_nop 1
	v_addc_co_u32_e32 v121, vcc, 0, v67, vcc
	global_load_dwordx2 v[130:131], v[120:121], off offset:1536
	global_load_dwordx2 v[152:153], v[120:121], off offset:1544
	v_add_co_u32_e32 v120, vcc, 0x130d3000, v66
	s_nop 1
	v_addc_co_u32_e32 v121, vcc, 0, v67, vcc
	global_load_dwordx2 v[238:239], v[120:121], off offset:2048
	global_load_dword v133, v[120:121], off offset:2056
	global_load_dword v194, v[120:121], off offset:2060
	v_add_f32_e32 v114, v114, v115
	v_add_f32_e32 v116, v116, v117
	v_add_f32_e32 v70, v70, v71
	v_add_f32_e32 v74, v74, v75
	v_add_f32_e32 v78, v78, v79
	s_waitcnt vmcnt(8)
	v_cndmask_b32_e64 v122, v129, 0, s[48:49]
	v_cndmask_b32_e64 v123, v128, 0, s[48:49]
	v_cndmask_b32_e64 v124, v127, 0, s[48:49]
	v_cndmask_b32_e64 v125, v126, 0, s[48:49]
	v_add_co_u32_e32 v120, vcc, 0x130df000, v66
	s_nop 1
	v_addc_co_u32_e32 v121, vcc, 0, v67, vcc
	global_load_dwordx4 v[126:129], v[120:121], off offset:3584
	v_and_b32_e32 v115, 0xffff0000, v125
	s_waitcnt vmcnt(7)
	v_cndmask_b32_e64 v231, v245, 0, s[48:49]
	v_cndmask_b32_e64 v233, v244, 0, s[48:49]
	v_cndmask_b32_e64 v235, v243, 0, s[48:49]
	v_cndmask_b32_e64 v214, v242, 0, s[48:49]
	v_add_co_u32_e32 v120, vcc, 0x130d7000, v66
	s_nop 1
	v_addc_co_u32_e32 v121, vcc, 0, v67, vcc
	global_load_dwordx4 v[242:245], v[120:121], off offset:2560
	s_waitcnt vmcnt(7)
	v_cndmask_b32_e64 v232, v249, 0, s[48:49]
	v_cndmask_b32_e64 v234, v248, 0, s[48:49]
	v_cndmask_b32_e64 v236, v247, 0, s[48:49]
	v_cndmask_b32_e64 v237, v246, 0, s[48:49]
	v_add_co_u32_e32 v120, vcc, 0x130db000, v66
	s_nop 1
	v_addc_co_u32_e32 v121, vcc, 0, v67, vcc
	global_load_dwordx4 v[246:249], v[120:121], off offset:3072
	s_waitcnt vmcnt(6)
	v_cndmask_b32_e64 v223, v153, 0, s[48:49]
	v_cndmask_b32_e64 v225, v152, 0, s[48:49]
	v_cndmask_b32_e64 v227, v131, 0, s[48:49]
	v_cndmask_b32_e64 v229, v130, 0, s[48:49]
	s_waitcnt vmcnt(3)
	v_cndmask_b32_e64 v224, v194, 0, s[48:49]
	v_cndmask_b32_e64 v226, v133, 0, s[48:49]
	v_cndmask_b32_e64 v228, v239, 0, s[48:49]
	v_cndmask_b32_e64 v230, v238, 0, s[48:49]
	s_waitcnt vmcnt(1)
	v_cndmask_b32_e64 v215, v245, 0, s[62:63]
	v_cndmask_b32_e64 v217, v244, 0, s[62:63]
	v_cndmask_b32_e64 v219, v243, 0, s[62:63]
	v_cndmask_b32_e64 v221, v242, 0, s[62:63]
	v_lshlrev_b32_e32 v121, 16, v125
	s_waitcnt vmcnt(0)
	v_cndmask_b32_e64 v216, v249, 0, s[64:65]
	v_cndmask_b32_e64 v218, v248, 0, s[64:65]
	v_cndmask_b32_e64 v220, v247, 0, s[64:65]
	v_cndmask_b32_e64 v222, v246, 0, s[64:65]
	v_cndmask_b32_e64 v16, v16, 0, s[48:49]
	v_lshlrev_b32_e32 v120, 16, v16
	v_pk_mov_b32 v[118:119], v[118:119], v[120:121] op_sel:[1,0]
	v_cndmask_b32_e64 v17, v17, 0, s[48:49]
	v_pk_mul_f32 v[66:67], v[64:65], v[118:119]
	v_pk_mul_f32 v[118:119], v[24:25], v[118:119]
	v_cndmask_b32_e64 v18, v18, 0, s[48:49]
	v_add_f32_e32 v116, v116, v118
	v_add_f32_e32 v116, v116, v119
	v_mul_f32_e32 v117, 0xbfb8aa3b, v116
	v_exp_f32_e32 v117, v117
	v_cndmask_b32_e64 v19, v19, 0, s[48:49]
	v_add_f32_e32 v66, v66, v67
	v_add_f32_e32 v117, 1.0, v117
	v_rcp_f32_e32 v117, v117
	s_waitcnt vmcnt(0)
	v_cndmask_b32_e64 v212, v127, 0, s[66:67]
	v_cndmask_b32_e64 v213, v126, 0, s[66:67]
	v_pk_mul_f32 v[126:127], v[24:25], v[120:121]
	v_cndmask_b32_e64 v195, v128, 0, s[66:67]
	v_add_f32_e32 v114, v114, v126
	v_add_f32_e32 v193, v114, v127
	v_and_b32_e32 v114, 0xffff0000, v16
	v_pk_mov_b32 v[118:119], v[112:113], v[114:115] op_sel:[1,0]
	v_add_f32_e32 v16, v68, v69
	v_pk_mul_f32 v[112:113], v[12:13], v[118:119]
	v_pk_mul_f32 v[118:119], v[4:5], v[118:119]
	v_pk_mul_f32 v[126:127], v[4:5], v[114:115]
	v_add_f32_e32 v16, v16, v118
	v_add_f32_e32 v16, v16, v119
	v_mul_f32_e32 v68, 0xbfb8aa3b, v16
	v_exp_f32_e32 v68, v68
	v_mul_f32_e32 v128, v116, v117
	v_cndmask_b32_e64 v194, v129, 0, s[66:67]
	v_pk_mul_f32 v[116:117], v[64:65], v[120:121]
	v_add_f32_e32 v68, 1.0, v68
	v_rcp_f32_e32 v68, v68
	v_pk_mul_f32 v[118:119], v[12:13], v[114:115]
	v_mul_f32_e32 v16, v16, v68
	v_add_f32_e32 v68, v84, v85
	v_lshlrev_b32_e32 v85, 16, v124
	v_lshlrev_b32_e32 v84, 16, v17
	v_add_f32_e32 v68, v68, v126
	v_pk_mov_b32 v[104:105], v[104:105], v[84:85] op_sel:[1,0]
	v_add_f32_e32 v152, v68, v127
	v_pk_mul_f32 v[68:69], v[62:63], v[104:105]
	v_pk_mul_f32 v[104:105], v[20:21], v[104:105]
	v_mul_f32_e32 v133, v16, v16
	v_add_f32_e32 v70, v70, v104
	v_add_f32_e32 v70, v70, v105
	v_mul_f32_e32 v71, 0xbfb8aa3b, v70
	v_exp_f32_e32 v71, v71
	v_fmac_f32_e32 v133, v128, v128
	v_cvt_pk_bf16_f32 v16, v128, v16
	v_pk_mul_f32 v[128:129], v[20:21], v[84:85]
	v_add_f32_e32 v71, 1.0, v71
	v_rcp_f32_e32 v71, v71
	v_and_b32_e32 v105, 0xffff0000, v124
	v_and_b32_e32 v104, 0xffff0000, v17
	v_pk_mov_b32 v[86:87], v[86:87], v[104:105] op_sel:[1,0]
	v_mul_f32_e32 v125, v70, v71
	v_add_f32_e32 v70, v106, v107
	v_add_f32_e32 v70, v70, v128
	v_add_f32_e32 v153, v70, v129
	v_pk_mul_f32 v[70:71], v[14:15], v[86:87]
	v_pk_mul_f32 v[86:87], v[6:7], v[86:87]
	v_add_f32_e32 v17, v72, v73
	v_add_f32_e32 v17, v17, v86
	v_add_f32_e32 v17, v17, v87
	v_mul_f32_e32 v72, 0xbfb8aa3b, v17
	v_exp_f32_e32 v72, v72
	v_pk_mul_f32 v[106:107], v[6:7], v[104:105]
	v_fmac_f32_e32 v133, v125, v125
	v_pk_mul_f32 v[126:127], v[62:63], v[84:85]
	v_add_f32_e32 v72, 1.0, v72
	v_rcp_f32_e32 v72, v72
	v_add_f32_e32 v70, v70, v71
	v_pk_mul_f32 v[86:87], v[14:15], v[104:105]
	v_mul_f32_e32 v17, v17, v72
	v_add_f32_e32 v72, v92, v93
	v_add_f32_e32 v72, v72, v106
	v_add_f32_e32 v238, v72, v107
	v_lshlrev_b32_e32 v107, 16, v123
	v_lshlrev_b32_e32 v106, 16, v18
	v_pk_mov_b32 v[92:93], v[102:103], v[106:107] op_sel:[1,0]
	v_pk_mul_f32 v[102:103], v[22:23], v[106:107]
	v_pk_mul_f32 v[72:73], v[30:31], v[92:93]
	v_pk_mul_f32 v[92:93], v[22:23], v[92:93]
	v_fmac_f32_e32 v133, v17, v17
	v_add_f32_e32 v74, v74, v92
	v_add_f32_e32 v74, v74, v93
	v_mul_f32_e32 v75, 0xbfb8aa3b, v74
	v_exp_f32_e32 v75, v75
	v_and_b32_e32 v93, 0xffff0000, v123
	v_and_b32_e32 v92, 0xffff0000, v18
	v_pk_mov_b32 v[94:95], v[94:95], v[92:93] op_sel:[1,0]
	v_add_f32_e32 v75, 1.0, v75
	v_rcp_f32_e32 v75, v75
	v_add_f32_e32 v18, v76, v77
	v_cvt_pk_bf16_f32 v17, v125, v17
	v_lshlrev_b32_e32 v125, 16, v122
	v_mul_f32_e32 v124, v74, v75
	v_add_f32_e32 v74, v108, v109
	v_add_f32_e32 v74, v74, v102
	v_add_f32_e32 v108, v74, v103
	v_pk_mul_f32 v[74:75], v[8:9], v[94:95]
	v_pk_mul_f32 v[94:95], v[0:1], v[94:95]
	v_fmac_f32_e32 v133, v124, v124
	v_add_f32_e32 v18, v18, v94
	v_add_f32_e32 v18, v18, v95
	v_mul_f32_e32 v76, 0xbfb8aa3b, v18
	v_exp_f32_e32 v76, v76
	v_pk_mul_f32 v[102:103], v[0:1], v[92:93]
	v_lshlrev_b32_e32 v123, 16, v237
	v_add_f32_e32 v72, v72, v73
	v_add_f32_e32 v76, 1.0, v76
	v_rcp_f32_e32 v76, v76
	v_pk_mul_f32 v[128:129], v[30:31], v[106:107]
	v_add_f32_e32 v74, v74, v75
	v_pk_mul_f32 v[94:95], v[8:9], v[92:93]
	v_mul_f32_e32 v18, v18, v76
	v_fmac_f32_e32 v133, v18, v18
	v_cvt_pk_bf16_f32 v18, v124, v18
	v_add_f32_e32 v76, v96, v97
	v_lshlrev_b32_e32 v124, 16, v19
	v_add_f32_e32 v76, v76, v102
	v_pk_mov_b32 v[96:97], v[100:101], v[124:125] op_sel:[1,0]
	v_add_f32_e32 v102, v76, v103
	v_pk_mul_f32 v[76:77], v[28:29], v[96:97]
	v_pk_mul_f32 v[96:97], v[26:27], v[96:97]
	v_pk_mul_f32 v[100:101], v[26:27], v[124:125]
	v_add_f32_e32 v78, v78, v96
	v_add_f32_e32 v78, v78, v97
	v_mul_f32_e32 v79, 0xbfb8aa3b, v78
	v_exp_f32_e32 v79, v79
	v_and_b32_e32 v97, 0xffff0000, v122
	v_and_b32_e32 v96, 0xffff0000, v19
	v_pk_mov_b32 v[98:99], v[98:99], v[96:97] op_sel:[1,0]
	v_add_f32_e32 v79, 1.0, v79
	v_rcp_f32_e32 v79, v79
	v_add_f32_e32 v19, v80, v81
	v_lshlrev_b32_e32 v122, 16, v214
	v_pk_mul_f32 v[130:131], v[28:29], v[124:125]
	v_mul_f32_e32 v103, v78, v79
	v_add_f32_e32 v78, v110, v111
	v_add_f32_e32 v78, v78, v100
	v_add_f32_e32 v109, v78, v101
	v_pk_mul_f32 v[78:79], v[10:11], v[98:99]
	v_pk_mul_f32 v[98:99], v[2:3], v[98:99]
	v_fmac_f32_e32 v133, v103, v103
	v_add_f32_e32 v19, v19, v98
	v_add_f32_e32 v19, v19, v99
	v_mul_f32_e32 v80, 0xbfb8aa3b, v19
	v_exp_f32_e32 v80, v80
	v_pk_mul_f32 v[100:101], v[2:3], v[96:97]
	v_mul_f32_e32 v98, 0xbfb8aa3b, v102
	v_mul_f32_e32 v99, 0xbfb8aa3b, v109
	v_add_f32_e32 v80, 1.0, v80
	v_rcp_f32_e32 v80, v80
	v_exp_f32_e32 v98, v98
	v_exp_f32_e32 v99, v99
	v_lshlrev_b32_e32 v111, 16, v236
	v_mul_f32_e32 v19, v19, v80
	v_fmac_f32_e32 v133, v19, v19
	v_cvt_pk_bf16_f32 v19, v103, v19
	ds_write_b128 v169, v[16:19] offset:1904
	v_add_f32_e32 v16, v82, v83
	v_mul_f32_e32 v18, 0xbfb8aa3b, v152
	v_add_f32_e32 v16, v16, v100
	v_mul_f32_e32 v17, 0xbfb8aa3b, v193
	v_exp_f32_e32 v18, v18
	v_add_f32_e32 v16, v16, v101
	v_exp_f32_e32 v17, v17
	v_mul_f32_e32 v19, 0xbfb8aa3b, v153
	v_exp_f32_e32 v19, v19
	v_mul_f32_e32 v82, 0xbfb8aa3b, v238
	v_mul_f32_e32 v100, 0xbfb8aa3b, v16
	v_exp_f32_e32 v82, v82
	v_mul_f32_e32 v83, 0xbfb8aa3b, v108
	v_exp_f32_e32 v100, v100
	v_add_f32_e32 v18, 1.0, v18
	v_exp_f32_e32 v83, v83
	v_add_f32_e32 v17, 1.0, v17
	v_rcp_f32_e32 v18, v18
	v_rcp_f32_e32 v17, v17
	v_add_f32_e32 v19, 1.0, v19
	v_rcp_f32_e32 v19, v19
	v_add_f32_e32 v82, 1.0, v82
	v_add_f32_e32 v100, 1.0, v100
	v_rcp_f32_e32 v82, v82
	v_add_f32_e32 v83, 1.0, v83
	v_add_f32_e32 v98, 1.0, v98
	v_add_f32_e32 v99, 1.0, v99
	v_rcp_f32_e32 v100, v100
	v_mul_f32_e32 v18, v152, v18
	v_rcp_f32_e32 v83, v83
	v_rcp_f32_e32 v98, v98
	v_rcp_f32_e32 v99, v99
	v_mul_f32_e32 v17, v193, v17
	v_mul_f32_e32 v193, v18, v18
	v_fmac_f32_e32 v193, v17, v17
	v_mul_f32_e32 v19, v153, v19
	v_fmac_f32_e32 v193, v19, v19
	v_mul_f32_e32 v82, v238, v82
	v_mul_f32_e32 v100, v16, v100
	v_cvt_pk_bf16_f32 v16, v17, v18
	v_cvt_pk_bf16_f32 v17, v19, v82
	v_fmac_f32_e32 v193, v82, v82
	v_mul_f32_e32 v83, v108, v83
	v_mul_f32_e32 v98, v102, v98
	v_mul_f32_e32 v99, v109, v99
	v_cvt_pk_bf16_f32 v18, v83, v98
	v_cvt_pk_bf16_f32 v19, v99, v100
	ds_write_b128 v169, v[16:19] offset:2176
	v_pk_mov_b32 v[16:17], v[120:121], v[122:123] op_sel:[1,0]
	v_fmac_f32_e32 v193, v83, v83
	v_pk_mul_f32 v[82:83], v[64:65], v[16:17]
	v_pk_mul_f32 v[16:17], v[24:25], v[16:17]
	v_fmac_f32_e32 v193, v98, v98
	v_add_f32_e32 v16, v66, v16
	v_add_f32_e32 v16, v16, v17
	v_mul_f32_e32 v17, 0xbfb8aa3b, v16
	v_exp_f32_e32 v17, v17
	v_pk_mul_f32 v[18:19], v[24:25], v[122:123]
	v_fmac_f32_e32 v193, v99, v99
	v_and_b32_e32 v99, 0xffff0000, v237
	v_add_f32_e32 v17, 1.0, v17
	v_rcp_f32_e32 v17, v17
	v_and_b32_e32 v98, 0xffff0000, v214
	v_fmac_f32_e32 v193, v100, v100
	v_add_f32_e32 v100, v112, v113
	v_mul_f32_e32 v102, v16, v17
	v_add_f32_e32 v16, v116, v117
	v_add_f32_e32 v16, v16, v18
	v_add_f32_e32 v238, v16, v19
	v_pk_mov_b32 v[16:17], v[114:115], v[98:99] op_sel:[1,0]
	v_pk_mul_f32 v[18:19], v[4:5], v[98:99]
	v_pk_mul_f32 v[66:67], v[12:13], v[16:17]
	v_pk_mul_f32 v[16:17], v[4:5], v[16:17]
	v_lshlrev_b32_e32 v110, 16, v235
	v_add_f32_e32 v16, v100, v16
	v_add_f32_e32 v16, v16, v17
	v_mul_f32_e32 v17, 0xbfb8aa3b, v16
	v_exp_f32_e32 v17, v17
	v_pk_mul_f32 v[80:81], v[10:11], v[96:97]
	v_add_f32_e32 v78, v78, v79
	v_add_f32_e32 v17, 1.0, v17
	v_rcp_f32_e32 v17, v17
	v_add_f32_e32 v82, v82, v83
	v_pk_mul_f32 v[120:121], v[64:65], v[122:123]
	v_add_f32_e32 v66, v66, v67
	v_mul_f32_e32 v16, v16, v17
	v_add_f32_e32 v17, v118, v119
	v_add_f32_e32 v17, v17, v18
	v_add_f32_e32 v152, v17, v19
	v_pk_mov_b32 v[18:19], v[84:85], v[110:111] op_sel:[1,0]
	v_add_f32_e32 v17, v68, v69
	v_pk_mul_f32 v[84:85], v[62:63], v[18:19]
	v_pk_mul_f32 v[18:19], v[20:21], v[18:19]
	v_mul_f32_e32 v214, v16, v16
	v_add_f32_e32 v17, v17, v18
	v_add_f32_e32 v17, v17, v19
	v_mul_f32_e32 v18, 0xbfb8aa3b, v17
	v_exp_f32_e32 v18, v18
	v_fmac_f32_e32 v214, v102, v102
	v_cvt_pk_bf16_f32 v16, v102, v16
	v_pk_mul_f32 v[102:103], v[20:21], v[110:111]
	v_add_f32_e32 v18, 1.0, v18
	v_rcp_f32_e32 v18, v18
	v_pk_mul_f32 v[100:101], v[12:13], v[98:99]
	v_pk_mul_f32 v[112:113], v[62:63], v[110:111]
	v_mul_f32_e32 v17, v17, v18
	v_add_f32_e32 v18, v126, v127
	v_add_f32_e32 v18, v18, v102
	v_add_f32_e32 v127, v18, v103
	v_and_b32_e32 v103, 0xffff0000, v236
	v_and_b32_e32 v102, 0xffff0000, v235
	v_pk_mov_b32 v[18:19], v[104:105], v[102:103] op_sel:[1,0]
	v_fmac_f32_e32 v214, v17, v17
	v_pk_mul_f32 v[68:69], v[14:15], v[18:19]
	v_pk_mul_f32 v[18:19], v[6:7], v[18:19]
	v_pk_mul_f32 v[108:109], v[6:7], v[102:103]
	v_add_f32_e32 v18, v70, v18
	v_add_f32_e32 v18, v18, v19
	v_mul_f32_e32 v19, 0xbfb8aa3b, v18
	v_exp_f32_e32 v19, v19
	v_add_f32_e32 v68, v68, v69
	v_pk_mul_f32 v[104:105], v[14:15], v[102:103]
	v_add_f32_e32 v19, 1.0, v19
	v_rcp_f32_e32 v19, v19
	s_nop 0
	v_mul_f32_e32 v18, v18, v19
	v_fmac_f32_e32 v214, v18, v18
	v_cvt_pk_bf16_f32 v17, v17, v18
	v_add_f32_e32 v18, v86, v87
	v_add_f32_e32 v18, v18, v108
	v_add_f32_e32 v153, v18, v109
	v_lshlrev_b32_e32 v109, 16, v234
	v_lshlrev_b32_e32 v108, 16, v233
	v_pk_mov_b32 v[18:19], v[106:107], v[108:109] op_sel:[1,0]
	v_pk_mul_f32 v[86:87], v[22:23], v[108:109]
	v_pk_mul_f32 v[70:71], v[30:31], v[18:19]
	v_pk_mul_f32 v[18:19], v[22:23], v[18:19]
	v_add_f32_e32 v70, v70, v71
	v_add_f32_e32 v18, v72, v18
	v_add_f32_e32 v18, v18, v19
	v_mul_f32_e32 v19, 0xbfb8aa3b, v18
	v_exp_f32_e32 v19, v19
	v_pk_mul_f32 v[114:115], v[30:31], v[108:109]
	v_add_f32_e32 v19, 1.0, v19
	v_rcp_f32_e32 v19, v19
	s_nop 0
	v_mul_f32_e32 v116, v18, v19
	v_add_f32_e32 v18, v128, v129
	v_add_f32_e32 v18, v18, v86
	v_add_f32_e32 v128, v18, v87
	v_and_b32_e32 v87, 0xffff0000, v234
	v_and_b32_e32 v86, 0xffff0000, v233
	v_pk_mov_b32 v[18:19], v[92:93], v[86:87] op_sel:[1,0]
	v_pk_mul_f32 v[106:107], v[0:1], v[86:87]
	v_pk_mul_f32 v[72:73], v[8:9], v[18:19]
	v_pk_mul_f32 v[18:19], v[0:1], v[18:19]
	v_fmac_f32_e32 v214, v116, v116
	v_add_f32_e32 v18, v74, v18
	v_add_f32_e32 v18, v18, v19
	v_mul_f32_e32 v19, 0xbfb8aa3b, v18
	v_exp_f32_e32 v19, v19
	v_add_f32_e32 v72, v72, v73
	v_pk_mul_f32 v[92:93], v[8:9], v[86:87]
	v_add_f32_e32 v19, 1.0, v19
	v_rcp_f32_e32 v19, v19
	s_nop 0
	v_mul_f32_e32 v18, v18, v19
	v_add_f32_e32 v19, v94, v95
	v_add_f32_e32 v19, v19, v106
	v_add_f32_e32 v129, v19, v107
	v_lshlrev_b32_e32 v107, 16, v232
	v_lshlrev_b32_e32 v106, 16, v231
	v_pk_mov_b32 v[94:95], v[124:125], v[106:107] op_sel:[1,0]
	v_add_f32_e32 v19, v76, v77
	v_pk_mul_f32 v[74:75], v[28:29], v[94:95]
	v_pk_mul_f32 v[94:95], v[26:27], v[94:95]
	v_pk_mul_f32 v[118:119], v[26:27], v[106:107]
	v_add_f32_e32 v19, v19, v94
	v_add_f32_e32 v19, v19, v95
	v_mul_f32_e32 v76, 0xbfb8aa3b, v19
	v_exp_f32_e32 v76, v76
	v_and_b32_e32 v95, 0xffff0000, v232
	v_and_b32_e32 v94, 0xffff0000, v231
	v_pk_mov_b32 v[96:97], v[96:97], v[94:95] op_sel:[1,0]
	v_add_f32_e32 v76, 1.0, v76
	v_rcp_f32_e32 v76, v76
	v_fmac_f32_e32 v214, v18, v18
	v_cvt_pk_bf16_f32 v18, v116, v18
	v_pk_mul_f32 v[116:117], v[28:29], v[106:107]
	v_mul_f32_e32 v19, v19, v76
	v_add_f32_e32 v76, v130, v131
	v_add_f32_e32 v76, v76, v118
	v_add_f32_e32 v124, v76, v119
	v_pk_mul_f32 v[76:77], v[10:11], v[96:97]
	v_pk_mul_f32 v[96:97], v[2:3], v[96:97]
	v_fmac_f32_e32 v214, v19, v19
	v_add_f32_e32 v78, v78, v96
	v_add_f32_e32 v78, v78, v97
	v_mul_f32_e32 v79, 0xbfb8aa3b, v78
	v_exp_f32_e32 v79, v79
	v_pk_mul_f32 v[118:119], v[2:3], v[94:95]
	v_mul_f32_e32 v97, 0xbfb8aa3b, v124
	v_exp_f32_e32 v97, v97
	v_add_f32_e32 v79, 1.0, v79
	v_rcp_f32_e32 v79, v79
	v_add_f32_e32 v76, v76, v77
	v_add_f32_e32 v97, 1.0, v97
	v_rcp_f32_e32 v97, v97
	v_mul_f32_e32 v96, v78, v79
	v_cvt_pk_bf16_f32 v19, v19, v96
	ds_write_b128 v169, v[16:19] offset:2448
	v_mul_f32_e32 v18, 0xbfb8aa3b, v152
	v_mul_f32_e32 v17, 0xbfb8aa3b, v238
	v_exp_f32_e32 v18, v18
	v_exp_f32_e32 v17, v17
	v_mul_f32_e32 v19, 0xbfb8aa3b, v127
	v_add_f32_e32 v16, v80, v81
	v_exp_f32_e32 v19, v19
	v_mul_f32_e32 v80, 0xbfb8aa3b, v153
	v_exp_f32_e32 v80, v80
	v_mul_f32_e32 v81, 0xbfb8aa3b, v128
	v_fmac_f32_e32 v214, v96, v96
	v_add_f32_e32 v16, v16, v118
	v_add_f32_e32 v18, 1.0, v18
	v_exp_f32_e32 v81, v81
	v_mul_f32_e32 v96, 0xbfb8aa3b, v129
	v_add_f32_e32 v16, v16, v119
	v_add_f32_e32 v17, 1.0, v17
	v_rcp_f32_e32 v18, v18
	v_exp_f32_e32 v96, v96
	v_rcp_f32_e32 v17, v17
	v_add_f32_e32 v19, 1.0, v19
	v_mul_f32_e32 v118, 0xbfb8aa3b, v16
	v_rcp_f32_e32 v19, v19
	v_add_f32_e32 v80, 1.0, v80
	v_exp_f32_e32 v118, v118
	v_rcp_f32_e32 v80, v80
	v_add_f32_e32 v81, 1.0, v81
	v_mul_f32_e32 v18, v152, v18
	v_rcp_f32_e32 v81, v81
	v_add_f32_e32 v96, 1.0, v96
	v_mul_f32_e32 v17, v238, v17
	v_mul_f32_e32 v126, v18, v18
	v_rcp_f32_e32 v96, v96
	v_fmac_f32_e32 v126, v17, v17
	v_mul_f32_e32 v19, v127, v19
	v_add_f32_e32 v118, 1.0, v118
	v_fmac_f32_e32 v126, v19, v19
	v_mul_f32_e32 v80, v153, v80
	v_rcp_f32_e32 v118, v118
	v_fmac_f32_e32 v126, v80, v80
	v_mul_f32_e32 v81, v128, v81
	v_fmac_f32_e32 v126, v81, v81
	v_mul_f32_e32 v96, v129, v96
	v_fmac_f32_e32 v126, v96, v96
	v_mul_f32_e32 v97, v124, v97
	v_fmac_f32_e32 v126, v97, v97
	v_mul_f32_e32 v118, v16, v118
	v_cvt_pk_bf16_f32 v16, v17, v18
	v_cvt_pk_bf16_f32 v17, v19, v80
	v_cvt_pk_bf16_f32 v18, v81, v96
	v_cvt_pk_bf16_f32 v19, v97, v118
	v_lshlrev_b32_e32 v97, 16, v230
	v_lshlrev_b32_e32 v96, 16, v229
	ds_write_b128 v169, v[16:19] offset:2720
	v_pk_mov_b32 v[16:17], v[122:123], v[96:97] op_sel:[1,0]
	v_pk_mul_f32 v[18:19], v[24:25], v[96:97]
	v_pk_mul_f32 v[80:81], v[64:65], v[16:17]
	v_pk_mul_f32 v[16:17], v[24:25], v[16:17]
	v_fmac_f32_e32 v126, v118, v118
	v_add_f32_e32 v16, v82, v16
	v_add_f32_e32 v16, v16, v17
	v_mul_f32_e32 v17, 0xbfb8aa3b, v16
	v_exp_f32_e32 v17, v17
	v_and_b32_e32 v119, 0xffff0000, v230
	v_and_b32_e32 v118, 0xffff0000, v229
	v_pk_mul_f32 v[78:79], v[10:11], v[94:95]
	v_add_f32_e32 v17, 1.0, v17
	v_rcp_f32_e32 v17, v17
	v_pk_mul_f32 v[122:123], v[64:65], v[96:97]
	v_mul_f32_e32 v124, v16, v17
	v_add_f32_e32 v16, v120, v121
	v_add_f32_e32 v16, v16, v18
	v_add_f32_e32 v128, v16, v19
	v_pk_mov_b32 v[16:17], v[98:99], v[118:119] op_sel:[1,0]
	v_pk_mul_f32 v[18:19], v[4:5], v[118:119]
	v_pk_mul_f32 v[82:83], v[12:13], v[16:17]
	v_pk_mul_f32 v[16:17], v[4:5], v[16:17]
	v_lshlrev_b32_e32 v99, 16, v228
	v_add_f32_e32 v16, v66, v16
	v_add_f32_e32 v16, v16, v17
	v_mul_f32_e32 v17, 0xbfb8aa3b, v16
	v_exp_f32_e32 v17, v17
	v_lshlrev_b32_e32 v98, 16, v227
	v_pk_mul_f32 v[120:121], v[12:13], v[118:119]
	v_add_f32_e32 v17, 1.0, v17
	v_rcp_f32_e32 v17, v17
	s_nop 0
	v_mul_f32_e32 v16, v16, v17
	v_add_f32_e32 v17, v100, v101
	v_add_f32_e32 v17, v17, v18
	v_add_f32_e32 v129, v17, v19
	v_pk_mov_b32 v[18:19], v[110:111], v[98:99] op_sel:[1,0]
	v_add_f32_e32 v17, v84, v85
	v_pk_mul_f32 v[66:67], v[62:63], v[18:19]
	v_pk_mul_f32 v[18:19], v[20:21], v[18:19]
	v_pk_mul_f32 v[100:101], v[20:21], v[98:99]
	v_add_f32_e32 v17, v17, v18
	v_add_f32_e32 v17, v17, v19
	v_mul_f32_e32 v18, 0xbfb8aa3b, v17
	v_exp_f32_e32 v18, v18
	v_mul_f32_e32 v127, v16, v16
	v_fmac_f32_e32 v127, v124, v124
	v_cvt_pk_bf16_f32 v16, v124, v16
	v_add_f32_e32 v18, 1.0, v18
	v_rcp_f32_e32 v18, v18
	v_pk_mul_f32 v[124:125], v[62:63], v[98:99]
	v_mul_f32_e32 v17, v17, v18
	v_add_f32_e32 v18, v112, v113
	v_add_f32_e32 v18, v18, v100
	v_add_f32_e32 v130, v18, v101
	v_and_b32_e32 v101, 0xffff0000, v228
	v_and_b32_e32 v100, 0xffff0000, v227
	v_pk_mov_b32 v[18:19], v[102:103], v[100:101] op_sel:[1,0]
	v_fmac_f32_e32 v127, v17, v17
	v_pk_mul_f32 v[84:85], v[14:15], v[18:19]
	v_pk_mul_f32 v[18:19], v[6:7], v[18:19]
	v_pk_mul_f32 v[102:103], v[6:7], v[100:101]
	v_add_f32_e32 v18, v68, v18
	v_add_f32_e32 v18, v18, v19
	v_mul_f32_e32 v19, 0xbfb8aa3b, v18
	v_exp_f32_e32 v19, v19
	v_pk_mul_f32 v[110:111], v[14:15], v[100:101]
	v_add_f32_e32 v19, 1.0, v19
	v_rcp_f32_e32 v19, v19
	s_nop 0
	v_mul_f32_e32 v18, v18, v19
	v_fmac_f32_e32 v127, v18, v18
	v_cvt_pk_bf16_f32 v17, v17, v18
	v_add_f32_e32 v18, v104, v105
	v_add_f32_e32 v18, v18, v102
	v_add_f32_e32 v131, v18, v103
	v_lshlrev_b32_e32 v103, 16, v226
	v_lshlrev_b32_e32 v102, 16, v225
	v_pk_mov_b32 v[18:19], v[108:109], v[102:103] op_sel:[1,0]
	v_pk_mul_f32 v[104:105], v[22:23], v[102:103]
	v_pk_mul_f32 v[68:69], v[30:31], v[18:19]
	v_pk_mul_f32 v[18:19], v[22:23], v[18:19]
	v_pk_mul_f32 v[112:113], v[30:31], v[102:103]
	v_add_f32_e32 v18, v70, v18
	v_add_f32_e32 v18, v18, v19
	v_mul_f32_e32 v19, 0xbfb8aa3b, v18
	v_exp_f32_e32 v19, v19
	v_add_f32_e32 v68, v68, v69
	v_and_b32_e32 v69, 0xffff0000, v218
	v_add_f32_e32 v19, 1.0, v19
	v_rcp_f32_e32 v19, v19
	s_nop 0
	v_mul_f32_e32 v152, v18, v19
	v_add_f32_e32 v18, v114, v115
	v_add_f32_e32 v18, v18, v104
	v_add_f32_e32 v153, v18, v105
	v_and_b32_e32 v105, 0xffff0000, v226
	v_and_b32_e32 v104, 0xffff0000, v225
	v_pk_mov_b32 v[18:19], v[86:87], v[104:105] op_sel:[1,0]
	v_pk_mul_f32 v[86:87], v[0:1], v[104:105]
	v_pk_mul_f32 v[70:71], v[8:9], v[18:19]
	v_pk_mul_f32 v[18:19], v[0:1], v[18:19]
	v_fmac_f32_e32 v127, v152, v152
	v_add_f32_e32 v18, v72, v18
	v_add_f32_e32 v18, v18, v19
	v_mul_f32_e32 v19, 0xbfb8aa3b, v18
	v_exp_f32_e32 v19, v19
	v_pk_mul_f32 v[108:109], v[8:9], v[104:105]
	v_add_f32_e32 v19, 1.0, v19
	v_rcp_f32_e32 v19, v19
	s_nop 0
	v_mul_f32_e32 v18, v18, v19
	v_add_f32_e32 v19, v92, v93
	v_add_f32_e32 v19, v19, v86
	v_fmac_f32_e32 v127, v18, v18
	v_cvt_pk_bf16_f32 v18, v152, v18
	v_add_f32_e32 v152, v19, v87
	v_lshlrev_b32_e32 v87, 16, v224
	v_lshlrev_b32_e32 v86, 16, v223
	v_pk_mov_b32 v[92:93], v[106:107], v[86:87] op_sel:[1,0]
	v_add_f32_e32 v19, v74, v75
	v_pk_mul_f32 v[72:73], v[28:29], v[92:93]
	v_pk_mul_f32 v[92:93], v[26:27], v[92:93]
	v_pk_mul_f32 v[114:115], v[26:27], v[86:87]
	v_add_f32_e32 v19, v19, v92
	v_add_f32_e32 v19, v19, v93
	v_mul_f32_e32 v74, 0xbfb8aa3b, v19
	v_exp_f32_e32 v74, v74
	v_and_b32_e32 v93, 0xffff0000, v224
	v_and_b32_e32 v92, 0xffff0000, v223
	v_pk_mov_b32 v[94:95], v[94:95], v[92:93] op_sel:[1,0]
	v_add_f32_e32 v74, 1.0, v74
	v_rcp_f32_e32 v74, v74
	v_pk_mul_f32 v[106:107], v[28:29], v[86:87]
	v_mul_f32_e32 v19, v19, v74
	v_add_f32_e32 v74, v116, v117
	v_add_f32_e32 v74, v74, v114
	v_add_f32_e32 v116, v74, v115
	v_pk_mul_f32 v[74:75], v[10:11], v[94:95]
	v_pk_mul_f32 v[94:95], v[2:3], v[94:95]
	v_fmac_f32_e32 v127, v19, v19
	v_add_f32_e32 v76, v76, v94
	v_add_f32_e32 v76, v76, v95
	v_mul_f32_e32 v77, 0xbfb8aa3b, v76
	v_exp_f32_e32 v77, v77
	v_pk_mul_f32 v[114:115], v[2:3], v[92:93]
	v_mul_f32_e32 v95, 0xbfb8aa3b, v152
	v_exp_f32_e32 v95, v95
	v_add_f32_e32 v77, 1.0, v77
	v_rcp_f32_e32 v77, v77
	v_add_f32_e32 v95, 1.0, v95
	v_rcp_f32_e32 v95, v95
	v_mul_f32_e32 v94, v76, v77
	v_cvt_pk_bf16_f32 v19, v19, v94
	ds_write_b128 v169, v[16:19] offset:2992
	v_add_f32_e32 v16, v78, v79
	v_mul_f32_e32 v18, 0xbfb8aa3b, v129
	v_add_f32_e32 v16, v16, v114
	v_mul_f32_e32 v17, 0xbfb8aa3b, v128
	v_exp_f32_e32 v18, v18
	v_add_f32_e32 v16, v16, v115
	v_exp_f32_e32 v17, v17
	v_mul_f32_e32 v19, 0xbfb8aa3b, v130
	v_exp_f32_e32 v19, v19
	v_mul_f32_e32 v78, 0xbfb8aa3b, v131
	v_mul_f32_e32 v115, 0xbfb8aa3b, v16
	v_exp_f32_e32 v78, v78
	v_mul_f32_e32 v79, 0xbfb8aa3b, v153
	v_mul_f32_e32 v114, 0xbfb8aa3b, v116
	v_exp_f32_e32 v115, v115
	v_add_f32_e32 v18, 1.0, v18
	v_exp_f32_e32 v79, v79
	v_exp_f32_e32 v114, v114
	v_add_f32_e32 v17, 1.0, v17
	v_rcp_f32_e32 v18, v18
	v_rcp_f32_e32 v17, v17
	v_add_f32_e32 v19, 1.0, v19
	v_rcp_f32_e32 v19, v19
	v_add_f32_e32 v78, 1.0, v78
	v_add_f32_e32 v115, 1.0, v115
	v_rcp_f32_e32 v78, v78
	v_add_f32_e32 v79, 1.0, v79
	v_add_f32_e32 v114, 1.0, v114
	v_rcp_f32_e32 v115, v115
	v_mul_f32_e32 v18, v129, v18
	v_rcp_f32_e32 v79, v79
	v_rcp_f32_e32 v114, v114
	v_fmac_f32_e32 v127, v94, v94
	v_mul_f32_e32 v17, v128, v17
	v_mul_f32_e32 v94, v18, v18
	v_fmac_f32_e32 v94, v17, v17
	v_mul_f32_e32 v19, v130, v19
	v_fmac_f32_e32 v94, v19, v19
	v_mul_f32_e32 v78, v131, v78
	v_mul_f32_e32 v115, v16, v115
	v_cvt_pk_bf16_f32 v16, v17, v18
	v_cvt_pk_bf16_f32 v17, v19, v78
	v_fmac_f32_e32 v94, v78, v78
	v_mul_f32_e32 v79, v153, v79
	v_mul_f32_e32 v95, v152, v95
	v_mul_f32_e32 v114, v116, v114
	v_cvt_pk_bf16_f32 v18, v79, v95
	v_cvt_pk_bf16_f32 v19, v114, v115
	ds_write_b128 v169, v[16:19] offset:3264
	v_lshlrev_b32_e32 v16, 16, v221
	v_lshlrev_b32_e32 v17, 16, v222
	v_fmac_f32_e32 v94, v79, v79
	v_pk_mov_b32 v[78:79], v[96:97], v[16:17] op_sel:[1,0]
	v_fmac_f32_e32 v94, v95, v95
	v_pk_mul_f32 v[18:19], v[64:65], v[78:79]
	v_pk_mul_f32 v[64:65], v[24:25], v[16:17]
	v_pk_mul_f32 v[78:79], v[24:25], v[78:79]
	v_add_f32_e32 v16, v80, v81
	v_add_f32_e32 v16, v16, v78
	v_add_f32_e32 v16, v16, v79
	v_mul_f32_e32 v78, 0xbfb8aa3b, v16
	v_exp_f32_e32 v78, v78
	v_fmac_f32_e32 v94, v114, v114
	v_pk_mul_f32 v[76:77], v[10:11], v[92:93]
	v_fmac_f32_e32 v94, v115, v115
	v_add_f32_e32 v78, 1.0, v78
	v_rcp_f32_e32 v78, v78
	s_nop 0
	v_mul_f32_e32 v114, v16, v78
	v_add_f32_e32 v16, v122, v123
	v_add_f32_e32 v16, v16, v64
	v_add_f32_e32 v95, v16, v65
	v_and_b32_e32 v65, 0xffff0000, v222
	v_and_b32_e32 v64, 0xffff0000, v221
	v_pk_mov_b32 v[80:81], v[118:119], v[64:65] op_sel:[1,0]
	v_add_f32_e32 v16, v82, v83
	v_pk_mul_f32 v[78:79], v[12:13], v[80:81]
	v_pk_mul_f32 v[12:13], v[4:5], v[80:81]
	v_pk_mul_f32 v[96:97], v[4:5], v[64:65]
	v_add_f32_e32 v12, v16, v12
	v_add_f32_e32 v12, v12, v13
	v_mul_f32_e32 v13, 0xbfb8aa3b, v12
	v_exp_f32_e32 v13, v13
	v_lshlrev_b32_e32 v80, 16, v219
	v_lshlrev_b32_e32 v81, 16, v220
	v_pk_mov_b32 v[82:83], v[98:99], v[80:81] op_sel:[1,0]
	v_add_f32_e32 v13, 1.0, v13
	v_rcp_f32_e32 v13, v13
	v_pk_mul_f32 v[62:63], v[62:63], v[82:83]
	v_pk_mul_f32 v[82:83], v[20:21], v[82:83]
	v_lshlrev_b32_e32 v99, 16, v194
	v_mul_f32_e32 v12, v12, v13
	v_add_f32_e32 v13, v120, v121
	v_add_f32_e32 v13, v13, v96
	v_add_f32_e32 v64, v13, v97
	v_add_f32_e32 v13, v66, v67
	v_add_f32_e32 v13, v13, v82
	v_add_f32_e32 v13, v13, v83
	v_mul_f32_e32 v66, 0xbfb8aa3b, v13
	v_exp_f32_e32 v66, v66
	v_pk_mul_f32 v[96:97], v[20:21], v[80:81]
	v_and_b32_e32 v67, 0xffff0000, v220
	v_mul_f32_e32 v16, v12, v12
	v_add_f32_e32 v66, 1.0, v66
	v_rcp_f32_e32 v66, v66
	v_fmac_f32_e32 v16, v114, v114
	v_cvt_pk_bf16_f32 v12, v114, v12
	v_mul_f32_e32 v13, v13, v66
	v_add_f32_e32 v66, v124, v125
	v_add_f32_e32 v66, v66, v96
	v_add_f32_e32 v80, v66, v97
	v_and_b32_e32 v66, 0xffff0000, v219
	v_pk_mov_b32 v[96:97], v[100:101], v[66:67] op_sel:[1,0]
	v_fmac_f32_e32 v16, v13, v13
	v_pk_mul_f32 v[82:83], v[14:15], v[96:97]
	v_pk_mul_f32 v[14:15], v[6:7], v[66:67]
	v_pk_mul_f32 v[96:97], v[6:7], v[96:97]
	v_add_f32_e32 v66, v84, v85
	v_add_f32_e32 v66, v66, v96
	v_add_f32_e32 v66, v66, v97
	v_mul_f32_e32 v84, 0xbfb8aa3b, v66
	v_exp_f32_e32 v84, v84
	v_lshlrev_b32_e32 v85, 16, v218
	v_and_b32_e32 v101, 0xffff0000, v194
	v_add_f32_e32 v84, 1.0, v84
	v_rcp_f32_e32 v84, v84
	s_nop 0
	v_mul_f32_e32 v66, v66, v84
	v_fmac_f32_e32 v16, v66, v66
	v_cvt_pk_bf16_f32 v13, v13, v66
	v_add_f32_e32 v66, v110, v111
	v_add_f32_e32 v14, v66, v14
	v_lshlrev_b32_e32 v84, 16, v217
	v_add_f32_e32 v66, v14, v15
	v_pk_mov_b32 v[14:15], v[102:103], v[84:85] op_sel:[1,0]
	v_pk_mul_f32 v[96:97], v[22:23], v[84:85]
	v_pk_mul_f32 v[30:31], v[30:31], v[14:15]
	v_pk_mul_f32 v[14:15], v[22:23], v[14:15]
	s_nop 0
	v_add_f32_e32 v14, v68, v14
	v_add_f32_e32 v14, v14, v15
	v_mul_f32_e32 v15, 0xbfb8aa3b, v14
	v_exp_f32_e32 v15, v15
	v_and_b32_e32 v68, 0xffff0000, v217
	v_add_f32_e32 v15, 1.0, v15
	v_rcp_f32_e32 v15, v15
	s_nop 0
	v_mul_f32_e32 v84, v14, v15
	v_add_f32_e32 v14, v112, v113
	v_add_f32_e32 v14, v14, v96
	v_add_f32_e32 v98, v14, v97
	v_pk_mov_b32 v[14:15], v[104:105], v[68:69] op_sel:[1,0]
	v_pk_mul_f32 v[96:97], v[0:1], v[68:69]
	v_pk_mul_f32 v[8:9], v[8:9], v[14:15]
	v_pk_mul_f32 v[14:15], v[0:1], v[14:15]
	v_add_f32_e32 v68, v70, v71
	v_add_f32_e32 v14, v68, v14
	v_add_f32_e32 v14, v14, v15
	v_mul_f32_e32 v15, 0xbfb8aa3b, v14
	v_exp_f32_e32 v15, v15
	v_lshlrev_b32_e32 v70, 16, v215
	v_lshlrev_b32_e32 v71, 16, v216
	v_pk_mov_b32 v[86:87], v[86:87], v[70:71] op_sel:[1,0]
	v_add_f32_e32 v15, 1.0, v15
	v_rcp_f32_e32 v15, v15
	v_pk_mul_f32 v[28:29], v[28:29], v[86:87]
	v_pk_mul_f32 v[86:87], v[26:27], v[86:87]
	v_fmac_f32_e32 v16, v84, v84
	v_mul_f32_e32 v14, v14, v15
	v_add_f32_e32 v15, v108, v109
	v_add_f32_e32 v15, v15, v96
	v_add_f32_e32 v68, v15, v97
	v_add_f32_e32 v15, v72, v73
	v_add_f32_e32 v15, v15, v86
	v_and_b32_e32 v73, 0xffff0000, v216
	v_and_b32_e32 v72, 0xffff0000, v215
	v_add_f32_e32 v15, v15, v87
	v_pk_mov_b32 v[86:87], v[92:93], v[72:73] op_sel:[1,0]
	v_pk_mul_f32 v[92:93], v[2:3], v[72:73]
	v_pk_mul_f32 v[10:11], v[10:11], v[86:87]
	v_pk_mul_f32 v[86:87], v[2:3], v[86:87]
	v_add_f32_e32 v72, v74, v75
	v_add_f32_e32 v72, v72, v86
	v_pk_mul_f32 v[96:97], v[26:27], v[70:71]
	v_mul_f32_e32 v70, 0xbfb8aa3b, v15
	v_add_f32_e32 v72, v72, v87
	v_exp_f32_e32 v70, v70
	v_mul_f32_e32 v74, 0xbfb8aa3b, v72
	v_exp_f32_e32 v74, v74
	v_fmac_f32_e32 v16, v14, v14
	v_add_f32_e32 v70, 1.0, v70
	v_rcp_f32_e32 v70, v70
	v_add_f32_e32 v74, 1.0, v74
	v_rcp_f32_e32 v74, v74
	v_cvt_pk_bf16_f32 v14, v84, v14
	v_mul_f32_e32 v15, v15, v70
	v_fmac_f32_e32 v16, v15, v15
	v_mul_f32_e32 v72, v72, v74
	v_cvt_pk_bf16_f32 v15, v15, v72
	ds_write_b128 v169, v[12:15] offset:3536
	v_add_f32_e32 v12, v76, v77
	v_add_f32_e32 v12, v12, v92
	v_add_f32_e32 v13, v12, v93
	v_mul_f32_e32 v12, 0xbfb8aa3b, v95
	v_exp_f32_e32 v12, v12
	v_mul_f32_e32 v74, 0xbfb8aa3b, v68
	v_exp_f32_e32 v74, v74
	v_add_f32_e32 v70, v106, v107
	v_add_f32_e32 v12, 1.0, v12
	v_rcp_f32_e32 v12, v12
	v_add_f32_e32 v74, 1.0, v74
	v_rcp_f32_e32 v74, v74
	v_fmac_f32_e32 v16, v72, v72
	v_mul_f32_e32 v14, v95, v12
	v_mul_f32_e32 v12, 0xbfb8aa3b, v64
	v_exp_f32_e32 v12, v12
	v_mul_f32_e32 v72, 0xbfb8aa3b, v66
	v_add_f32_e32 v70, v70, v96
	v_exp_f32_e32 v72, v72
	v_add_f32_e32 v70, v70, v97
	v_add_f32_e32 v12, 1.0, v12
	v_mul_f32_e32 v68, v68, v74
	v_mul_f32_e32 v74, 0xbfb8aa3b, v70
	v_rcp_f32_e32 v12, v12
	v_exp_f32_e32 v74, v74
	v_add_f32_e32 v72, 1.0, v72
	v_rcp_f32_e32 v72, v72
	v_mul_f32_e32 v15, v64, v12
	v_mul_f32_e32 v64, 0xbfb8aa3b, v80
	v_add_f32_e32 v74, 1.0, v74
	v_exp_f32_e32 v64, v64
	v_rcp_f32_e32 v74, v74
	v_mul_f32_e32 v66, v66, v72
	v_mul_f32_e32 v72, 0xbfb8aa3b, v98
	v_exp_f32_e32 v72, v72
	v_add_f32_e32 v64, 1.0, v64
	v_mul_f32_e32 v70, v70, v74
	v_mul_f32_e32 v74, 0xbfb8aa3b, v13
	v_rcp_f32_e32 v64, v64
	v_exp_f32_e32 v74, v74
	v_add_f32_e32 v72, 1.0, v72
	v_rcp_f32_e32 v72, v72
	v_mul_f32_e32 v12, v15, v15
	v_fmac_f32_e32 v12, v14, v14
	v_mul_f32_e32 v64, v80, v64
	v_add_f32_e32 v74, 1.0, v74
	v_fmac_f32_e32 v12, v64, v64
	v_rcp_f32_e32 v74, v74
	v_fmac_f32_e32 v12, v66, v66
	v_mul_f32_e32 v72, v98, v72
	v_fmac_f32_e32 v12, v72, v72
	v_fmac_f32_e32 v12, v68, v68
	v_fmac_f32_e32 v12, v70, v70
	v_mul_f32_e32 v13, v13, v74
	v_cvt_pk_bf16_f32 v74, v14, v15
	v_cvt_pk_bf16_f32 v75, v64, v66
	v_lshlrev_b32_e32 v15, 16, v213
	v_mov_b32_e32 v14, v17
	v_fmac_f32_e32 v12, v13, v13
	v_cvt_pk_bf16_f32 v76, v72, v68
	v_cvt_pk_bf16_f32 v77, v70, v13
	ds_write_b128 v169, v[74:77] offset:3808
	v_and_b32_e32 v75, 0xffff0000, v213
	v_pk_mul_f32 v[14:15], v[24:25], v[14:15]
	v_add_f32_e32 v13, v18, v19
	v_mov_b32_e32 v74, v65
	v_add_f32_e32 v13, v13, v14
	v_pk_mul_f32 v[4:5], v[4:5], v[74:75]
	v_add_f32_e32 v14, v78, v79
	v_lshlrev_b32_e32 v77, 16, v212
	v_add_f32_e32 v4, v14, v4
	v_mov_b32_e32 v76, v81
	v_add_f32_e32 v13, v13, v15
	v_add_f32_e32 v14, v4, v5
	v_pk_mul_f32 v[4:5], v[20:21], v[76:77]
	v_add_f32_e32 v15, v62, v63
	v_and_b32_e32 v87, 0xffff0000, v212
	v_add_f32_e32 v4, v15, v4
	v_mov_b32_e32 v86, v67
	v_add_f32_e32 v15, v4, v5
	v_pk_mul_f32 v[4:5], v[6:7], v[86:87]
	v_add_f32_e32 v6, v82, v83
	v_lshlrev_b32_e32 v93, 16, v195
	v_add_f32_e32 v4, v6, v4
	v_mov_b32_e32 v92, v85
	v_add_f32_e32 v6, v4, v5
	v_pk_mul_f32 v[4:5], v[22:23], v[92:93]
	v_add_f32_e32 v7, v30, v31
	v_add_f32_e32 v4, v7, v4
	v_add_f32_e32 v4, v4, v5
	v_add_f32_e32 v5, v8, v9
	v_mul_f32_e32 v9, 0xbfb8aa3b, v6
	v_exp_f32_e32 v9, v9
	v_and_b32_e32 v97, 0xffff0000, v195
	v_mov_b32_e32 v96, v69
	v_pk_mul_f32 v[0:1], v[0:1], v[96:97]
	v_add_f32_e32 v9, 1.0, v9
	v_rcp_f32_e32 v9, v9
	v_add_f32_e32 v0, v5, v0
	v_mov_b32_e32 v98, v71
	v_add_f32_e32 v5, v0, v1
	v_mul_f32_e32 v6, v6, v9
	v_mul_f32_e32 v9, 0xbfb8aa3b, v4
	v_exp_f32_e32 v9, v9
	v_pk_mul_f32 v[0:1], v[26:27], v[98:99]
	v_add_f32_e32 v7, v28, v29
	v_add_f32_e32 v0, v7, v0
	v_add_f32_e32 v9, 1.0, v9
	v_rcp_f32_e32 v9, v9
	v_mov_b32_e32 v100, v73
	v_add_f32_e32 v7, v0, v1
	v_pk_mul_f32 v[0:1], v[2:3], v[100:101]
	v_mul_f32_e32 v4, v4, v9
	v_mul_f32_e32 v9, 0xbfb8aa3b, v5
	v_add_f32_e32 v2, v10, v11
	v_exp_f32_e32 v9, v9
	v_add_f32_e32 v0, v2, v0
	v_add_f32_e32 v1, v0, v1
	v_mul_f32_e32 v0, 0xbfb8aa3b, v13
	v_exp_f32_e32 v0, v0
	v_add_f32_e32 v9, 1.0, v9
	v_rcp_f32_e32 v9, v9
	v_mul_f32_e32 v8, 0xbfb8aa3b, v15
	v_add_f32_e32 v0, 1.0, v0
	v_rcp_f32_e32 v0, v0
	v_mul_f32_e32 v5, v5, v9
	v_mul_f32_e32 v9, 0xbfb8aa3b, v7
	v_exp_f32_e32 v9, v9
	v_mul_f32_e32 v2, v13, v0
	v_mul_f32_e32 v0, 0xbfb8aa3b, v14
	v_exp_f32_e32 v0, v0
	v_add_f32_e32 v9, 1.0, v9
	v_exp_f32_e32 v8, v8
	v_rcp_f32_e32 v9, v9
	v_add_f32_e32 v0, 1.0, v0
	v_rcp_f32_e32 v0, v0
	v_add_f32_e32 v8, 1.0, v8
	v_mul_f32_e32 v7, v7, v9
	v_mul_f32_e32 v9, 0xbfb8aa3b, v1
	v_rcp_f32_e32 v8, v8
	v_exp_f32_e32 v9, v9
	v_mul_f32_e32 v3, v14, v0
	v_mul_f32_e32 v0, v3, v3
	v_fmac_f32_e32 v0, v2, v2
	v_mul_f32_e32 v8, v15, v8
	v_add_f32_e32 v9, 1.0, v9
	v_fmac_f32_e32 v0, v8, v8
	v_rcp_f32_e32 v9, v9
	v_fmac_f32_e32 v0, v6, v6
	v_fmac_f32_e32 v0, v4, v4
	v_fmac_f32_e32 v0, v5, v5
	v_fmac_f32_e32 v0, v7, v7
	v_mul_f32_e32 v1, v1, v9
	v_fmac_f32_e32 v0, v1, v1
	v_cvt_pk_bf16_f32 v2, v2, v3
	v_cvt_pk_bf16_f32 v3, v8, v6
	v_cvt_pk_bf16_f32 v4, v4, v5
	v_cvt_pk_bf16_f32 v5, v7, v1
	ds_write_b128 v169, v[2:5] offset:4080
	v_readlane_b32 s8, v255, 7
	v_readlane_b32 s9, v255, 8
	s_andn2_b64 vcc, exec, s[8:9]
	s_cbranch_vccnz .LBB0_286
	v_and_b32_e32 v2, 64, v202
	v_add_u32_e32 v5, 64, v2
	v_xor_b32_e32 v1, 1, v202
	v_cmp_lt_i32_e32 vcc, v1, v5
	s_nop 1
	v_cndmask_b32_e32 v1, v202, v1, vcc
	v_lshlrev_b32_e32 v4, 2, v1
	v_xor_b32_e32 v1, 2, v202
	v_cmp_lt_i32_e32 vcc, v1, v5
	s_nop 1
	v_cndmask_b32_e32 v1, v202, v1, vcc
	v_lshlrev_b32_e32 v3, 2, v1
	v_xor_b32_e32 v1, 4, v202
	v_cmp_lt_i32_e32 vcc, v1, v5
	s_nop 1
	v_cndmask_b32_e32 v1, v202, v1, vcc
	v_lshlrev_b32_e32 v2, 2, v1
	v_xor_b32_e32 v1, 8, v202
	v_cmp_lt_i32_e32 vcc, v1, v5
	s_nop 1
	v_cndmask_b32_e32 v1, v202, v1, vcc
	v_lshlrev_b32_e32 v1, 2, v1
	ds_bpermute_b32 v20, v4, v134
	ds_bpermute_b32 v21, v4, v135
	ds_bpermute_b32 v22, v4, v136
	ds_bpermute_b32 v23, v4, v137
	ds_bpermute_b32 v24, v4, v191
	ds_bpermute_b32 v25, v4, v192
	ds_bpermute_b32 v26, v4, v132
	ds_bpermute_b32 v27, v4, v133
	s_waitcnt lgkmcnt(7)
	v_add_f32_e32 v134, v134, v20
	s_waitcnt lgkmcnt(6)
	v_add_f32_e32 v135, v135, v21
	s_waitcnt lgkmcnt(5)
	v_add_f32_e32 v136, v136, v22
	s_waitcnt lgkmcnt(4)
	v_add_f32_e32 v137, v137, v23
	s_waitcnt lgkmcnt(3)
	v_add_f32_e32 v191, v191, v24
	s_waitcnt lgkmcnt(2)
	v_add_f32_e32 v192, v192, v25
	s_waitcnt lgkmcnt(1)
	v_add_f32_e32 v132, v132, v26
	s_waitcnt lgkmcnt(0)
	v_add_f32_e32 v133, v133, v27
	ds_bpermute_b32 v20, v4, v193
	ds_bpermute_b32 v21, v4, v214
	ds_bpermute_b32 v22, v4, v126
	ds_bpermute_b32 v23, v4, v127
	ds_bpermute_b32 v24, v4, v94
	ds_bpermute_b32 v25, v4, v16
	ds_bpermute_b32 v26, v4, v12
	ds_bpermute_b32 v27, v4, v0
	s_waitcnt lgkmcnt(7)
	v_add_f32_e32 v193, v193, v20
	s_waitcnt lgkmcnt(6)
	v_add_f32_e32 v214, v214, v21
	s_waitcnt lgkmcnt(5)
	v_add_f32_e32 v126, v126, v22
	s_waitcnt lgkmcnt(4)
	v_add_f32_e32 v127, v127, v23
	s_waitcnt lgkmcnt(3)
	v_add_f32_e32 v94, v94, v24
	s_waitcnt lgkmcnt(2)
	v_add_f32_e32 v16, v16, v25
	s_waitcnt lgkmcnt(1)
	v_add_f32_e32 v12, v12, v26
	s_waitcnt lgkmcnt(0)
	v_add_f32_e32 v0, v0, v27
	ds_bpermute_b32 v20, v3, v134
	ds_bpermute_b32 v21, v3, v135
	ds_bpermute_b32 v22, v3, v136
	ds_bpermute_b32 v23, v3, v137
	ds_bpermute_b32 v24, v3, v191
	ds_bpermute_b32 v25, v3, v192
	ds_bpermute_b32 v26, v3, v132
	ds_bpermute_b32 v27, v3, v133
	s_waitcnt lgkmcnt(7)
	v_add_f32_e32 v134, v134, v20
	s_waitcnt lgkmcnt(6)
	v_add_f32_e32 v135, v135, v21
	s_waitcnt lgkmcnt(5)
	v_add_f32_e32 v136, v136, v22
	s_waitcnt lgkmcnt(4)
	v_add_f32_e32 v137, v137, v23
	s_waitcnt lgkmcnt(3)
	v_add_f32_e32 v191, v191, v24
	s_waitcnt lgkmcnt(2)
	v_add_f32_e32 v192, v192, v25
	s_waitcnt lgkmcnt(1)
	v_add_f32_e32 v132, v132, v26
	s_waitcnt lgkmcnt(0)
	v_add_f32_e32 v133, v133, v27
	ds_bpermute_b32 v20, v3, v193
	ds_bpermute_b32 v21, v3, v214
	ds_bpermute_b32 v22, v3, v126
	ds_bpermute_b32 v23, v3, v127
	ds_bpermute_b32 v24, v3, v94
	ds_bpermute_b32 v25, v3, v16
	ds_bpermute_b32 v26, v3, v12
	ds_bpermute_b32 v27, v3, v0
	s_waitcnt lgkmcnt(7)
	v_add_f32_e32 v193, v193, v20
	s_waitcnt lgkmcnt(6)
	v_add_f32_e32 v214, v214, v21
	s_waitcnt lgkmcnt(5)
	v_add_f32_e32 v126, v126, v22
	s_waitcnt lgkmcnt(4)
	v_add_f32_e32 v127, v127, v23
	s_waitcnt lgkmcnt(3)
	v_add_f32_e32 v94, v94, v24
	s_waitcnt lgkmcnt(2)
	v_add_f32_e32 v16, v16, v25
	s_waitcnt lgkmcnt(1)
	v_add_f32_e32 v12, v12, v26
	s_waitcnt lgkmcnt(0)
	v_add_f32_e32 v0, v0, v27
	ds_bpermute_b32 v20, v2, v134
	ds_bpermute_b32 v21, v2, v135
	ds_bpermute_b32 v22, v2, v136
	ds_bpermute_b32 v23, v2, v137
	ds_bpermute_b32 v24, v2, v191
	ds_bpermute_b32 v25, v2, v192
	ds_bpermute_b32 v26, v2, v132
	ds_bpermute_b32 v27, v2, v133
	s_waitcnt lgkmcnt(7)
	v_add_f32_e32 v134, v134, v20
	s_waitcnt lgkmcnt(6)
	v_add_f32_e32 v135, v135, v21
	s_waitcnt lgkmcnt(5)
	v_add_f32_e32 v136, v136, v22
	s_waitcnt lgkmcnt(4)
	v_add_f32_e32 v137, v137, v23
	s_waitcnt lgkmcnt(3)
	v_add_f32_e32 v191, v191, v24
	s_waitcnt lgkmcnt(2)
	v_add_f32_e32 v192, v192, v25
	s_waitcnt lgkmcnt(1)
	v_add_f32_e32 v132, v132, v26
	s_waitcnt lgkmcnt(0)
	v_add_f32_e32 v133, v133, v27
	ds_bpermute_b32 v20, v2, v193
	ds_bpermute_b32 v21, v2, v214
	ds_bpermute_b32 v22, v2, v126
	ds_bpermute_b32 v23, v2, v127
	ds_bpermute_b32 v24, v2, v94
	ds_bpermute_b32 v25, v2, v16
	ds_bpermute_b32 v26, v2, v12
	ds_bpermute_b32 v27, v2, v0
	s_waitcnt lgkmcnt(7)
	v_add_f32_e32 v193, v193, v20
	s_waitcnt lgkmcnt(6)
	v_add_f32_e32 v214, v214, v21
	s_waitcnt lgkmcnt(5)
	v_add_f32_e32 v126, v126, v22
	s_waitcnt lgkmcnt(4)
	v_add_f32_e32 v127, v127, v23
	s_waitcnt lgkmcnt(3)
	v_add_f32_e32 v94, v94, v24
	s_waitcnt lgkmcnt(2)
	v_add_f32_e32 v16, v16, v25
	s_waitcnt lgkmcnt(1)
	v_add_f32_e32 v12, v12, v26
	s_waitcnt lgkmcnt(0)
	v_add_f32_e32 v0, v0, v27
	ds_bpermute_b32 v20, v1, v134
	ds_bpermute_b32 v21, v1, v135
	ds_bpermute_b32 v22, v1, v136
	ds_bpermute_b32 v23, v1, v137
	ds_bpermute_b32 v24, v1, v191
	ds_bpermute_b32 v25, v1, v192
	ds_bpermute_b32 v26, v1, v132
	ds_bpermute_b32 v27, v1, v133
	s_waitcnt lgkmcnt(7)
	v_add_f32_e32 v134, v134, v20
	s_waitcnt lgkmcnt(6)
	v_add_f32_e32 v135, v135, v21
	s_waitcnt lgkmcnt(5)
	v_add_f32_e32 v136, v136, v22
	s_waitcnt lgkmcnt(4)
	v_add_f32_e32 v137, v137, v23
	s_waitcnt lgkmcnt(3)
	v_add_f32_e32 v191, v191, v24
	s_waitcnt lgkmcnt(2)
	v_add_f32_e32 v192, v192, v25
	s_waitcnt lgkmcnt(1)
	v_add_f32_e32 v132, v132, v26
	s_waitcnt lgkmcnt(0)
	v_add_f32_e32 v133, v133, v27
	ds_bpermute_b32 v20, v1, v193
	ds_bpermute_b32 v21, v1, v214
	ds_bpermute_b32 v22, v1, v126
	ds_bpermute_b32 v23, v1, v127
	ds_bpermute_b32 v24, v1, v94
	ds_bpermute_b32 v25, v1, v16
	ds_bpermute_b32 v26, v1, v12
	ds_bpermute_b32 v27, v1, v0
	s_waitcnt lgkmcnt(7)
	v_add_f32_e32 v193, v193, v20
	s_waitcnt lgkmcnt(6)
	v_add_f32_e32 v214, v214, v21
	s_waitcnt lgkmcnt(5)
	v_add_f32_e32 v126, v126, v22
	s_waitcnt lgkmcnt(4)
	v_add_f32_e32 v127, v127, v23
	s_waitcnt lgkmcnt(3)
	v_add_f32_e32 v94, v94, v24
	s_waitcnt lgkmcnt(2)
	v_add_f32_e32 v16, v16, v25
	s_waitcnt lgkmcnt(1)
	v_add_f32_e32 v12, v12, v26
	s_waitcnt lgkmcnt(0)
	v_add_f32_e32 v0, v0, v27
	v_cndmask_b32_e64 v5, 0, v134, s[6:7]
	v_readlane_b32 s8, v254, 20
	v_readlane_b32 s9, v254, 21
	s_nop 1
	v_cndmask_b32_e64 v5, v5, v135, s[8:9]
	v_readlane_b32 s8, v254, 22
	v_readlane_b32 s9, v254, 23
	s_nop 1
	v_cndmask_b32_e64 v5, v5, v136, s[8:9]
	v_readlane_b32 s8, v254, 24
	v_readlane_b32 s9, v254, 25
	s_nop 1
	v_cndmask_b32_e64 v5, v5, v137, s[8:9]
	v_readlane_b32 s8, v254, 26
	v_readlane_b32 s9, v254, 27
	s_nop 1
	v_cndmask_b32_e64 v5, v5, v191, s[8:9]
	v_readlane_b32 s8, v254, 28
	v_readlane_b32 s9, v254, 29
	s_nop 1
	v_cndmask_b32_e64 v5, v5, v192, s[8:9]
	v_readlane_b32 s8, v254, 30
	v_readlane_b32 s9, v254, 31
	s_nop 1
	v_cndmask_b32_e64 v5, v5, v132, s[8:9]
	v_readlane_b32 s8, v254, 32
	v_readlane_b32 s9, v254, 33
	s_nop 1
	v_cndmask_b32_e64 v5, v5, v133, s[8:9]
	v_readlane_b32 s8, v254, 34
	v_readlane_b32 s9, v254, 35
	s_nop 1
	v_cndmask_b32_e64 v5, v5, v193, s[8:9]
	v_readlane_b32 s8, v254, 36
	v_readlane_b32 s9, v254, 37
	s_nop 1
	v_cndmask_b32_e64 v5, v5, v214, s[8:9]
	v_readlane_b32 s8, v254, 38
	v_readlane_b32 s9, v254, 39
	s_nop 1
	v_cndmask_b32_e64 v5, v5, v126, s[8:9]
	v_readlane_b32 s8, v254, 40
	v_readlane_b32 s9, v254, 41
	s_nop 1
	v_cndmask_b32_e64 v5, v5, v127, s[8:9]
	v_readlane_b32 s8, v254, 42
	v_readlane_b32 s9, v254, 43
	s_nop 1
	v_cndmask_b32_e64 v5, v5, v94, s[8:9]
	v_readlane_b32 s8, v254, 44
	v_readlane_b32 s9, v254, 45
	s_nop 1
	v_cndmask_b32_e64 v5, v5, v16, s[8:9]
	v_readlane_b32 s8, v254, 46
	v_readlane_b32 s9, v254, 47
	s_nop 1
	v_cndmask_b32_e64 v5, v5, v12, s[8:9]
	v_readlane_b32 s8, v254, 48
	v_readlane_b32 s9, v254, 49
	s_nop 1
	v_cndmask_b32_e64 v0, v5, v0, s[8:9]
	v_add_f32_e32 v0, 0x358637bd, v0
	v_cmp_gt_f32_e32 vcc, s86, v0
	v_mul_f32_e32 v1, 0x4b800000, v0
	s_nop 0
	v_cndmask_b32_e32 v0, v0, v1, vcc
	v_rsq_f32_e32 v0, v0
	s_nop 0
	v_mul_f32_e32 v1, 0x45800000, v0
	v_cndmask_b32_e32 v0, v0, v1, vcc
	v_mul_f32_e32 v0, v170, v0
	ds_write_b32 v171, v0

.LBB0_634:
	s_or_b64 exec, exec, s[2:3]
	s_mov_b64 s[2:3], 0x410000
	v_cmp_gt_u64_e32 vcc, s[2:3], v[4:5]
	s_and_saveexec_b64 s[2:3], vcc
	s_cbranch_execz .LBB0_24
	v_readlane_b32 s6, v252, 29
	v_readlane_b32 s7, v252, 30
	v_readlane_b32 s10, v252, 27
	v_readlane_b32 s12, v252, 23
	v_readlane_b32 s14, v252, 13
	v_lshlrev_b64 v[6:7], 4, v[160:161]
	s_lshl_b64 s[4:5], s[56:57], 13
	v_lshl_add_u64 v[8:9], v[160:161], 3, s[6:7]
	s_lshl_b64 s[6:7], s[56:57], 12
	s_mov_b64 s[8:9], 0
	v_readlane_b32 s11, v252, 28
	v_readlane_b32 s13, v252, 24
	v_readlane_b32 s15, v252, 14
	s_cmp_eq_u32 s56, 0x100
	s_cbranch_scc0 .Lxc_done
	s_mov_b32 s100, 0xed360000
	s_mov_b32 s101, -1
	v_lshl_add_u64 v[14:15], s[14:15], 0, v[6:7]
	global_load_dwordx4 v[162:165], v[14:15], off
	s_add_u32 s14, s14, s4
	s_addc_u32 s15, s15, s5
	v_lshl_add_u64 v[14:15], s[14:15], 0, v[6:7]
	global_load_dwordx4 v[166:169], v[14:15], off
	s_add_u32 s14, s14, s4
	s_addc_u32 s15, s15, s5
	v_lshl_add_u64 v[14:15], s[14:15], 0, v[6:7]
	global_load_dwordx4 v[172:175], v[14:15], off
	s_add_u32 s14, s14, s4
	s_addc_u32 s15, s15, s5
	v_lshl_add_u64 v[14:15], s[14:15], 0, v[6:7]
	global_load_dwordx4 v[176:179], v[14:15], off
	s_add_u32 s14, s14, s4
	s_addc_u32 s15, s15, s5
	v_lshl_add_u64 v[14:15], s[14:15], 0, v[6:7]
	global_load_dwordx4 v[180:183], v[14:15], off
	s_add_u32 s14, s14, s4
	s_addc_u32 s15, s15, s5
	v_lshl_add_u64 v[14:15], s[14:15], 0, v[6:7]
	global_load_dwordx4 v[184:187], v[14:15], off
	s_add_u32 s14, s14, s4
	s_addc_u32 s15, s15, s5
	v_lshl_add_u64 v[14:15], s[14:15], 0, v[6:7]
	global_load_dwordx4 v[192:195], v[14:15], off
	s_add_u32 s14, s14, s4
	s_addc_u32 s15, s15, s5
	v_lshl_add_u64 v[14:15], s[14:15], 0, v[6:7]
	global_load_dwordx4 v[212:215], v[14:15], off
	s_add_u32 s14, s14, s4
	s_addc_u32 s15, s15, s5
	v_lshl_add_u64 v[24:25], s[10:11], 0, v[6:7]
	s_waitcnt vmcnt(7)
	global_store_dwordx4 v[24:25], v[162:165], off
	v_cvt_pk_bf16_f32 v44, v162, v163
	v_cvt_pk_bf16_f32 v45, v164, v165
	v_lshl_add_u64 v[26:27], v[8:9], 0, s[100:101]
	global_store_dwordx2 v[26:27], v[44:45], off
	s_add_u32 s10, s10, s4
	s_addc_u32 s11, s11, s5
	s_add_u32 s12, s12, s4
	s_addc_u32 s13, s13, s5
	v_lshl_add_u64 v[8:9], v[8:9], 0, s[6:7]
	v_lshl_add_u64 v[14:15], s[14:15], 0, v[6:7]
	global_load_dwordx4 v[162:165], v[14:15], off
	s_add_u32 s14, s14, s4
	s_addc_u32 s15, s15, s5
	v_lshl_add_u64 v[24:25], s[10:11], 0, v[6:7]
	s_waitcnt vmcnt(9)
	global_store_dwordx4 v[24:25], v[166:169], off
	v_cvt_pk_bf16_f32 v44, v166, v167
	v_cvt_pk_bf16_f32 v45, v168, v169
	v_lshl_add_u64 v[26:27], v[8:9], 0, s[100:101]
	global_store_dwordx2 v[26:27], v[44:45], off
	s_add_u32 s10, s10, s4
	s_addc_u32 s11, s11, s5
	s_add_u32 s12, s12, s4
	s_addc_u32 s13, s13, s5
	v_lshl_add_u64 v[8:9], v[8:9], 0, s[6:7]
	v_lshl_add_u64 v[14:15], s[14:15], 0, v[6:7]
	global_load_dwordx4 v[166:169], v[14:15], off
	s_add_u32 s14, s14, s4
	s_addc_u32 s15, s15, s5
	v_lshl_add_u64 v[24:25], s[10:11], 0, v[6:7]
	s_waitcnt vmcnt(11)
	global_store_dwordx4 v[24:25], v[172:175], off
	v_cvt_pk_bf16_f32 v44, v172, v173
	v_cvt_pk_bf16_f32 v45, v174, v175
	v_lshl_add_u64 v[26:27], v[8:9], 0, s[100:101]
	global_store_dwordx2 v[26:27], v[44:45], off
	s_add_u32 s10, s10, s4
	s_addc_u32 s11, s11, s5
	s_add_u32 s12, s12, s4
	s_addc_u32 s13, s13, s5
	v_lshl_add_u64 v[8:9], v[8:9], 0, s[6:7]
	v_lshl_add_u64 v[14:15], s[14:15], 0, v[6:7]
	global_load_dwordx4 v[172:175], v[14:15], off
	s_add_u32 s14, s14, s4
	s_addc_u32 s15, s15, s5
	v_lshl_add_u64 v[24:25], s[10:11], 0, v[6:7]
	s_waitcnt vmcnt(13)
	global_store_dwordx4 v[24:25], v[176:179], off
	v_cvt_pk_bf16_f32 v44, v176, v177
	v_cvt_pk_bf16_f32 v45, v178, v179
	v_lshl_add_u64 v[26:27], v[8:9], 0, s[100:101]
	global_store_dwordx2 v[26:27], v[44:45], off
	s_add_u32 s10, s10, s4
	s_addc_u32 s11, s11, s5
	s_add_u32 s12, s12, s4
	s_addc_u32 s13, s13, s5
	v_lshl_add_u64 v[8:9], v[8:9], 0, s[6:7]
	v_lshl_add_u64 v[14:15], s[14:15], 0, v[6:7]
	global_load_dwordx4 v[176:179], v[14:15], off
	s_add_u32 s14, s14, s4
	s_addc_u32 s15, s15, s5
	v_lshl_add_u64 v[24:25], s[10:11], 0, v[6:7]
	s_waitcnt vmcnt(15)
	global_store_dwordx4 v[24:25], v[180:183], off
	v_cvt_pk_bf16_f32 v44, v180, v181
	v_cvt_pk_bf16_f32 v45, v182, v183
	v_lshl_add_u64 v[26:27], v[8:9], 0, s[100:101]
	global_store_dwordx2 v[26:27], v[44:45], off
	s_add_u32 s10, s10, s4
	s_addc_u32 s11, s11, s5
	s_add_u32 s12, s12, s4
	s_addc_u32 s13, s13, s5
	v_lshl_add_u64 v[8:9], v[8:9], 0, s[6:7]
	v_lshl_add_u64 v[14:15], s[14:15], 0, v[6:7]
	global_load_dwordx4 v[180:183], v[14:15], off
	s_add_u32 s14, s14, s4
	s_addc_u32 s15, s15, s5
	v_lshl_add_u64 v[24:25], s[10:11], 0, v[6:7]
	s_waitcnt vmcnt(17)
	global_store_dwordx4 v[24:25], v[184:187], off
	v_cvt_pk_bf16_f32 v44, v184, v185
	v_cvt_pk_bf16_f32 v45, v186, v187
	v_lshl_add_u64 v[26:27], v[8:9], 0, s[100:101]
	global_store_dwordx2 v[26:27], v[44:45], off
	s_add_u32 s10, s10, s4
	s_addc_u32 s11, s11, s5
	s_add_u32 s12, s12, s4
	s_addc_u32 s13, s13, s5
	v_lshl_add_u64 v[8:9], v[8:9], 0, s[6:7]
	v_lshl_add_u64 v[14:15], s[14:15], 0, v[6:7]
	global_load_dwordx4 v[184:187], v[14:15], off
	s_add_u32 s14, s14, s4
	s_addc_u32 s15, s15, s5
	v_lshl_add_u64 v[24:25], s[10:11], 0, v[6:7]
	s_waitcnt vmcnt(19)
	global_store_dwordx4 v[24:25], v[192:195], off
	v_cvt_pk_bf16_f32 v44, v192, v193
	v_cvt_pk_bf16_f32 v45, v194, v195
	v_lshl_add_u64 v[26:27], v[8:9], 0, s[100:101]
	global_store_dwordx2 v[26:27], v[44:45], off
	s_add_u32 s10, s10, s4
	s_addc_u32 s11, s11, s5
	s_add_u32 s12, s12, s4
	s_addc_u32 s13, s13, s5
	v_lshl_add_u64 v[8:9], v[8:9], 0, s[6:7]
	v_lshl_add_u64 v[14:15], s[14:15], 0, v[6:7]
	global_load_dwordx4 v[192:195], v[14:15], off
	s_add_u32 s14, s14, s4
	s_addc_u32 s15, s15, s5
	v_lshl_add_u64 v[24:25], s[10:11], 0, v[6:7]
	s_waitcnt vmcnt(21)
	global_store_dwordx4 v[24:25], v[212:215], off
	v_cvt_pk_bf16_f32 v44, v212, v213
	v_cvt_pk_bf16_f32 v45, v214, v215
	v_lshl_add_u64 v[26:27], v[8:9], 0, s[100:101]
	global_store_dwordx2 v[26:27], v[44:45], off
	s_add_u32 s10, s10, s4
	s_addc_u32 s11, s11, s5
	s_add_u32 s12, s12, s4
	s_addc_u32 s13, s13, s5
	v_lshl_add_u64 v[8:9], v[8:9], 0, s[6:7]
	v_lshl_add_u64 v[14:15], s[14:15], 0, v[6:7]
	global_load_dwordx4 v[212:215], v[14:15], off
	s_add_u32 s14, s14, s4
	s_addc_u32 s15, s15, s5
	v_lshl_add_u64 v[24:25], s[10:11], 0, v[6:7]
	s_waitcnt vmcnt(21)
	global_store_dwordx4 v[24:25], v[162:165], off
	v_cvt_pk_bf16_f32 v44, v162, v163
	v_cvt_pk_bf16_f32 v45, v164, v165
	v_lshl_add_u64 v[26:27], v[8:9], 0, s[100:101]
	global_store_dwordx2 v[26:27], v[44:45], off
	s_add_u32 s10, s10, s4
	s_addc_u32 s11, s11, s5
	s_add_u32 s12, s12, s4
	s_addc_u32 s13, s13, s5
	v_lshl_add_u64 v[8:9], v[8:9], 0, s[6:7]
	v_lshl_add_u64 v[14:15], s[14:15], 0, v[6:7]
	global_load_dwordx4 v[162:165], v[14:15], off
	s_add_u32 s14, s14, s4
	s_addc_u32 s15, s15, s5
	v_lshl_add_u64 v[24:25], s[10:11], 0, v[6:7]
	s_waitcnt vmcnt(21)
	global_store_dwordx4 v[24:25], v[166:169], off
	v_cvt_pk_bf16_f32 v44, v166, v167
	v_cvt_pk_bf16_f32 v45, v168, v169
	v_lshl_add_u64 v[26:27], v[8:9], 0, s[100:101]
	global_store_dwordx2 v[26:27], v[44:45], off
	s_add_u32 s10, s10, s4
	s_addc_u32 s11, s11, s5
	s_add_u32 s12, s12, s4
	s_addc_u32 s13, s13, s5
	v_lshl_add_u64 v[8:9], v[8:9], 0, s[6:7]
	v_lshl_add_u64 v[14:15], s[14:15], 0, v[6:7]
	global_load_dwordx4 v[166:169], v[14:15], off
	s_add_u32 s14, s14, s4
	s_addc_u32 s15, s15, s5
	v_lshl_add_u64 v[24:25], s[10:11], 0, v[6:7]
	s_waitcnt vmcnt(21)
	global_store_dwordx4 v[24:25], v[172:175], off
	v_cvt_pk_bf16_f32 v44, v172, v173
	v_cvt_pk_bf16_f32 v45, v174, v175
	v_lshl_add_u64 v[26:27], v[8:9], 0, s[100:101]
	global_store_dwordx2 v[26:27], v[44:45], off
	s_add_u32 s10, s10, s4
	s_addc_u32 s11, s11, s5
	s_add_u32 s12, s12, s4
	s_addc_u32 s13, s13, s5
	v_lshl_add_u64 v[8:9], v[8:9], 0, s[6:7]
	v_lshl_add_u64 v[14:15], s[14:15], 0, v[6:7]
	global_load_dwordx4 v[172:175], v[14:15], off
	s_add_u32 s14, s14, s4
	s_addc_u32 s15, s15, s5
	v_lshl_add_u64 v[24:25], s[10:11], 0, v[6:7]
	s_waitcnt vmcnt(21)
	global_store_dwordx4 v[24:25], v[176:179], off
	v_cvt_pk_bf16_f32 v44, v176, v177
	v_cvt_pk_bf16_f32 v45, v178, v179
	v_lshl_add_u64 v[26:27], v[8:9], 0, s[100:101]
	global_store_dwordx2 v[26:27], v[44:45], off
	s_add_u32 s10, s10, s4
	s_addc_u32 s11, s11, s5
	s_add_u32 s12, s12, s4
	s_addc_u32 s13, s13, s5
	v_lshl_add_u64 v[8:9], v[8:9], 0, s[6:7]
	v_lshl_add_u64 v[14:15], s[14:15], 0, v[6:7]
	global_load_dwordx4 v[176:179], v[14:15], off
	s_add_u32 s14, s14, s4
	s_addc_u32 s15, s15, s5
	v_lshl_add_u64 v[24:25], s[10:11], 0, v[6:7]
	s_waitcnt vmcnt(21)
	global_store_dwordx4 v[24:25], v[180:183], off
	v_cvt_pk_bf16_f32 v44, v180, v181
	v_cvt_pk_bf16_f32 v45, v182, v183
	v_lshl_add_u64 v[26:27], v[8:9], 0, s[100:101]
	global_store_dwordx2 v[26:27], v[44:45], off
	s_add_u32 s10, s10, s4
	s_addc_u32 s11, s11, s5
	s_add_u32 s12, s12, s4
	s_addc_u32 s13, s13, s5
	v_lshl_add_u64 v[8:9], v[8:9], 0, s[6:7]
	v_lshl_add_u64 v[14:15], s[14:15], 0, v[6:7]
	global_load_dwordx4 v[180:183], v[14:15], off
	s_add_u32 s14, s14, s4
	s_addc_u32 s15, s15, s5
	v_lshl_add_u64 v[24:25], s[10:11], 0, v[6:7]
	s_waitcnt vmcnt(21)
	global_store_dwordx4 v[24:25], v[184:187], off
	v_cvt_pk_bf16_f32 v44, v184, v185
	v_cvt_pk_bf16_f32 v45, v186, v187
	v_lshl_add_u64 v[26:27], v[8:9], 0, s[100:101]
	global_store_dwordx2 v[26:27], v[44:45], off
	s_add_u32 s10, s10, s4
	s_addc_u32 s11, s11, s5
	s_add_u32 s12, s12, s4
	s_addc_u32 s13, s13, s5
	v_lshl_add_u64 v[8:9], v[8:9], 0, s[6:7]
	v_lshl_add_u64 v[14:15], s[14:15], 0, v[6:7]
	global_load_dwordx4 v[184:187], v[14:15], off
	s_add_u32 s14, s14, s4
	s_addc_u32 s15, s15, s5
	v_lshl_add_u64 v[24:25], s[10:11], 0, v[6:7]
	s_waitcnt vmcnt(21)
	global_store_dwordx4 v[24:25], v[192:195], off
	v_cvt_pk_bf16_f32 v44, v192, v193
	v_cvt_pk_bf16_f32 v45, v194, v195
	v_lshl_add_u64 v[26:27], v[8:9], 0, s[100:101]
	global_store_dwordx2 v[26:27], v[44:45], off
	s_add_u32 s10, s10, s4
	s_addc_u32 s11, s11, s5
	s_add_u32 s12, s12, s4
	s_addc_u32 s13, s13, s5
	v_lshl_add_u64 v[8:9], v[8:9], 0, s[6:7]
	v_lshl_add_u64 v[14:15], s[14:15], 0, v[6:7]
	global_load_dwordx4 v[192:195], v[14:15], off
	s_add_u32 s14, s14, s4
	s_addc_u32 s15, s15, s5
	v_lshl_add_u64 v[24:25], s[10:11], 0, v[6:7]
	s_waitcnt vmcnt(21)
	global_store_dwordx4 v[24:25], v[212:215], off
	v_cvt_pk_bf16_f32 v44, v212, v213
	v_cvt_pk_bf16_f32 v45, v214, v215
	v_lshl_add_u64 v[26:27], v[8:9], 0, s[100:101]
	global_store_dwordx2 v[26:27], v[44:45], off
	s_add_u32 s10, s10, s4
	s_addc_u32 s11, s11, s5
	s_add_u32 s12, s12, s4
	s_addc_u32 s13, s13, s5
	v_lshl_add_u64 v[8:9], v[8:9], 0, s[6:7]
	v_lshl_add_u64 v[14:15], s[14:15], 0, v[6:7]
	global_load_dwordx4 v[212:215], v[14:15], off
	s_add_u32 s14, s14, s4
	s_addc_u32 s15, s15, s5
	v_lshl_add_u64 v[24:25], s[10:11], 0, v[6:7]
	s_waitcnt vmcnt(21)
	global_store_dwordx4 v[24:25], v[162:165], off
	v_cvt_pk_bf16_f32 v44, v162, v163
	v_cvt_pk_bf16_f32 v45, v164, v165
	v_lshl_add_u64 v[26:27], v[8:9], 0, s[100:101]
	global_store_dwordx2 v[26:27], v[44:45], off
	s_add_u32 s10, s10, s4
	s_addc_u32 s11, s11, s5
	s_add_u32 s12, s12, s4
	s_addc_u32 s13, s13, s5
	v_lshl_add_u64 v[8:9], v[8:9], 0, s[6:7]
	v_lshl_add_u64 v[14:15], s[14:15], 0, v[6:7]
	global_load_dwordx4 v[162:165], v[14:15], off
	s_add_u32 s14, s14, s4
	s_addc_u32 s15, s15, s5
	v_lshl_add_u64 v[24:25], s[10:11], 0, v[6:7]
	s_waitcnt vmcnt(21)
	global_store_dwordx4 v[24:25], v[166:169], off
	v_cvt_pk_bf16_f32 v44, v166, v167
	v_cvt_pk_bf16_f32 v45, v168, v169
	v_lshl_add_u64 v[26:27], v[8:9], 0, s[100:101]
	global_store_dwordx2 v[26:27], v[44:45], off
	s_add_u32 s10, s10, s4
	s_addc_u32 s11, s11, s5
	s_add_u32 s12, s12, s4
	s_addc_u32 s13, s13, s5
	v_lshl_add_u64 v[8:9], v[8:9], 0, s[6:7]
	v_lshl_add_u64 v[14:15], s[14:15], 0, v[6:7]
	global_load_dwordx4 v[166:169], v[14:15], off
	s_add_u32 s14, s14, s4
	s_addc_u32 s15, s15, s5
	v_lshl_add_u64 v[24:25], s[10:11], 0, v[6:7]
	s_waitcnt vmcnt(21)
	global_store_dwordx4 v[24:25], v[172:175], off
	v_cvt_pk_bf16_f32 v44, v172, v173
	v_cvt_pk_bf16_f32 v45, v174, v175
	v_lshl_add_u64 v[26:27], v[8:9], 0, s[100:101]
	global_store_dwordx2 v[26:27], v[44:45], off
	s_add_u32 s10, s10, s4
	s_addc_u32 s11, s11, s5
	s_add_u32 s12, s12, s4
	s_addc_u32 s13, s13, s5
	v_lshl_add_u64 v[8:9], v[8:9], 0, s[6:7]
	v_lshl_add_u64 v[14:15], s[14:15], 0, v[6:7]
	global_load_dwordx4 v[172:175], v[14:15], off
	s_add_u32 s14, s14, s4
	s_addc_u32 s15, s15, s5
	v_lshl_add_u64 v[24:25], s[10:11], 0, v[6:7]
	s_waitcnt vmcnt(21)
	global_store_dwordx4 v[24:25], v[176:179], off
	v_cvt_pk_bf16_f32 v44, v176, v177
	v_cvt_pk_bf16_f32 v45, v178, v179
	v_lshl_add_u64 v[26:27], v[8:9], 0, s[100:101]
	global_store_dwordx2 v[26:27], v[44:45], off
	s_add_u32 s10, s10, s4
	s_addc_u32 s11, s11, s5
	s_add_u32 s12, s12, s4
	s_addc_u32 s13, s13, s5
	v_lshl_add_u64 v[8:9], v[8:9], 0, s[6:7]
	v_lshl_add_u64 v[14:15], s[14:15], 0, v[6:7]
	global_load_dwordx4 v[176:179], v[14:15], off
	s_add_u32 s14, s14, s4
	s_addc_u32 s15, s15, s5
	v_lshl_add_u64 v[24:25], s[10:11], 0, v[6:7]
	s_waitcnt vmcnt(21)
	global_store_dwordx4 v[24:25], v[180:183], off
	v_cvt_pk_bf16_f32 v44, v180, v181
	v_cvt_pk_bf16_f32 v45, v182, v183
	v_lshl_add_u64 v[26:27], v[8:9], 0, s[100:101]
	global_store_dwordx2 v[26:27], v[44:45], off
	s_add_u32 s10, s10, s4
	s_addc_u32 s11, s11, s5
	s_add_u32 s12, s12, s4
	s_addc_u32 s13, s13, s5
	v_lshl_add_u64 v[8:9], v[8:9], 0, s[6:7]
	v_lshl_add_u64 v[14:15], s[14:15], 0, v[6:7]
	global_load_dwordx4 v[180:183], v[14:15], off
	s_add_u32 s14, s14, s4
	s_addc_u32 s15, s15, s5
	v_lshl_add_u64 v[24:25], s[10:11], 0, v[6:7]
	s_waitcnt vmcnt(21)
	global_store_dwordx4 v[24:25], v[184:187], off
	v_cvt_pk_bf16_f32 v44, v184, v185
	v_cvt_pk_bf16_f32 v45, v186, v187
	v_lshl_add_u64 v[26:27], v[8:9], 0, s[100:101]
	global_store_dwordx2 v[26:27], v[44:45], off
	s_add_u32 s10, s10, s4
	s_addc_u32 s11, s11, s5
	s_add_u32 s12, s12, s4
	s_addc_u32 s13, s13, s5
	v_lshl_add_u64 v[8:9], v[8:9], 0, s[6:7]
	v_lshl_add_u64 v[14:15], s[14:15], 0, v[6:7]
	global_load_dwordx4 v[184:187], v[14:15], off
	s_add_u32 s14, s14, s4
	s_addc_u32 s15, s15, s5
	v_lshl_add_u64 v[24:25], s[10:11], 0, v[6:7]
	s_waitcnt vmcnt(21)
	global_store_dwordx4 v[24:25], v[192:195], off
	v_cvt_pk_bf16_f32 v44, v192, v193
	v_cvt_pk_bf16_f32 v45, v194, v195
	v_lshl_add_u64 v[26:27], v[8:9], 0, s[100:101]
	global_store_dwordx2 v[26:27], v[44:45], off
	s_add_u32 s10, s10, s4
	s_addc_u32 s11, s11, s5
	s_add_u32 s12, s12, s4
	s_addc_u32 s13, s13, s5
	v_lshl_add_u64 v[8:9], v[8:9], 0, s[6:7]
	v_lshl_add_u64 v[14:15], s[14:15], 0, v[6:7]
	global_load_dwordx4 v[192:195], v[14:15], off
	s_add_u32 s14, s14, s4
	s_addc_u32 s15, s15, s5
	v_lshl_add_u64 v[24:25], s[10:11], 0, v[6:7]
	s_waitcnt vmcnt(21)
	global_store_dwordx4 v[24:25], v[212:215], off
	v_cvt_pk_bf16_f32 v44, v212, v213
	v_cvt_pk_bf16_f32 v45, v214, v215
	v_lshl_add_u64 v[26:27], v[8:9], 0, s[100:101]
	global_store_dwordx2 v[26:27], v[44:45], off
	s_add_u32 s10, s10, s4
	s_addc_u32 s11, s11, s5
	s_add_u32 s12, s12, s4
	s_addc_u32 s13, s13, s5
	v_lshl_add_u64 v[8:9], v[8:9], 0, s[6:7]
	v_lshl_add_u64 v[14:15], s[14:15], 0, v[6:7]
	global_load_dwordx4 v[212:215], v[14:15], off
	s_add_u32 s14, s14, s4
	s_addc_u32 s15, s15, s5
	v_lshl_add_u64 v[24:25], s[10:11], 0, v[6:7]
	s_waitcnt vmcnt(21)
	global_store_dwordx4 v[24:25], v[162:165], off
	v_cvt_pk_bf16_f32 v44, v162, v163
	v_cvt_pk_bf16_f32 v45, v164, v165
	v_lshl_add_u64 v[26:27], v[8:9], 0, s[100:101]
	global_store_dwordx2 v[26:27], v[44:45], off
	s_add_u32 s10, s10, s4
	s_addc_u32 s11, s11, s5
	s_add_u32 s12, s12, s4
	s_addc_u32 s13, s13, s5
	v_lshl_add_u64 v[8:9], v[8:9], 0, s[6:7]
	v_lshl_add_u64 v[24:25], s[10:11], 0, v[6:7]
	s_waitcnt vmcnt(20)
	global_store_dwordx4 v[24:25], v[166:169], off
	v_cvt_pk_bf16_f32 v44, v166, v167
	v_cvt_pk_bf16_f32 v45, v168, v169
	v_lshl_add_u64 v[26:27], v[8:9], 0, s[100:101]
	global_store_dwordx2 v[26:27], v[44:45], off
	s_add_u32 s10, s10, s4
	s_addc_u32 s11, s11, s5
	s_add_u32 s12, s12, s4
	s_addc_u32 s13, s13, s5
	v_lshl_add_u64 v[8:9], v[8:9], 0, s[6:7]
	v_lshl_add_u64 v[24:25], s[10:11], 0, v[6:7]
	s_waitcnt vmcnt(19)
	global_store_dwordx4 v[24:25], v[172:175], off
	v_cvt_pk_bf16_f32 v44, v172, v173
	v_cvt_pk_bf16_f32 v45, v174, v175
	v_lshl_add_u64 v[26:27], v[8:9], 0, s[100:101]
	global_store_dwordx2 v[26:27], v[44:45], off
	s_add_u32 s10, s10, s4
	s_addc_u32 s11, s11, s5
	s_add_u32 s12, s12, s4
	s_addc_u32 s13, s13, s5
	v_lshl_add_u64 v[8:9], v[8:9], 0, s[6:7]
	v_lshl_add_u64 v[24:25], s[10:11], 0, v[6:7]
	s_waitcnt vmcnt(18)
	global_store_dwordx4 v[24:25], v[176:179], off
	v_cvt_pk_bf16_f32 v44, v176, v177
	v_cvt_pk_bf16_f32 v45, v178, v179
	v_lshl_add_u64 v[26:27], v[8:9], 0, s[100:101]
	global_store_dwordx2 v[26:27], v[44:45], off
	s_add_u32 s10, s10, s4
	s_addc_u32 s11, s11, s5
	s_add_u32 s12, s12, s4
	s_addc_u32 s13, s13, s5
	v_lshl_add_u64 v[8:9], v[8:9], 0, s[6:7]
	v_lshl_add_u64 v[24:25], s[10:11], 0, v[6:7]
	s_waitcnt vmcnt(17)
	global_store_dwordx4 v[24:25], v[180:183], off
	v_cvt_pk_bf16_f32 v44, v180, v181
	v_cvt_pk_bf16_f32 v45, v182, v183
	v_lshl_add_u64 v[26:27], v[8:9], 0, s[100:101]
	global_store_dwordx2 v[26:27], v[44:45], off
	s_add_u32 s10, s10, s4
	s_addc_u32 s11, s11, s5
	s_add_u32 s12, s12, s4
	s_addc_u32 s13, s13, s5
	v_lshl_add_u64 v[8:9], v[8:9], 0, s[6:7]
	v_lshl_add_u64 v[24:25], s[10:11], 0, v[6:7]
	s_waitcnt vmcnt(16)
	global_store_dwordx4 v[24:25], v[184:187], off
	v_cvt_pk_bf16_f32 v44, v184, v185
	v_cvt_pk_bf16_f32 v45, v186, v187
	v_lshl_add_u64 v[26:27], v[8:9], 0, s[100:101]
	global_store_dwordx2 v[26:27], v[44:45], off
	s_add_u32 s10, s10, s4
	s_addc_u32 s11, s11, s5
	s_add_u32 s12, s12, s4
	s_addc_u32 s13, s13, s5
	v_lshl_add_u64 v[8:9], v[8:9], 0, s[6:7]
	v_lshl_add_u64 v[24:25], s[10:11], 0, v[6:7]
	s_waitcnt vmcnt(15)
	global_store_dwordx4 v[24:25], v[192:195], off
	v_cvt_pk_bf16_f32 v44, v192, v193
	v_cvt_pk_bf16_f32 v45, v194, v195
	v_lshl_add_u64 v[26:27], v[8:9], 0, s[100:101]
	global_store_dwordx2 v[26:27], v[44:45], off
	s_add_u32 s10, s10, s4
	s_addc_u32 s11, s11, s5
	s_add_u32 s12, s12, s4
	s_addc_u32 s13, s13, s5
	v_lshl_add_u64 v[8:9], v[8:9], 0, s[6:7]
	v_lshl_add_u64 v[24:25], s[10:11], 0, v[6:7]
	s_waitcnt vmcnt(14)
	global_store_dwordx4 v[24:25], v[212:215], off
	v_cvt_pk_bf16_f32 v44, v212, v213
	v_cvt_pk_bf16_f32 v45, v214, v215
	v_lshl_add_u64 v[26:27], v[8:9], 0, s[100:101]
	global_store_dwordx2 v[26:27], v[44:45], off
	s_add_u32 s10, s10, s4
	s_addc_u32 s11, s11, s5
	s_add_u32 s12, s12, s4
	s_addc_u32 s13, s13, s5
	v_lshl_add_u64 v[8:9], v[8:9], 0, s[6:7]
	s_lshl_b64 s[100:101], s[0:1], 5
	v_lshl_add_u64 v[4:5], v[4:5], 0, s[100:101]
	s_mov_b64 s[16:17], 0x40ffff
	v_cmp_lt_u64_e32 vcc, s[16:17], v[4:5]
	s_or_b64 s[8:9], vcc, s[8:9]
	s_andn2_b64 exec, exec, s[8:9]
	s_cbranch_execz .LBB0_24
.Lxc_done:
	s_branch .LBB0_637
